# stack + scalar fma pairs instead of packed fma in the gqa loop + duplicate lgkmcnt(0) before the gemm mfma blocks removed
# speedup vs baseline: 1.0230x; 1.0003x over previous
; #define PG8_STAGE(bufoff, gbase, voff) do { _Pragma("unroll") for (int _i = 0; _i < 2; ++_i) \
;         __builtin_amdgcn_global_load_lds((const unsigned*)((const char*)(gbase) + (voff)[_i]), (LAS unsigned*)(lds + (bufoff) + ldsw + _i * 8192), 16, 0, 0); } while (0)
; #define PG8_LDA(dst, b, h) do { _Pragma("unroll") for (int m = 0; m < 4; ++m) _Pragma("unroll") for (int k = 0; k < 2; ++k) dst[m][k] = *(const LAS bf16x8*)(lds + PG8_SA(b, h) + aoff + m * 2048 + k * 1024); } while (0)
; #define PG8_LDB(dst, b, h) do { _Pragma("unroll") for (int n = 0; n < 2; ++n) _Pragma("unroll") for (int k = 0; k < 2; ++k) dst[n][k] = *(const LAS bf16x8*)(lds + PG8_SB(b, h) + boff + n * 2048 + k * 1024); } while (0)
; #define PG8_MMA(ai, bj, At, Bt) do { __builtin_amdgcn_s_setprio(1); _Pragma("unroll") for (int m = 0; m < 4; ++m) _Pragma("unroll") for (int n = 0; n < 2; ++n) _Pragma("unroll") for (int k = 0; k < 2; ++k) \
;         acc[ai][bj][m][n] = __builtin_amdgcn_mfma_f32_16x16x32_bf16(Bt[n][k], At[m][k], acc[ai][bj][m][n], 0, 0, 0); __builtin_amdgcn_s_setprio(0); } while (0)
; #define PG8_WAIT_L(n) asm volatile("s_waitcnt lgkmcnt(" #n ")" ::: "memory")
; #define PG8_BAR __builtin_amdgcn_s_barrier()
; #define PG8_SCHED __builtin_amdgcn_sched_barrier(0)
; template <class Epi>
; __device__ __forceinline__ void gemm_phase(LAS unsigned char* lds, const Gemm g, const StaticOrder S, const Epi E) {
;     ...
;         for (int t = 0; t < nt; t += 2) {
;             const bool last = (t == nt - 2);
;             const char* a1 = cA + (size_t)(t + 1) * kstep;
;             const char* a2 = last ? nA : cA + (size_t)(t + 2) * kstep; const char* b2 = last ? nB : cB + (size_t)(t + 2) * kstep;
;             const char* a3 = a2 + kstep; const char* b3 = b2 + kstep;
;             PG8_LDB(B0, 0, 0); PG8_SCHED; PG8_LDA(At, 0, 0); PG8_STAGE(PG8_SA(1, 1), a1 + hstep, voffA);
;             PG8_WAIT_L(8); PG8_BAR; PG8_WAIT_L(0); PG8_MMA(0, 0, At, B0); PG8_BAR; PG8_SCHED;
;             PG8_LDB(B1, 0, 1); PG8_STAGE(PG8_SB(0, 0), b2, voffA);
;             PG8_BAR; PG8_WAIT_L(0); PG8_MMA(0, 1, At, B1); PG8_BAR;
;             PG8_LDA(At, 0, 1); PG8_STAGE(PG8_SA(0, 0), a2, voffA);
;             PG8_BAR; PG8_WAIT_L(0); PG8_MMA(1, 0, At, B0); PG8_BAR; PG8_SCHED;
.LBB0_2219:
	s_add_u32 s30, s44, 0xfff80080
	s_addc_u32 s31, s45, -1
	s_add_i32 s57, 0, 0x10000
	v_add_u32_e32 v134, s57, v137
	ds_read_b128 v[140:143], v134
	ds_read_b128 v[144:147], v134 offset:1024
	ds_read_b128 v[148:151], v134 offset:2048
	ds_read_b128 v[152:155], v134 offset:3072
	s_cmp_eq_u32 s56, 28
	s_cselect_b32 s49, s11, s31
	s_cselect_b32 s48, s28, s30
	s_cselect_b32 s47, s3, s55
	s_cselect_b32 s46, s29, s54
	v_lshl_add_u64 v[134:135], s[44:45], 0, v[130:131]
	s_add_i32 m0, s23, 0xc000
	ds_read_b128 v[156:159], v139
	ds_read_b128 v[160:163], v139 offset:1024
	ds_read_b128 v[164:167], v139 offset:2048
	ds_read_b128 v[168:171], v139 offset:3072
	ds_read_b128 v[172:175], v139 offset:4096
	ds_read_b128 v[194:197], v139 offset:5120
	ds_read_b128 v[198:201], v139 offset:6144
	ds_read_b128 v[202:205], v139 offset:7168
	global_load_lds_dwordx4 v[134:135], off
	v_lshl_add_u64 v[134:135], s[44:45], 0, v[132:133]
	s_add_i32 m0, s23, 0xe000
	s_nop 0
	global_load_lds_dwordx4 v[134:135], off
	s_waitcnt lgkmcnt(8)
	s_barrier
	s_waitcnt lgkmcnt(0)
	s_setprio 1
	v_mfma_f32_16x16x32_bf16 v[120:123], v[140:143], v[156:159], v[120:123]
	v_mfma_f32_16x16x32_bf16 v[124:127], v[148:151], v[156:159], v[124:127]
	v_mfma_f32_16x16x32_bf16 v[104:107], v[140:143], v[164:167], v[104:107]
	v_mfma_f32_16x16x32_bf16 v[108:111], v[148:151], v[164:167], v[108:111]
	v_mfma_f32_16x16x32_bf16 v[88:91], v[140:143], v[172:175], v[88:91]
	v_mfma_f32_16x16x32_bf16 v[92:95], v[148:151], v[172:175], v[92:95]
	v_mfma_f32_16x16x32_bf16 v[72:75], v[140:143], v[198:201], v[72:75]
	v_mfma_f32_16x16x32_bf16 v[76:79], v[148:151], v[198:201], v[76:79]
	v_mfma_f32_16x16x32_bf16 v[120:123], v[144:147], v[160:163], v[120:123]
	v_mfma_f32_16x16x32_bf16 v[124:127], v[152:155], v[160:163], v[124:127]
	v_mfma_f32_16x16x32_bf16 v[104:107], v[144:147], v[168:171], v[104:107]
	v_mfma_f32_16x16x32_bf16 v[108:111], v[152:155], v[168:171], v[108:111]
	v_mfma_f32_16x16x32_bf16 v[88:91], v[144:147], v[194:197], v[88:91]
	v_mfma_f32_16x16x32_bf16 v[92:95], v[152:155], v[194:197], v[92:95]
	v_mfma_f32_16x16x32_bf16 v[72:75], v[144:147], v[202:205], v[72:75]
	v_mfma_f32_16x16x32_bf16 v[76:79], v[152:155], v[202:205], v[76:79]
	s_setprio 0
	s_barrier
	s_add_i32 s58, 0, 0x14000
	v_add_u32_e32 v134, s58, v137
	s_add_i32 s30, s57, s22
	ds_read_b128 v[206:209], v134
	ds_read_b128 v[228:231], v134 offset:1024
	ds_read_b128 v[232:235], v134 offset:2048
	ds_read_b128 v[236:239], v134 offset:3072
	v_lshl_add_u64 v[134:135], s[46:47], 0, v[178:179]
	s_mov_b32 m0, s30
	v_lshl_add_u64 v[210:211], s[46:47], 0, v[128:129]
	global_load_lds_dwordx4 v[134:135], off
	s_add_i32 m0, s30, 0x2000
	s_nop 0
	global_load_lds_dwordx4 v[210:211], off
	s_barrier
	s_waitcnt lgkmcnt(0)
	s_setprio 1
	v_mfma_f32_16x16x32_bf16 v[112:115], v[206:209], v[156:159], v[112:115]
	v_mfma_f32_16x16x32_bf16 v[116:119], v[232:235], v[156:159], v[116:119]
	v_mfma_f32_16x16x32_bf16 v[96:99], v[206:209], v[164:167], v[96:99]
	v_mfma_f32_16x16x32_bf16 v[100:103], v[232:235], v[164:167], v[100:103]
	v_mfma_f32_16x16x32_bf16 v[80:83], v[206:209], v[172:175], v[80:83]
	v_mfma_f32_16x16x32_bf16 v[84:87], v[232:235], v[172:175], v[84:87]
	v_mfma_f32_16x16x32_bf16 v[64:67], v[206:209], v[198:201], v[64:67]
	v_mfma_f32_16x16x32_bf16 v[68:71], v[232:235], v[198:201], v[68:71]
	v_mfma_f32_16x16x32_bf16 v[112:115], v[228:231], v[160:163], v[112:115]
	v_mfma_f32_16x16x32_bf16 v[116:119], v[236:239], v[160:163], v[116:119]
	v_mfma_f32_16x16x32_bf16 v[96:99], v[228:231], v[168:171], v[96:99]
	v_mfma_f32_16x16x32_bf16 v[100:103], v[236:239], v[168:171], v[100:103]
	v_mfma_f32_16x16x32_bf16 v[80:83], v[228:231], v[194:197], v[80:83]
	v_mfma_f32_16x16x32_bf16 v[84:87], v[236:239], v[194:197], v[84:87]
	v_mfma_f32_16x16x32_bf16 v[64:67], v[228:231], v[202:205], v[64:67]
	v_mfma_f32_16x16x32_bf16 v[68:71], v[236:239], v[202:205], v[68:71]
	s_setprio 0
	s_barrier
	s_mov_b32 m0, s23
	v_lshl_add_u64 v[220:221], s[48:49], 0, v[178:179]
	ds_read_b128 v[156:159], v139 offset:16384
	ds_read_b128 v[160:163], v139 offset:17408
	ds_read_b128 v[164:167], v139 offset:18432
	ds_read_b128 v[168:171], v139 offset:19456
	ds_read_b128 v[172:175], v139 offset:20480
	ds_read_b128 v[194:197], v139 offset:21504
	ds_read_b128 v[198:201], v139 offset:22528
	ds_read_b128 v[202:205], v139 offset:23552
	global_load_lds_dwordx4 v[220:221], off
	v_lshl_add_u64 v[222:223], s[48:49], 0, v[128:129]
	s_mov_b32 m0, s24
	s_nop 0
	global_load_lds_dwordx4 v[222:223], off
	s_barrier
	s_waitcnt lgkmcnt(0)
	s_setprio 1
	v_mfma_f32_16x16x32_bf16 v[56:59], v[140:143], v[156:159], v[56:59]
	v_mfma_f32_16x16x32_bf16 v[60:63], v[148:151], v[156:159], v[60:63]
	v_mfma_f32_16x16x32_bf16 v[40:43], v[140:143], v[164:167], v[40:43]
	v_mfma_f32_16x16x32_bf16 v[44:47], v[148:151], v[164:167], v[44:47]
	v_mfma_f32_16x16x32_bf16 v[24:27], v[140:143], v[172:175], v[24:27]
	v_mfma_f32_16x16x32_bf16 v[28:31], v[148:151], v[172:175], v[28:31]
	v_mfma_f32_16x16x32_bf16 v[8:11], v[140:143], v[198:201], v[8:11]
	v_mfma_f32_16x16x32_bf16 v[12:15], v[148:151], v[198:201], v[12:15]
	v_mfma_f32_16x16x32_bf16 v[56:59], v[144:147], v[160:163], v[56:59]
	v_mfma_f32_16x16x32_bf16 v[60:63], v[152:155], v[160:163], v[60:63]
	v_mfma_f32_16x16x32_bf16 v[40:43], v[144:147], v[168:171], v[40:43]
	v_mfma_f32_16x16x32_bf16 v[44:47], v[152:155], v[168:171], v[44:47]
	v_mfma_f32_16x16x32_bf16 v[24:27], v[144:147], v[194:197], v[24:27]
	v_mfma_f32_16x16x32_bf16 v[28:31], v[152:155], v[194:197], v[28:31]
	v_mfma_f32_16x16x32_bf16 v[8:11], v[144:147], v[202:205], v[8:11]
	v_mfma_f32_16x16x32_bf16 v[12:15], v[152:155], v[202:205], v[12:15]
	s_setprio 0
	s_barrier
; #define PG8_STAGE(bufoff, gbase, voff) do { _Pragma("unroll") for (int _i = 0; _i < 2; ++_i) \
;         __builtin_amdgcn_global_load_lds((const unsigned*)((const char*)(gbase) + (voff)[_i]), (LAS unsigned*)(lds + (bufoff) + ldsw + _i * 8192), 16, 0, 0); } while (0)
; #define PG8_LDA(dst, b, h) do { _Pragma("unroll") for (int m = 0; m < 4; ++m) _Pragma("unroll") for (int k = 0; k < 2; ++k) dst[m][k] = *(const LAS bf16x8*)(lds + PG8_SA(b, h) + aoff + m * 2048 + k * 1024); } while (0)
; #define PG8_LDB(dst, b, h) do { _Pragma("unroll") for (int n = 0; n < 2; ++n) _Pragma("unroll") for (int k = 0; k < 2; ++k) dst[n][k] = *(const LAS bf16x8*)(lds + PG8_SB(b, h) + boff + n * 2048 + k * 1024); } while (0)
; #define PG8_MMA(ai, bj, At, Bt) do { __builtin_amdgcn_s_setprio(1); _Pragma("unroll") for (int m = 0; m < 4; ++m) _Pragma("unroll") for (int n = 0; n < 2; ++n) _Pragma("unroll") for (int k = 0; k < 2; ++k) \
;         acc[ai][bj][m][n] = __builtin_amdgcn_mfma_f32_16x16x32_bf16(Bt[n][k], At[m][k], acc[ai][bj][m][n], 0, 0, 0); __builtin_amdgcn_s_setprio(0); } while (0)
; #define PG8_WAIT_V(n) asm volatile("s_waitcnt vmcnt(" #n ")" ::: "memory")
; #define PG8_WAIT_L(n) asm volatile("s_waitcnt lgkmcnt(" #n ")" ::: "memory")
; #define PG8_BAR __builtin_amdgcn_s_barrier()
; #define PG8_SCHED __builtin_amdgcn_sched_barrier(0)
; template <class Epi>
; __device__ __forceinline__ void gemm_phase(LAS unsigned char* lds, const Gemm g, const StaticOrder S, const Epi E) {
;     ...
;             PG8_STAGE(PG8_SB(0, 1), b2 + hstep, voffA);
;             PG8_WAIT_V(6); PG8_BAR; PG8_MMA(1, 1, At, B1); PG8_BAR;
;             PG8_LDB(B0, 1, 0); PG8_SCHED; PG8_LDA(At, 1, 0); PG8_STAGE(PG8_SA(0, 1), a2 + hstep, voffA);
;             PG8_WAIT_L(8); PG8_BAR; PG8_WAIT_L(0); PG8_MMA(0, 0, At, B0); PG8_BAR; PG8_SCHED;
;             PG8_LDB(B1, 1, 1); PG8_STAGE(PG8_SB(1, 0), b3, voffA);
;             PG8_BAR; PG8_WAIT_L(0); PG8_MMA(0, 1, At, B1); PG8_BAR;
;             PG8_LDA(At, 1, 1); PG8_STAGE(PG8_SA(1, 0), a3, voffA);
;             PG8_BAR; PG8_WAIT_L(0); PG8_MMA(1, 0, At, B0); PG8_BAR; PG8_SCHED;
	s_add_u32 s30, s46, 0x80000
	s_addc_u32 s31, s47, 0
	s_add_i32 s57, s58, s22
	v_lshl_add_u64 v[140:141], s[30:31], 0, v[178:179]
	s_mov_b32 m0, s57
	s_nop 0
	global_load_lds_dwordx4 v[140:141], off
	v_lshl_add_u64 v[140:141], s[30:31], 0, v[128:129]
	s_add_i32 m0, s57, 0x2000
	s_nop 0
	global_load_lds_dwordx4 v[140:141], off
	s_waitcnt vmcnt(6)
	s_barrier
	s_setprio 1
	v_mfma_f32_16x16x32_bf16 v[48:51], v[206:209], v[156:159], v[48:51]
	v_mfma_f32_16x16x32_bf16 v[52:55], v[232:235], v[156:159], v[52:55]
	v_mfma_f32_16x16x32_bf16 v[32:35], v[206:209], v[164:167], v[32:35]
	v_mfma_f32_16x16x32_bf16 v[36:39], v[232:235], v[164:167], v[36:39]
	v_mfma_f32_16x16x32_bf16 v[16:19], v[206:209], v[172:175], v[16:19]
	v_mfma_f32_16x16x32_bf16 v[20:23], v[232:235], v[172:175], v[20:23]
	v_mfma_f32_16x16x32_bf16 v[0:3], v[206:209], v[198:201], v[0:3]
	v_mfma_f32_16x16x32_bf16 v[4:7], v[232:235], v[198:201], v[4:7]
	v_mfma_f32_16x16x32_bf16 v[48:51], v[228:231], v[160:163], v[48:51]
	v_mfma_f32_16x16x32_bf16 v[52:55], v[236:239], v[160:163], v[52:55]
	v_mfma_f32_16x16x32_bf16 v[32:35], v[228:231], v[168:171], v[32:35]
	v_mfma_f32_16x16x32_bf16 v[36:39], v[236:239], v[168:171], v[36:39]
	v_mfma_f32_16x16x32_bf16 v[16:19], v[228:231], v[194:197], v[16:19]
	v_mfma_f32_16x16x32_bf16 v[20:23], v[236:239], v[194:197], v[20:23]
	v_mfma_f32_16x16x32_bf16 v[0:3], v[228:231], v[202:205], v[0:3]
	v_mfma_f32_16x16x32_bf16 v[4:7], v[236:239], v[202:205], v[4:7]
	s_setprio 0
	s_barrier
	s_add_i32 s57, 0, 0x18000
	v_add_u32_e32 v152, s57, v137
	ds_read_b128 v[140:143], v152
	ds_read_b128 v[144:147], v152 offset:1024
	ds_read_b128 v[148:151], v152 offset:2048
	ds_read_b128 v[152:155], v152 offset:3072
	s_add_u32 s30, s48, 0x80000
	s_addc_u32 s31, s49, 0
	s_mov_b32 m0, s25
	v_lshl_add_u64 v[206:207], s[30:31], 0, v[178:179]
	ds_read_b128 v[156:159], v139 offset:32768
	ds_read_b128 v[160:163], v139 offset:33792
	ds_read_b128 v[164:167], v139 offset:34816
	ds_read_b128 v[168:171], v139 offset:35840
	ds_read_b128 v[172:175], v139 offset:36864
	ds_read_b128 v[194:197], v139 offset:37888
	ds_read_b128 v[198:201], v139 offset:38912
	ds_read_b128 v[202:205], v139 offset:39936
	global_load_lds_dwordx4 v[206:207], off
	v_lshl_add_u64 v[206:207], s[30:31], 0, v[128:129]
	s_mov_b32 m0, s50
	s_nop 0
	global_load_lds_dwordx4 v[206:207], off
	s_waitcnt lgkmcnt(8)
	s_barrier
	s_waitcnt lgkmcnt(0)
	s_setprio 1
	v_mfma_f32_16x16x32_bf16 v[120:123], v[140:143], v[156:159], v[120:123]
	v_mfma_f32_16x16x32_bf16 v[124:127], v[148:151], v[156:159], v[124:127]
	v_mfma_f32_16x16x32_bf16 v[104:107], v[140:143], v[164:167], v[104:107]
	v_mfma_f32_16x16x32_bf16 v[108:111], v[148:151], v[164:167], v[108:111]
	v_mfma_f32_16x16x32_bf16 v[88:91], v[140:143], v[172:175], v[88:91]
	v_mfma_f32_16x16x32_bf16 v[92:95], v[148:151], v[172:175], v[92:95]
	v_mfma_f32_16x16x32_bf16 v[72:75], v[140:143], v[198:201], v[72:75]
	v_mfma_f32_16x16x32_bf16 v[76:79], v[148:151], v[198:201], v[76:79]
	v_mfma_f32_16x16x32_bf16 v[120:123], v[144:147], v[160:163], v[120:123]
	v_mfma_f32_16x16x32_bf16 v[124:127], v[152:155], v[160:163], v[124:127]
	v_mfma_f32_16x16x32_bf16 v[104:107], v[144:147], v[168:171], v[104:107]
	v_mfma_f32_16x16x32_bf16 v[108:111], v[152:155], v[168:171], v[108:111]
	v_mfma_f32_16x16x32_bf16 v[88:91], v[144:147], v[194:197], v[88:91]
	v_mfma_f32_16x16x32_bf16 v[92:95], v[152:155], v[194:197], v[92:95]
	v_mfma_f32_16x16x32_bf16 v[72:75], v[144:147], v[202:205], v[72:75]
	v_mfma_f32_16x16x32_bf16 v[76:79], v[152:155], v[202:205], v[76:79]
	s_setprio 0
	s_barrier
	s_add_i32 s48, 0, 0x1c000
	s_add_i32 s30, s57, s22
	v_add_u32_e32 v227, s48, v137
	v_lshl_add_u64 v[134:135], v[134:135], 0, s[34:35]
	s_mov_b32 m0, s30
	ds_read_b128 v[206:209], v227
	ds_read_b128 v[228:231], v227 offset:1024
	ds_read_b128 v[232:235], v227 offset:2048
	ds_read_b128 v[236:239], v227 offset:3072
	global_load_lds_dwordx4 v[134:135], off
	v_lshl_add_u64 v[134:135], v[210:211], 0, s[34:35]
	s_add_i32 m0, s30, 0x2000
	s_nop 0
	global_load_lds_dwordx4 v[134:135], off
	s_barrier
	s_waitcnt lgkmcnt(0)
	s_setprio 1
	v_mfma_f32_16x16x32_bf16 v[112:115], v[206:209], v[156:159], v[112:115]
	v_mfma_f32_16x16x32_bf16 v[116:119], v[232:235], v[156:159], v[116:119]
	v_mfma_f32_16x16x32_bf16 v[96:99], v[206:209], v[164:167], v[96:99]
	v_mfma_f32_16x16x32_bf16 v[100:103], v[232:235], v[164:167], v[100:103]
	v_mfma_f32_16x16x32_bf16 v[80:83], v[206:209], v[172:175], v[80:83]
	v_mfma_f32_16x16x32_bf16 v[84:87], v[232:235], v[172:175], v[84:87]
	v_mfma_f32_16x16x32_bf16 v[64:67], v[206:209], v[198:201], v[64:67]
	v_mfma_f32_16x16x32_bf16 v[68:71], v[232:235], v[198:201], v[68:71]
	v_mfma_f32_16x16x32_bf16 v[112:115], v[228:231], v[160:163], v[112:115]
	v_mfma_f32_16x16x32_bf16 v[116:119], v[236:239], v[160:163], v[116:119]
	v_mfma_f32_16x16x32_bf16 v[96:99], v[228:231], v[168:171], v[96:99]
	v_mfma_f32_16x16x32_bf16 v[100:103], v[236:239], v[168:171], v[100:103]
	v_mfma_f32_16x16x32_bf16 v[80:83], v[228:231], v[194:197], v[80:83]
	v_mfma_f32_16x16x32_bf16 v[84:87], v[236:239], v[194:197], v[84:87]
	v_mfma_f32_16x16x32_bf16 v[64:67], v[228:231], v[202:205], v[64:67]
	v_mfma_f32_16x16x32_bf16 v[68:71], v[236:239], v[202:205], v[68:71]
	s_setprio 0
	s_barrier
	s_mov_b32 m0, s51
	v_lshl_add_u64 v[134:135], v[220:221], 0, s[34:35]
	ds_read_b128 v[156:159], v139 offset:49152
	ds_read_b128 v[160:163], v139 offset:50176
	ds_read_b128 v[164:167], v139 offset:51200
	ds_read_b128 v[168:171], v139 offset:52224
	ds_read_b128 v[172:175], v139 offset:53248
	ds_read_b128 v[194:197], v139 offset:54272
	ds_read_b128 v[198:201], v139 offset:55296
	ds_read_b128 v[202:205], v139 offset:56320
	global_load_lds_dwordx4 v[134:135], off
	v_lshl_add_u64 v[134:135], v[222:223], 0, s[34:35]
	s_mov_b32 m0, s52
	s_nop 0
	global_load_lds_dwordx4 v[134:135], off
	s_barrier
; __device__ __forceinline__ unsigned cvt_pk_bf16(float lo, float hi) { unsigned r; asm("v_cvt_pk_bf16_f32 %0, %1, %2" : "=v"(r) : "v"(lo), "v"(hi)); return r; }
; #define PG8_STAGE(bufoff, gbase, voff) do { _Pragma("unroll") for (int _i = 0; _i < 2; ++_i) \
;         __builtin_amdgcn_global_load_lds((const unsigned*)((const char*)(gbase) + (voff)[_i]), (LAS unsigned*)(lds + (bufoff) + ldsw + _i * 8192), 16, 0, 0); } while (0)
; #define PG8_MMA(ai, bj, At, Bt) do { __builtin_amdgcn_s_setprio(1); _Pragma("unroll") for (int m = 0; m < 4; ++m) _Pragma("unroll") for (int n = 0; n < 2; ++n) _Pragma("unroll") for (int k = 0; k < 2; ++k) \
;         acc[ai][bj][m][n] = __builtin_amdgcn_mfma_f32_16x16x32_bf16(Bt[n][k], At[m][k], acc[ai][bj][m][n], 0, 0, 0); __builtin_amdgcn_s_setprio(0); } while (0)
; #define PG8_WAIT_V(n) asm volatile("s_waitcnt vmcnt(" #n ")" ::: "memory")
; #define PG8_WAIT_L(n) asm volatile("s_waitcnt lgkmcnt(" #n ")" ::: "memory")
; #define PG8_BAR __builtin_amdgcn_s_barrier()
; #define PG8_SCHED __builtin_amdgcn_sched_barrier(0)
; template <class Epi>
; __device__ __forceinline__ void gemm_phase(LAS unsigned char* lds, const Gemm g, const StaticOrder S, const Epi E) {
;     ...
;             PG8_BAR; PG8_WAIT_L(0); PG8_MMA(1, 0, At, B0); PG8_BAR; PG8_SCHED;
;             PG8_STAGE(PG8_SB(1, 1), b3 + hstep, voffA);
;             PG8_WAIT_V(6); PG8_BAR; PG8_MMA(1, 1, At, B1); PG8_BAR;
;         }
;     __device__ __forceinline__ void operator()(AccRef acc, const pg8::Unit& u, int wr, int wc, int fr, int fq) const {
;     ...
;             for (int m = 0; m < 4; ++m) { bf16_t* rowp = G + (size_t)(row0 + ai * 128 + m * 16) * FH + col0;
; #pragma unroll
;                 for (int bj = 0; bj < 2; ++bj) { const f32x4 gq = acc[ai][bj][m][0], uq = acc[ai][bj][m][1]; float v[4];
; #pragma unroll
;                     for (int i = 0; i < 4; ++i) v[i] = gq[i] * uq[i] * __builtin_amdgcn_rcpf(1.f + __builtin_amdgcn_exp2f(-gq[i] * LOG2E));
;                     u32x2 w; w.x = cvt_pk_bf16(v[0], v[1]); w.y = cvt_pk_bf16(v[2], v[3]);
;                     *(u32x2*)(rowp + bj * 64) = w; } }
	s_waitcnt lgkmcnt(0)
	s_setprio 1
	v_mfma_f32_16x16x32_bf16 v[56:59], v[140:143], v[156:159], v[56:59]
	v_mfma_f32_16x16x32_bf16 v[60:63], v[148:151], v[156:159], v[60:63]
	v_mfma_f32_16x16x32_bf16 v[40:43], v[140:143], v[164:167], v[40:43]
	v_mfma_f32_16x16x32_bf16 v[44:47], v[148:151], v[164:167], v[44:47]
	v_mfma_f32_16x16x32_bf16 v[24:27], v[140:143], v[172:175], v[24:27]
	v_mfma_f32_16x16x32_bf16 v[28:31], v[148:151], v[172:175], v[28:31]
	v_mfma_f32_16x16x32_bf16 v[8:11], v[140:143], v[198:201], v[8:11]
	v_mfma_f32_16x16x32_bf16 v[12:15], v[148:151], v[198:201], v[12:15]
	v_mfma_f32_16x16x32_bf16 v[56:59], v[144:147], v[160:163], v[56:59]
	v_mfma_f32_16x16x32_bf16 v[60:63], v[152:155], v[160:163], v[60:63]
	v_mfma_f32_16x16x32_bf16 v[40:43], v[144:147], v[168:171], v[40:43]
	v_mfma_f32_16x16x32_bf16 v[44:47], v[152:155], v[168:171], v[44:47]
	v_mfma_f32_16x16x32_bf16 v[24:27], v[144:147], v[194:197], v[24:27]
	v_mfma_f32_16x16x32_bf16 v[28:31], v[152:155], v[194:197], v[28:31]
	v_mfma_f32_16x16x32_bf16 v[8:11], v[144:147], v[202:205], v[8:11]
	v_mfma_f32_16x16x32_bf16 v[12:15], v[152:155], v[202:205], v[12:15]
	s_setprio 0
	s_barrier
	s_add_u32 s30, s46, 0x80080
	s_addc_u32 s31, s47, 0
	s_add_i32 s46, s48, s22
	v_lshl_add_u64 v[134:135], s[30:31], 0, v[178:179]
	s_mov_b32 m0, s46
	s_nop 0
	global_load_lds_dwordx4 v[134:135], off
	v_lshl_add_u64 v[134:135], s[30:31], 0, v[128:129]
	s_add_i32 m0, s46, 0x2000
	s_nop 0
	global_load_lds_dwordx4 v[134:135], off
	s_waitcnt vmcnt(6)
	s_barrier
	s_setprio 1
	v_mfma_f32_16x16x32_bf16 v[48:51], v[206:209], v[156:159], v[48:51]
	v_mfma_f32_16x16x32_bf16 v[52:55], v[232:235], v[156:159], v[52:55]
	v_mfma_f32_16x16x32_bf16 v[32:35], v[206:209], v[164:167], v[32:35]
	v_mfma_f32_16x16x32_bf16 v[36:39], v[232:235], v[164:167], v[36:39]
	v_mfma_f32_16x16x32_bf16 v[16:19], v[206:209], v[172:175], v[16:19]
	v_mfma_f32_16x16x32_bf16 v[20:23], v[232:235], v[172:175], v[20:23]
	v_mfma_f32_16x16x32_bf16 v[0:3], v[206:209], v[198:201], v[0:3]
	v_mfma_f32_16x16x32_bf16 v[4:7], v[232:235], v[198:201], v[4:7]
	v_mfma_f32_16x16x32_bf16 v[48:51], v[228:231], v[160:163], v[48:51]
	v_mfma_f32_16x16x32_bf16 v[52:55], v[236:239], v[160:163], v[52:55]
	v_mfma_f32_16x16x32_bf16 v[32:35], v[228:231], v[168:171], v[32:35]
	v_mfma_f32_16x16x32_bf16 v[36:39], v[236:239], v[168:171], v[36:39]
	v_mfma_f32_16x16x32_bf16 v[16:19], v[228:231], v[194:197], v[16:19]
	v_mfma_f32_16x16x32_bf16 v[20:23], v[236:239], v[194:197], v[20:23]
	v_mfma_f32_16x16x32_bf16 v[0:3], v[228:231], v[202:205], v[0:3]
	v_mfma_f32_16x16x32_bf16 v[4:7], v[236:239], v[202:205], v[4:7]
	s_setprio 0
	s_barrier
	s_add_i32 s56, s56, 2
	s_add_u32 s44, s44, 0x100
	s_addc_u32 s45, s45, 0
	s_add_u32 s54, s54, 0x100
	s_addc_u32 s55, s55, 0
	s_cmp_gt_u32 s56, 29
	s_cbranch_scc0 .LBB0_2219
	v_mul_f32_e32 v116, v116, v112
	v_mul_f32_e32 v112, 0xbfb8aa3b, v112
	v_exp_f32_e32 v112, v112
	v_mul_f32_e32 v100, v100, v96
	v_mul_f32_e32 v96, 0xbfb8aa3b, v96
	v_exp_f32_e32 v96, v96
	v_mul_f32_e32 v84, v84, v80
	v_mul_f32_e32 v80, 0xbfb8aa3b, v80
	v_add_f32_e32 v112, 1.0, v112
	v_exp_f32_e32 v80, v80
	v_rcp_f32_e32 v112, v112
	v_mul_f32_e32 v68, v68, v64
	v_mul_f32_e32 v64, 0xbfb8aa3b, v64
	v_add_f32_e32 v96, 1.0, v96
	v_exp_f32_e32 v64, v64
	v_rcp_f32_e32 v96, v96
	v_mul_f32_e32 v52, v52, v48
	v_mul_f32_e32 v48, 0xbfb8aa3b, v48
	v_add_f32_e32 v80, 1.0, v80
	v_exp_f32_e32 v48, v48
	v_mul_f32_e32 v112, v116, v112
	v_mul_f32_e32 v116, v117, v113
	v_mul_f32_e32 v113, 0xbfb8aa3b, v113
	v_rcp_f32_e32 v80, v80
	v_mul_f32_e32 v36, v36, v32
	v_mul_f32_e32 v32, 0xbfb8aa3b, v32
	v_exp_f32_e32 v113, v113
	v_add_f32_e32 v64, 1.0, v64
	v_exp_f32_e32 v32, v32
	v_mul_f32_e32 v96, v100, v96
	v_mul_f32_e32 v100, v101, v97
	v_mul_f32_e32 v97, 0xbfb8aa3b, v97
	v_rcp_f32_e32 v64, v64
	v_mul_f32_e32 v20, v20, v16
	v_mul_f32_e32 v16, 0xbfb8aa3b, v16
	v_exp_f32_e32 v97, v97
	v_add_f32_e32 v48, 1.0, v48
	v_exp_f32_e32 v16, v16
	v_mul_f32_e32 v80, v84, v80
	v_mul_f32_e32 v84, v85, v81
	v_mul_f32_e32 v81, 0xbfb8aa3b, v81
	v_rcp_f32_e32 v48, v48
	v_mul_f32_e32 v124, v124, v120
	v_mul_f32_e32 v120, 0xbfb8aa3b, v120
	v_add_f32_e32 v113, 1.0, v113
	v_mul_f32_e32 v108, v108, v104
	v_mul_f32_e32 v104, 0xbfb8aa3b, v104
	v_mul_f32_e32 v92, v92, v88
	v_mul_f32_e32 v88, 0xbfb8aa3b, v88
	v_exp_f32_e32 v81, v81
	v_mul_f32_e32 v76, v76, v72
	v_mul_f32_e32 v72, 0xbfb8aa3b, v72
	v_mul_f32_e32 v60, v60, v56
	v_mul_f32_e32 v56, 0xbfb8aa3b, v56
	v_mul_f32_e32 v44, v44, v40
	v_mul_f32_e32 v40, 0xbfb8aa3b, v40
	v_add_f32_e32 v32, 1.0, v32
	v_mul_f32_e32 v28, v28, v24
	v_mul_f32_e32 v24, 0xbfb8aa3b, v24
	v_mul_f32_e32 v12, v12, v8
	v_mul_f32_e32 v8, 0xbfb8aa3b, v8
	v_mul_f32_e32 v4, v4, v0
	v_mul_f32_e32 v0, 0xbfb8aa3b, v0
	v_exp_f32_e32 v120, v120
	v_rcp_f32_e32 v113, v113
	v_exp_f32_e32 v104, v104
	v_exp_f32_e32 v88, v88
	v_exp_f32_e32 v72, v72
	v_mul_f32_e32 v64, v68, v64
	v_mul_f32_e32 v68, v69, v65
	v_mul_f32_e32 v65, 0xbfb8aa3b, v65
	v_exp_f32_e32 v56, v56
	v_exp_f32_e32 v40, v40
	v_rcp_f32_e32 v32, v32
	v_exp_f32_e32 v24, v24
	v_exp_f32_e32 v8, v8
	v_exp_f32_e32 v0, v0
	v_add_f32_e32 v97, 1.0, v97
	v_exp_f32_e32 v65, v65
	v_add_f32_e32 v16, 1.0, v16
	v_rcp_f32_e32 v97, v97
	v_mul_f32_e32 v48, v52, v48
	v_mul_f32_e32 v52, v53, v49
	v_mul_f32_e32 v49, 0xbfb8aa3b, v49
	v_rcp_f32_e32 v16, v16
	v_add_f32_e32 v81, 1.0, v81
	v_exp_f32_e32 v49, v49
	v_add_f32_e32 v120, 1.0, v120
	v_mul_f32_e32 v113, v116, v113
	v_mul_f32_e32 v116, v118, v114
	v_mul_f32_e32 v114, 0xbfb8aa3b, v114
	v_add_f32_e32 v104, 1.0, v104
	v_add_f32_e32 v88, 1.0, v88
	v_rcp_f32_e32 v81, v81
	v_add_f32_e32 v72, 1.0, v72
	v_add_f32_e32 v56, 1.0, v56
; __device__ __forceinline__ unsigned cvt_pk_bf16(float lo, float hi) { unsigned r; asm("v_cvt_pk_bf16_f32 %0, %1, %2" : "=v"(r) : "v"(lo), "v"(hi)); return r; }
;     __device__ __forceinline__ void operator()(AccRef acc, const pg8::Unit& u, int wr, int wc, int fr, int fq) const {
;     ...
;             for (int m = 0; m < 4; ++m) { bf16_t* rowp = G + (size_t)(row0 + ai * 128 + m * 16) * FH + col0;
; #pragma unroll
;                 for (int bj = 0; bj < 2; ++bj) { const f32x4 gq = acc[ai][bj][m][0], uq = acc[ai][bj][m][1]; float v[4];
; #pragma unroll
;                     for (int i = 0; i < 4; ++i) v[i] = gq[i] * uq[i] * __builtin_amdgcn_rcpf(1.f + __builtin_amdgcn_exp2f(-gq[i] * LOG2E));
;                     u32x2 w; w.x = cvt_pk_bf16(v[0], v[1]); w.y = cvt_pk_bf16(v[2], v[3]);
;                     *(u32x2*)(rowp + bj * 64) = w; } }
	v_add_f32_e32 v40, 1.0, v40
	v_mul_f32_e32 v32, v36, v32
	v_mul_f32_e32 v36, v37, v33
	v_mul_f32_e32 v33, 0xbfb8aa3b, v33
	v_add_f32_e32 v24, 1.0, v24
	v_add_f32_e32 v8, 1.0, v8
	v_add_f32_e32 v0, 1.0, v0
	v_rcp_f32_e32 v120, v120
	v_exp_f32_e32 v114, v114
	v_rcp_f32_e32 v104, v104
	v_rcp_f32_e32 v88, v88
	v_rcp_f32_e32 v72, v72
	v_add_f32_e32 v65, 1.0, v65
	v_rcp_f32_e32 v56, v56
	v_rcp_f32_e32 v40, v40
	v_exp_f32_e32 v33, v33
	v_rcp_f32_e32 v24, v24
	v_rcp_f32_e32 v8, v8
	v_rcp_f32_e32 v0, v0
	v_mul_f32_e32 v97, v100, v97
	v_mul_f32_e32 v100, v102, v98
	v_mul_f32_e32 v98, 0xbfb8aa3b, v98
	v_rcp_f32_e32 v65, v65
	v_mul_f32_e32 v16, v20, v16
	v_mul_f32_e32 v20, v21, v17
	v_mul_f32_e32 v17, 0xbfb8aa3b, v17
	v_exp_f32_e32 v98, v98
	v_add_f32_e32 v49, 1.0, v49
	v_exp_f32_e32 v17, v17
	v_mul_f32_e32 v81, v84, v81
	v_mul_f32_e32 v84, v86, v82
	v_mul_f32_e32 v82, 0xbfb8aa3b, v82
	v_rcp_f32_e32 v49, v49
	v_mul_f32_e32 v120, v124, v120
	v_mul_f32_e32 v124, v125, v121
	v_mul_f32_e32 v121, 0xbfb8aa3b, v121
	v_add_f32_e32 v114, 1.0, v114
	v_mul_f32_e32 v104, v108, v104
	v_mul_f32_e32 v108, v109, v105
	v_mul_f32_e32 v105, 0xbfb8aa3b, v105
	v_mul_f32_e32 v88, v92, v88
	v_mul_f32_e32 v92, v93, v89
	v_mul_f32_e32 v89, 0xbfb8aa3b, v89
	v_exp_f32_e32 v82, v82
	v_mul_f32_e32 v72, v76, v72
	v_mul_f32_e32 v76, v77, v73
	v_mul_f32_e32 v73, 0xbfb8aa3b, v73
	v_mul_f32_e32 v56, v60, v56
	v_mul_f32_e32 v60, v61, v57
	v_mul_f32_e32 v57, 0xbfb8aa3b, v57
	v_mul_f32_e32 v40, v44, v40
	v_mul_f32_e32 v44, v45, v41
	v_mul_f32_e32 v41, 0xbfb8aa3b, v41
	v_add_f32_e32 v33, 1.0, v33
	v_mul_f32_e32 v24, v28, v24
	v_mul_f32_e32 v28, v29, v25
	v_mul_f32_e32 v25, 0xbfb8aa3b, v25
	v_mul_f32_e32 v8, v12, v8
	v_mul_f32_e32 v12, v13, v9
	v_mul_f32_e32 v9, 0xbfb8aa3b, v9
	v_mul_f32_e32 v0, v4, v0
	v_mul_f32_e32 v4, v5, v1
	v_mul_f32_e32 v1, 0xbfb8aa3b, v1
	v_exp_f32_e32 v121, v121
	v_rcp_f32_e32 v114, v114
	v_exp_f32_e32 v105, v105
	v_exp_f32_e32 v89, v89
	v_exp_f32_e32 v73, v73
	v_mul_f32_e32 v65, v68, v65
	v_mul_f32_e32 v68, v70, v66
	v_mul_f32_e32 v66, 0xbfb8aa3b, v66
	v_exp_f32_e32 v57, v57
	v_exp_f32_e32 v41, v41
	v_rcp_f32_e32 v33, v33
	v_exp_f32_e32 v25, v25
	v_exp_f32_e32 v9, v9
	v_exp_f32_e32 v1, v1
	v_add_f32_e32 v98, 1.0, v98
	v_exp_f32_e32 v66, v66
	v_add_f32_e32 v17, 1.0, v17
	v_rcp_f32_e32 v98, v98
	v_mul_f32_e32 v49, v52, v49
	v_mul_f32_e32 v52, v54, v50
	v_mul_f32_e32 v50, 0xbfb8aa3b, v50
	v_rcp_f32_e32 v17, v17
	v_add_f32_e32 v82, 1.0, v82
	v_exp_f32_e32 v50, v50
	v_add_f32_e32 v121, 1.0, v121
	v_mul_f32_e32 v114, v116, v114
	v_mul_f32_e32 v116, v119, v115
	v_mul_f32_e32 v115, 0xbfb8aa3b, v115
	v_add_f32_e32 v105, 1.0, v105
	v_add_f32_e32 v89, 1.0, v89
	v_rcp_f32_e32 v82, v82
	v_add_f32_e32 v73, 1.0, v73
	v_add_f32_e32 v57, 1.0, v57
	v_add_f32_e32 v41, 1.0, v41
	v_mul_f32_e32 v33, v36, v33
	v_mul_f32_e32 v36, v38, v34
	v_mul_f32_e32 v34, 0xbfb8aa3b, v34
	v_add_f32_e32 v25, 1.0, v25
	v_add_f32_e32 v9, 1.0, v9
	v_add_f32_e32 v1, 1.0, v1
	v_rcp_f32_e32 v121, v121
	v_exp_f32_e32 v115, v115
	v_rcp_f32_e32 v105, v105
	v_rcp_f32_e32 v89, v89
	v_rcp_f32_e32 v73, v73
	v_add_f32_e32 v66, 1.0, v66
	v_rcp_f32_e32 v57, v57
	v_rcp_f32_e32 v41, v41
	v_exp_f32_e32 v34, v34
	v_rcp_f32_e32 v25, v25
	v_rcp_f32_e32 v9, v9
	v_rcp_f32_e32 v1, v1
	v_mul_f32_e32 v98, v100, v98
	v_mul_f32_e32 v100, v103, v99
	v_mul_f32_e32 v99, 0xbfb8aa3b, v99
	v_rcp_f32_e32 v66, v66
	v_mul_f32_e32 v17, v20, v17
	v_mul_f32_e32 v20, v22, v18
	v_mul_f32_e32 v18, 0xbfb8aa3b, v18
	v_exp_f32_e32 v99, v99
	v_add_f32_e32 v50, 1.0, v50
	v_exp_f32_e32 v18, v18
	v_mul_f32_e32 v82, v84, v82
	v_mul_f32_e32 v84, v87, v83
	v_mul_f32_e32 v83, 0xbfb8aa3b, v83
	v_rcp_f32_e32 v50, v50
	v_mul_f32_e32 v121, v124, v121
	v_mul_f32_e32 v124, v126, v122
	v_mul_f32_e32 v122, 0xbfb8aa3b, v122
	v_add_f32_e32 v115, 1.0, v115
	v_mul_f32_e32 v105, v108, v105
	v_mul_f32_e32 v108, v110, v106
	v_mul_f32_e32 v106, 0xbfb8aa3b, v106
	v_mul_f32_e32 v89, v92, v89
	v_mul_f32_e32 v92, v94, v90
	v_mul_f32_e32 v90, 0xbfb8aa3b, v90
	v_exp_f32_e32 v83, v83
	v_mul_f32_e32 v73, v76, v73
	v_mul_f32_e32 v76, v78, v74
	v_mul_f32_e32 v74, 0xbfb8aa3b, v74
	v_mul_f32_e32 v57, v60, v57
	v_mul_f32_e32 v60, v62, v58
	v_mul_f32_e32 v58, 0xbfb8aa3b, v58
	v_mul_f32_e32 v41, v44, v41
	v_mul_f32_e32 v44, v46, v42
	v_mul_f32_e32 v42, 0xbfb8aa3b, v42
	v_add_f32_e32 v34, 1.0, v34
	v_mul_f32_e32 v25, v28, v25
	v_mul_f32_e32 v28, v30, v26
	v_mul_f32_e32 v26, 0xbfb8aa3b, v26
	v_mul_f32_e32 v9, v12, v9
	v_mul_f32_e32 v12, v14, v10
	v_mul_f32_e32 v10, 0xbfb8aa3b, v10
	v_mul_f32_e32 v1, v4, v1
	v_mul_f32_e32 v4, v6, v2
	v_mul_f32_e32 v2, 0xbfb8aa3b, v2
	v_lshl_or_b32 v134, s26, 7, v138
	v_exp_f32_e32 v122, v122
	v_rcp_f32_e32 v115, v115
	v_exp_f32_e32 v106, v106
	v_exp_f32_e32 v90, v90
	v_exp_f32_e32 v74, v74
	v_mul_f32_e32 v66, v68, v66
	v_mul_f32_e32 v68, v71, v67
	v_mul_f32_e32 v67, 0xbfb8aa3b, v67
	v_exp_f32_e32 v58, v58
	v_exp_f32_e32 v42, v42
	v_rcp_f32_e32 v34, v34
	v_exp_f32_e32 v26, v26
	v_exp_f32_e32 v10, v10
	v_exp_f32_e32 v2, v2
	v_ashrrev_i32_e32 v135, 31, v134
	v_add_f32_e32 v99, 1.0, v99
	v_exp_f32_e32 v67, v67
	v_add_f32_e32 v18, 1.0, v18
	v_lshl_add_u32 v140, s27, 8, v136
	v_lshl_add_u64 v[134:135], v[134:135], 1, s[74:75]
	v_rcp_f32_e32 v99, v99
	v_mul_f32_e32 v50, v52, v50
	v_mul_f32_e32 v52, v55, v51
	v_mul_f32_e32 v51, 0xbfb8aa3b, v51
	v_rcp_f32_e32 v18, v18
	v_mad_i64_i32 v[142:143], s[26:27], v140, s33, v[134:135]
	v_cvt_pk_bf16_f32 v112, v112, v113
	v_add_f32_e32 v83, 1.0, v83
	v_exp_f32_e32 v51, v51
	v_add_f32_e32 v122, 1.0, v122
	v_mul_f32_e32 v115, v116, v115
	v_cvt_pk_bf16_f32 v113, v114, v115
; __device__ __forceinline__ unsigned cvt_pk_bf16(float lo, float hi) { unsigned r; asm("v_cvt_pk_bf16_f32 %0, %1, %2" : "=v"(r) : "v"(lo), "v"(hi)); return r; }
;     __device__ __forceinline__ void operator()(AccRef acc, const pg8::Unit& u, int wr, int wc, int fr, int fq) const {
;         const int row0 = u.pm * 256 + wr * 64 + fr, col0 = u.pn * 128 + wc * 16 + 4 * fq;
; #pragma unroll
;         for (int ai = 0; ai < 2; ++ai)
; #pragma unroll
;             for (int m = 0; m < 4; ++m) { bf16_t* rowp = G + (size_t)(row0 + ai * 128 + m * 16) * FH + col0;
; #pragma unroll
;                 for (int bj = 0; bj < 2; ++bj) { const f32x4 gq = acc[ai][bj][m][0], uq = acc[ai][bj][m][1]; float v[4];
; #pragma unroll
;                     for (int i = 0; i < 4; ++i) v[i] = gq[i] * uq[i] * __builtin_amdgcn_rcpf(1.f + __builtin_amdgcn_exp2f(-gq[i] * LOG2E));
;                     u32x2 w; w.x = cvt_pk_bf16(v[0], v[1]); w.y = cvt_pk_bf16(v[2], v[3]);
;                     *(u32x2*)(rowp + bj * 64) = w; } }
	global_store_dwordx2 v[142:143], v[112:113], off offset:128
	v_or_b32_e32 v112, 16, v140
	v_add_f32_e32 v106, 1.0, v106
	v_add_f32_e32 v90, 1.0, v90
	v_rcp_f32_e32 v83, v83
	v_add_f32_e32 v74, 1.0, v74
	v_add_f32_e32 v58, 1.0, v58
	v_add_f32_e32 v42, 1.0, v42
	v_mul_f32_e32 v34, v36, v34
	v_mul_f32_e32 v36, v39, v35
	v_mul_f32_e32 v35, 0xbfb8aa3b, v35
	v_add_f32_e32 v26, 1.0, v26
	v_add_f32_e32 v10, 1.0, v10
	v_add_f32_e32 v2, 1.0, v2
	v_rcp_f32_e32 v122, v122
	v_mad_i64_i32 v[112:113], s[26:27], v112, s33, v[134:135]
	v_rcp_f32_e32 v106, v106
	v_cvt_pk_bf16_f32 v96, v96, v97
	v_rcp_f32_e32 v90, v90
	v_rcp_f32_e32 v74, v74
	v_add_f32_e32 v67, 1.0, v67
	v_rcp_f32_e32 v58, v58
	v_rcp_f32_e32 v42, v42
	v_exp_f32_e32 v35, v35
	v_rcp_f32_e32 v26, v26
	v_rcp_f32_e32 v10, v10
	v_rcp_f32_e32 v2, v2
	v_mul_f32_e32 v99, v100, v99
	v_cvt_pk_bf16_f32 v97, v98, v99
	global_store_dwordx2 v[112:113], v[96:97], off offset:128
	v_or_b32_e32 v96, 32, v140
	v_rcp_f32_e32 v67, v67
	v_mul_f32_e32 v18, v20, v18
	v_mul_f32_e32 v20, v23, v19
	v_mul_f32_e32 v19, 0xbfb8aa3b, v19
	v_mad_i64_i32 v[96:97], s[26:27], v96, s33, v[134:135]
	v_cvt_pk_bf16_f32 v80, v80, v81
	v_add_f32_e32 v51, 1.0, v51
	v_exp_f32_e32 v19, v19
	v_mul_f32_e32 v83, v84, v83
	v_cvt_pk_bf16_f32 v81, v82, v83
	global_store_dwordx2 v[96:97], v[80:81], off offset:128
	v_or_b32_e32 v80, 48, v140
	v_rcp_f32_e32 v51, v51
	v_mul_f32_e32 v122, v124, v122
	v_mul_f32_e32 v124, v127, v123
	v_mul_f32_e32 v123, 0xbfb8aa3b, v123
	v_mul_f32_e32 v106, v108, v106
	v_mul_f32_e32 v108, v111, v107
	v_mul_f32_e32 v107, 0xbfb8aa3b, v107
	v_mul_f32_e32 v90, v92, v90
	v_mul_f32_e32 v92, v95, v91
	v_mul_f32_e32 v91, 0xbfb8aa3b, v91
	v_mad_i64_i32 v[80:81], s[26:27], v80, s33, v[134:135]
	v_mul_f32_e32 v74, v76, v74
	v_mul_f32_e32 v76, v79, v75
	v_mul_f32_e32 v75, 0xbfb8aa3b, v75
	v_cvt_pk_bf16_f32 v64, v64, v65
	v_mul_f32_e32 v58, v60, v58
	v_mul_f32_e32 v60, v63, v59
	v_mul_f32_e32 v59, 0xbfb8aa3b, v59
	v_mul_f32_e32 v42, v44, v42
	v_mul_f32_e32 v44, v47, v43
	v_mul_f32_e32 v43, 0xbfb8aa3b, v43
	v_add_f32_e32 v35, 1.0, v35
	v_mul_f32_e32 v26, v28, v26
	v_mul_f32_e32 v28, v31, v27
	v_mul_f32_e32 v27, 0xbfb8aa3b, v27
	v_mul_f32_e32 v10, v12, v10
	v_mul_f32_e32 v12, v15, v11
	v_mul_f32_e32 v11, 0xbfb8aa3b, v11
	v_mul_f32_e32 v2, v4, v2
	v_mul_f32_e32 v4, v7, v3
	v_mul_f32_e32 v3, 0xbfb8aa3b, v3
	v_exp_f32_e32 v123, v123
	v_exp_f32_e32 v107, v107
	v_exp_f32_e32 v91, v91
	v_exp_f32_e32 v75, v75
	v_mul_f32_e32 v67, v68, v67
	v_cvt_pk_bf16_f32 v65, v66, v67
	global_store_dwordx2 v[80:81], v[64:65], off offset:128
	v_add_u32_e32 v64, 0x80, v140
	v_exp_f32_e32 v59, v59
	v_exp_f32_e32 v43, v43
	v_rcp_f32_e32 v35, v35
	v_exp_f32_e32 v27, v27
	v_exp_f32_e32 v11, v11
	v_exp_f32_e32 v3, v3
	v_mad_i64_i32 v[64:65], s[26:27], v64, s33, v[134:135]
	v_cvt_pk_bf16_f32 v48, v48, v49
	v_add_f32_e32 v19, 1.0, v19
	v_mul_f32_e32 v51, v52, v51
	v_cvt_pk_bf16_f32 v49, v50, v51
	global_store_dwordx2 v[64:65], v[48:49], off offset:128
	v_add_u32_e32 v48, 0x90, v140
	v_rcp_f32_e32 v19, v19
	v_mad_i64_i32 v[48:49], s[26:27], v48, s33, v[134:135]
	v_cvt_pk_bf16_f32 v32, v32, v33
	v_add_f32_e32 v123, 1.0, v123
	v_add_f32_e32 v107, 1.0, v107
	v_add_f32_e32 v91, 1.0, v91
	v_add_f32_e32 v75, 1.0, v75
	v_add_f32_e32 v59, 1.0, v59
	v_add_f32_e32 v43, 1.0, v43
	v_mul_f32_e32 v35, v36, v35
	v_cvt_pk_bf16_f32 v33, v34, v35
	global_store_dwordx2 v[48:49], v[32:33], off offset:128
	v_add_u32_e32 v32, 0xa0, v140
	v_add_f32_e32 v27, 1.0, v27
	v_add_f32_e32 v11, 1.0, v11
	v_add_f32_e32 v3, 1.0, v3
	v_rcp_f32_e32 v123, v123
	v_rcp_f32_e32 v107, v107
	v_rcp_f32_e32 v91, v91
	v_rcp_f32_e32 v75, v75
	v_rcp_f32_e32 v59, v59
	v_rcp_f32_e32 v43, v43
	v_mad_i64_i32 v[32:33], s[26:27], v32, s33, v[134:135]
	v_rcp_f32_e32 v27, v27
	v_cvt_pk_bf16_f32 v16, v16, v17
	v_rcp_f32_e32 v11, v11
	v_rcp_f32_e32 v3, v3
	v_mul_f32_e32 v19, v20, v19
	v_cvt_pk_bf16_f32 v17, v18, v19
	global_store_dwordx2 v[32:33], v[16:17], off offset:128
	v_add_u32_e32 v16, 0xb0, v140
	v_mad_i64_i32 v[16:17], s[26:27], v16, s33, v[134:135]
	s_and_b64 vcc, exec, s[38:39]
	s_mov_b32 s26, s2
	s_mov_b32 s27, s10
	s_mov_b64 s[46:47], s[42:43]
	s_mov_b64 s[44:45], s[40:41]
	v_mul_f32_e32 v123, v124, v123
	v_cvt_pk_bf16_f32 v120, v120, v121
	v_cvt_pk_bf16_f32 v121, v122, v123
	global_store_dwordx2 v[142:143], v[120:121], off
	v_mul_f32_e32 v107, v108, v107
	v_cvt_pk_bf16_f32 v104, v104, v105
	v_cvt_pk_bf16_f32 v105, v106, v107
	global_store_dwordx2 v[112:113], v[104:105], off
	v_mul_f32_e32 v91, v92, v91
	v_cvt_pk_bf16_f32 v88, v88, v89
	v_cvt_pk_bf16_f32 v89, v90, v91
	global_store_dwordx2 v[96:97], v[88:89], off
	v_mul_f32_e32 v75, v76, v75
	v_cvt_pk_bf16_f32 v72, v72, v73
	v_cvt_pk_bf16_f32 v73, v74, v75
	global_store_dwordx2 v[80:81], v[72:73], off
	v_mul_f32_e32 v59, v60, v59
	v_cvt_pk_bf16_f32 v56, v56, v57
	v_cvt_pk_bf16_f32 v57, v58, v59
	global_store_dwordx2 v[64:65], v[56:57], off
	v_mul_f32_e32 v43, v44, v43
	v_cvt_pk_bf16_f32 v40, v40, v41
	v_cvt_pk_bf16_f32 v41, v42, v43
	global_store_dwordx2 v[48:49], v[40:41], off
	v_mul_f32_e32 v27, v28, v27
	v_cvt_pk_bf16_f32 v24, v24, v25
	v_cvt_pk_bf16_f32 v25, v26, v27
	global_store_dwordx2 v[32:33], v[24:25], off
	v_mul_f32_e32 v11, v12, v11
	v_cvt_pk_bf16_f32 v8, v8, v9
	v_cvt_pk_bf16_f32 v9, v10, v11
	global_store_dwordx2 v[16:17], v[8:9], off
	v_mul_f32_e32 v3, v4, v3
	v_cvt_pk_bf16_f32 v0, v0, v1
	v_cvt_pk_bf16_f32 v1, v2, v3
	global_store_dwordx2 v[16:17], v[0:1], off offset:128
	s_cbranch_vccz .LBB0_2212
	s_waitcnt vmcnt(0)
	s_cmpk_gt_u32 s4, 0xff
	s_cbranch_scc1 .LBB0_2223
	s_barrier

; #define PG8_STAGE(bufoff, gbase, voff) do { _Pragma("unroll") for (int _i = 0; _i < 2; ++_i) \
;         __builtin_amdgcn_global_load_lds((const unsigned*)((const char*)(gbase) + (voff)[_i]), (LAS unsigned*)(lds + (bufoff) + ldsw + _i * 8192), 16, 0, 0); } while (0)
; #define PG8_LDA(dst, b, h) do { _Pragma("unroll") for (int m = 0; m < 4; ++m) _Pragma("unroll") for (int k = 0; k < 2; ++k) dst[m][k] = *(const LAS bf16x8*)(lds + PG8_SA(b, h) + aoff + m * 2048 + k * 1024); } while (0)
; #define PG8_LDB(dst, b, h) do { _Pragma("unroll") for (int n = 0; n < 2; ++n) _Pragma("unroll") for (int k = 0; k < 2; ++k) dst[n][k] = *(const LAS bf16x8*)(lds + PG8_SB(b, h) + boff + n * 2048 + k * 1024); } while (0)
; #define PG8_MMA(ai, bj, At, Bt) do { __builtin_amdgcn_s_setprio(1); _Pragma("unroll") for (int m = 0; m < 4; ++m) _Pragma("unroll") for (int n = 0; n < 2; ++n) _Pragma("unroll") for (int k = 0; k < 2; ++k) \
;         acc[ai][bj][m][n] = __builtin_amdgcn_mfma_f32_16x16x32_bf16(Bt[n][k], At[m][k], acc[ai][bj][m][n], 0, 0, 0); __builtin_amdgcn_s_setprio(0); } while (0)
; #define PG8_WAIT_L(n) asm volatile("s_waitcnt lgkmcnt(" #n ")" ::: "memory")
; #define PG8_BAR __builtin_amdgcn_s_barrier()
; #define PG8_SCHED __builtin_amdgcn_sched_barrier(0)
; template <class Epi>
; __device__ __forceinline__ void gemm_phase(LAS unsigned char* lds, const Gemm g, const StaticOrder S, const Epi E) {
;     ...
;         for (int t = 0; t < nt; t += 2) {
;             const bool last = (t == nt - 2);
;             const char* a1 = cA + (size_t)(t + 1) * kstep;
;             const char* a2 = last ? nA : cA + (size_t)(t + 2) * kstep; const char* b2 = last ? nB : cB + (size_t)(t + 2) * kstep;
;             const char* a3 = a2 + kstep; const char* b3 = b2 + kstep;
;             PG8_LDB(B0, 0, 0); PG8_SCHED; PG8_LDA(At, 0, 0); PG8_STAGE(PG8_SA(1, 1), a1 + hstep, voffA);
;             PG8_WAIT_L(8); PG8_BAR; PG8_WAIT_L(0); PG8_MMA(0, 0, At, B0); PG8_BAR; PG8_SCHED;
;             PG8_LDB(B1, 0, 1); PG8_STAGE(PG8_SB(0, 0), b2, voffA);
;             PG8_BAR; PG8_WAIT_L(0); PG8_MMA(0, 1, At, B1); PG8_BAR;
;             PG8_LDA(At, 0, 1); PG8_STAGE(PG8_SA(0, 0), a2, voffA);
;             PG8_BAR; PG8_WAIT_L(0); PG8_MMA(1, 0, At, B0); PG8_BAR; PG8_SCHED;
.LBB0_2573:
	s_add_i32 s66, s50, 2
	s_add_u32 s48, s38, 0x100
	s_addc_u32 s49, s39, 0
	s_add_i32 s30, 0, 0x10000
	v_add_u32_e32 v140, s30, v228
	ds_read_b128 v[128:131], v140
	ds_read_b128 v[132:135], v140 offset:1024
	ds_read_b128 v[136:139], v140 offset:2048
	ds_read_b128 v[140:143], v140 offset:3072
	s_cmp_eq_u32 s11, s50
	s_cselect_b32 s50, s46, s64
	s_cselect_b32 s53, s43, s49
	s_cselect_b32 s52, s42, s48
	s_cselect_b32 s51, s47, s65
	v_lshl_add_u64 v[200:201], s[38:39], 0, v[196:197]
	s_add_i32 m0, s23, 0xc000
	ds_read_b128 v[144:147], v230
	ds_read_b128 v[148:151], v230 offset:1024
	ds_read_b128 v[152:155], v230 offset:2048
	ds_read_b128 v[156:159], v230 offset:3072
	ds_read_b128 v[160:163], v230 offset:4096
	ds_read_b128 v[164:167], v230 offset:5120
	ds_read_b128 v[168:171], v230 offset:6144
	ds_read_b128 v[172:175], v230 offset:7168
	global_load_lds_dwordx4 v[200:201], off
	v_lshl_add_u64 v[200:201], s[38:39], 0, v[198:199]
	s_add_i32 m0, s23, 0xe000
	s_nop 0
	global_load_lds_dwordx4 v[200:201], off
	s_waitcnt lgkmcnt(8)
	s_barrier
	s_waitcnt lgkmcnt(0)
	s_setprio 1
	v_mfma_f32_16x16x32_bf16 v[124:127], v[128:131], v[144:147], v[124:127]
	v_mfma_f32_16x16x32_bf16 v[120:123], v[136:139], v[144:147], v[120:123]
	v_mfma_f32_16x16x32_bf16 v[112:115], v[128:131], v[152:155], v[112:115]
	v_mfma_f32_16x16x32_bf16 v[104:107], v[136:139], v[152:155], v[104:107]
	v_mfma_f32_16x16x32_bf16 v[92:95], v[128:131], v[160:163], v[92:95]
	v_mfma_f32_16x16x32_bf16 v[88:91], v[136:139], v[160:163], v[88:91]
	v_mfma_f32_16x16x32_bf16 v[80:83], v[128:131], v[168:171], v[80:83]
	v_mfma_f32_16x16x32_bf16 v[72:75], v[136:139], v[168:171], v[72:75]
	v_mfma_f32_16x16x32_bf16 v[124:127], v[132:135], v[148:151], v[124:127]
	v_mfma_f32_16x16x32_bf16 v[120:123], v[140:143], v[148:151], v[120:123]
	v_mfma_f32_16x16x32_bf16 v[112:115], v[132:135], v[156:159], v[112:115]
	v_mfma_f32_16x16x32_bf16 v[104:107], v[140:143], v[156:159], v[104:107]
	v_mfma_f32_16x16x32_bf16 v[92:95], v[132:135], v[164:167], v[92:95]
	v_mfma_f32_16x16x32_bf16 v[88:91], v[140:143], v[164:167], v[88:91]
	v_mfma_f32_16x16x32_bf16 v[80:83], v[132:135], v[172:175], v[80:83]
	v_mfma_f32_16x16x32_bf16 v[72:75], v[140:143], v[172:175], v[72:75]
	s_setprio 0
	s_barrier
	s_add_i32 s38, 0, 0x14000
	v_add_u32_e32 v220, s38, v228
	s_add_i32 s30, s30, s22
	ds_read_b128 v[200:203], v220
	ds_read_b128 v[204:207], v220 offset:1024
	ds_read_b128 v[208:211], v220 offset:2048
	ds_read_b128 v[232:235], v220 offset:3072
	v_lshl_add_u64 v[220:221], s[50:51], 0, v[178:179]
	s_mov_b32 m0, s30
	v_lshl_add_u64 v[222:223], s[50:51], 0, v[194:195]
	global_load_lds_dwordx4 v[220:221], off
	s_add_i32 m0, s30, 0x2000
	s_nop 0
	global_load_lds_dwordx4 v[222:223], off
	s_barrier
	s_waitcnt lgkmcnt(0)
	s_setprio 1
	v_mfma_f32_16x16x32_bf16 v[116:119], v[200:203], v[144:147], v[116:119]
	v_mfma_f32_16x16x32_bf16 v[108:111], v[208:211], v[144:147], v[108:111]
	v_mfma_f32_16x16x32_bf16 v[100:103], v[200:203], v[152:155], v[100:103]
	v_mfma_f32_16x16x32_bf16 v[96:99], v[208:211], v[152:155], v[96:99]
	v_mfma_f32_16x16x32_bf16 v[84:87], v[200:203], v[160:163], v[84:87]
	v_mfma_f32_16x16x32_bf16 v[76:79], v[208:211], v[160:163], v[76:79]
	v_mfma_f32_16x16x32_bf16 v[68:71], v[200:203], v[168:171], v[68:71]
	v_mfma_f32_16x16x32_bf16 v[64:67], v[208:211], v[168:171], v[64:67]
	v_mfma_f32_16x16x32_bf16 v[116:119], v[204:207], v[148:151], v[116:119]
	v_mfma_f32_16x16x32_bf16 v[108:111], v[232:235], v[148:151], v[108:111]
	v_mfma_f32_16x16x32_bf16 v[100:103], v[204:207], v[156:159], v[100:103]
	v_mfma_f32_16x16x32_bf16 v[96:99], v[232:235], v[156:159], v[96:99]
	v_mfma_f32_16x16x32_bf16 v[84:87], v[204:207], v[164:167], v[84:87]
	v_mfma_f32_16x16x32_bf16 v[76:79], v[232:235], v[164:167], v[76:79]
	v_mfma_f32_16x16x32_bf16 v[68:71], v[204:207], v[172:175], v[68:71]
	v_mfma_f32_16x16x32_bf16 v[64:67], v[232:235], v[172:175], v[64:67]
	s_setprio 0
	s_barrier
	s_mov_b32 m0, s23
	v_lshl_add_u64 v[236:237], s[52:53], 0, v[178:179]
	ds_read_b128 v[144:147], v230 offset:16384
	ds_read_b128 v[148:151], v230 offset:17408
	ds_read_b128 v[152:155], v230 offset:18432
	ds_read_b128 v[156:159], v230 offset:19456
	ds_read_b128 v[160:163], v230 offset:20480
	ds_read_b128 v[164:167], v230 offset:21504
	ds_read_b128 v[168:171], v230 offset:22528
	ds_read_b128 v[172:175], v230 offset:23552
	global_load_lds_dwordx4 v[236:237], off
	v_lshl_add_u64 v[238:239], s[52:53], 0, v[194:195]
	s_mov_b32 m0, s24
	s_nop 0
	global_load_lds_dwordx4 v[238:239], off
	s_barrier
	s_waitcnt lgkmcnt(0)
	s_setprio 1
	v_mfma_f32_16x16x32_bf16 v[60:63], v[128:131], v[144:147], v[60:63]
	v_mfma_f32_16x16x32_bf16 v[56:59], v[136:139], v[144:147], v[56:59]
	v_mfma_f32_16x16x32_bf16 v[48:51], v[128:131], v[152:155], v[48:51]
	v_mfma_f32_16x16x32_bf16 v[40:43], v[136:139], v[152:155], v[40:43]
	v_mfma_f32_16x16x32_bf16 v[28:31], v[128:131], v[160:163], v[28:31]
	v_mfma_f32_16x16x32_bf16 v[24:27], v[136:139], v[160:163], v[24:27]
	v_mfma_f32_16x16x32_bf16 v[16:19], v[128:131], v[168:171], v[16:19]
	v_mfma_f32_16x16x32_bf16 v[8:11], v[136:139], v[168:171], v[8:11]
	v_mfma_f32_16x16x32_bf16 v[60:63], v[132:135], v[148:151], v[60:63]
	v_mfma_f32_16x16x32_bf16 v[56:59], v[140:143], v[148:151], v[56:59]
	v_mfma_f32_16x16x32_bf16 v[48:51], v[132:135], v[156:159], v[48:51]
	v_mfma_f32_16x16x32_bf16 v[40:43], v[140:143], v[156:159], v[40:43]
	v_mfma_f32_16x16x32_bf16 v[28:31], v[132:135], v[164:167], v[28:31]
	v_mfma_f32_16x16x32_bf16 v[24:27], v[140:143], v[164:167], v[24:27]
	v_mfma_f32_16x16x32_bf16 v[16:19], v[132:135], v[172:175], v[16:19]
	v_mfma_f32_16x16x32_bf16 v[8:11], v[140:143], v[172:175], v[8:11]
	s_setprio 0
	s_barrier
; #define PG8_STAGE(bufoff, gbase, voff) do { _Pragma("unroll") for (int _i = 0; _i < 2; ++_i) \
;         __builtin_amdgcn_global_load_lds((const unsigned*)((const char*)(gbase) + (voff)[_i]), (LAS unsigned*)(lds + (bufoff) + ldsw + _i * 8192), 16, 0, 0); } while (0)
; #define PG8_LDA(dst, b, h) do { _Pragma("unroll") for (int m = 0; m < 4; ++m) _Pragma("unroll") for (int k = 0; k < 2; ++k) dst[m][k] = *(const LAS bf16x8*)(lds + PG8_SA(b, h) + aoff + m * 2048 + k * 1024); } while (0)
; #define PG8_LDB(dst, b, h) do { _Pragma("unroll") for (int n = 0; n < 2; ++n) _Pragma("unroll") for (int k = 0; k < 2; ++k) dst[n][k] = *(const LAS bf16x8*)(lds + PG8_SB(b, h) + boff + n * 2048 + k * 1024); } while (0)
; #define PG8_MMA(ai, bj, At, Bt) do { __builtin_amdgcn_s_setprio(1); _Pragma("unroll") for (int m = 0; m < 4; ++m) _Pragma("unroll") for (int n = 0; n < 2; ++n) _Pragma("unroll") for (int k = 0; k < 2; ++k) \
;         acc[ai][bj][m][n] = __builtin_amdgcn_mfma_f32_16x16x32_bf16(Bt[n][k], At[m][k], acc[ai][bj][m][n], 0, 0, 0); __builtin_amdgcn_s_setprio(0); } while (0)
; #define PG8_WAIT_V(n) asm volatile("s_waitcnt vmcnt(" #n ")" ::: "memory")
; #define PG8_WAIT_L(n) asm volatile("s_waitcnt lgkmcnt(" #n ")" ::: "memory")
; #define PG8_BAR __builtin_amdgcn_s_barrier()
; #define PG8_SCHED __builtin_amdgcn_sched_barrier(0)
; template <class Epi>
; __device__ __forceinline__ void gemm_phase(LAS unsigned char* lds, const Gemm g, const StaticOrder S, const Epi E) {
;     ...
;             PG8_STAGE(PG8_SB(0, 1), b2 + hstep, voffA);
;             PG8_WAIT_V(6); PG8_BAR; PG8_MMA(1, 1, At, B1); PG8_BAR;
;             PG8_LDB(B0, 1, 0); PG8_SCHED; PG8_LDA(At, 1, 0); PG8_STAGE(PG8_SA(0, 1), a2 + hstep, voffA);
;             PG8_WAIT_L(8); PG8_BAR; PG8_WAIT_L(0); PG8_MMA(0, 0, At, B0); PG8_BAR; PG8_SCHED;
;             PG8_LDB(B1, 1, 1); PG8_STAGE(PG8_SB(1, 0), b3, voffA);
;             PG8_BAR; PG8_WAIT_L(0); PG8_MMA(0, 1, At, B1); PG8_BAR;
;             PG8_LDA(At, 1, 1); PG8_STAGE(PG8_SA(1, 0), a3, voffA);
;             PG8_BAR; PG8_WAIT_L(0); PG8_MMA(1, 0, At, B0); PG8_BAR; PG8_SCHED;
	s_add_u32 s30, s50, 0x158000
	s_addc_u32 s31, s51, 0
	s_add_i32 s38, s38, s22
	v_lshl_add_u64 v[128:129], s[30:31], 0, v[178:179]
	s_mov_b32 m0, s38
	s_nop 0
	global_load_lds_dwordx4 v[128:129], off
	v_lshl_add_u64 v[128:129], s[30:31], 0, v[194:195]
	s_add_i32 m0, s38, 0x2000
	s_nop 0
	global_load_lds_dwordx4 v[128:129], off
	s_waitcnt vmcnt(6)
	s_barrier
	s_setprio 1
	v_mfma_f32_16x16x32_bf16 v[52:55], v[200:203], v[144:147], v[52:55]
	v_mfma_f32_16x16x32_bf16 v[44:47], v[208:211], v[144:147], v[44:47]
	v_mfma_f32_16x16x32_bf16 v[36:39], v[200:203], v[152:155], v[36:39]
	v_mfma_f32_16x16x32_bf16 v[32:35], v[208:211], v[152:155], v[32:35]
	v_mfma_f32_16x16x32_bf16 v[20:23], v[200:203], v[160:163], v[20:23]
	v_mfma_f32_16x16x32_bf16 v[12:15], v[208:211], v[160:163], v[12:15]
	v_mfma_f32_16x16x32_bf16 v[4:7], v[200:203], v[168:171], v[4:7]
	v_mfma_f32_16x16x32_bf16 v[0:3], v[208:211], v[168:171], v[0:3]
	v_mfma_f32_16x16x32_bf16 v[52:55], v[204:207], v[148:151], v[52:55]
	v_mfma_f32_16x16x32_bf16 v[44:47], v[232:235], v[148:151], v[44:47]
	v_mfma_f32_16x16x32_bf16 v[36:39], v[204:207], v[156:159], v[36:39]
	v_mfma_f32_16x16x32_bf16 v[32:35], v[232:235], v[156:159], v[32:35]
	v_mfma_f32_16x16x32_bf16 v[20:23], v[204:207], v[164:167], v[20:23]
	v_mfma_f32_16x16x32_bf16 v[12:15], v[232:235], v[164:167], v[12:15]
	v_mfma_f32_16x16x32_bf16 v[4:7], v[204:207], v[172:175], v[4:7]
	v_mfma_f32_16x16x32_bf16 v[0:3], v[232:235], v[172:175], v[0:3]
	s_setprio 0
	s_barrier
	s_add_i32 s38, 0, 0x18000
	v_add_u32_e32 v140, s38, v228
	ds_read_b128 v[128:131], v140
	ds_read_b128 v[132:135], v140 offset:1024
	ds_read_b128 v[136:139], v140 offset:2048
	ds_read_b128 v[140:143], v140 offset:3072
	s_add_u32 s30, s52, 0x158000
	s_addc_u32 s31, s53, 0
	s_mov_b32 m0, s25
	v_lshl_add_u64 v[200:201], s[30:31], 0, v[178:179]
	ds_read_b128 v[144:147], v230 offset:32768
	ds_read_b128 v[148:151], v230 offset:33792
	ds_read_b128 v[152:155], v230 offset:34816
	ds_read_b128 v[156:159], v230 offset:35840
	ds_read_b128 v[160:163], v230 offset:36864
	ds_read_b128 v[164:167], v230 offset:37888
	ds_read_b128 v[168:171], v230 offset:38912
	ds_read_b128 v[172:175], v230 offset:39936
	global_load_lds_dwordx4 v[200:201], off
	v_lshl_add_u64 v[200:201], s[30:31], 0, v[194:195]
	s_mov_b32 m0, s14
	s_nop 0
	global_load_lds_dwordx4 v[200:201], off
	s_waitcnt lgkmcnt(8)
	s_barrier
	s_waitcnt lgkmcnt(0)
	s_setprio 1
	v_mfma_f32_16x16x32_bf16 v[124:127], v[128:131], v[144:147], v[124:127]
	v_mfma_f32_16x16x32_bf16 v[120:123], v[136:139], v[144:147], v[120:123]
	v_mfma_f32_16x16x32_bf16 v[112:115], v[128:131], v[152:155], v[112:115]
	v_mfma_f32_16x16x32_bf16 v[104:107], v[136:139], v[152:155], v[104:107]
	v_mfma_f32_16x16x32_bf16 v[92:95], v[128:131], v[160:163], v[92:95]
	v_mfma_f32_16x16x32_bf16 v[88:91], v[136:139], v[160:163], v[88:91]
	v_mfma_f32_16x16x32_bf16 v[80:83], v[128:131], v[168:171], v[80:83]
	v_mfma_f32_16x16x32_bf16 v[72:75], v[136:139], v[168:171], v[72:75]
	v_mfma_f32_16x16x32_bf16 v[124:127], v[132:135], v[148:151], v[124:127]
	v_mfma_f32_16x16x32_bf16 v[120:123], v[140:143], v[148:151], v[120:123]
	v_mfma_f32_16x16x32_bf16 v[112:115], v[132:135], v[156:159], v[112:115]
	v_mfma_f32_16x16x32_bf16 v[104:107], v[140:143], v[156:159], v[104:107]
	v_mfma_f32_16x16x32_bf16 v[92:95], v[132:135], v[164:167], v[92:95]
	v_mfma_f32_16x16x32_bf16 v[88:91], v[140:143], v[164:167], v[88:91]
	v_mfma_f32_16x16x32_bf16 v[80:83], v[132:135], v[172:175], v[80:83]
	v_mfma_f32_16x16x32_bf16 v[72:75], v[140:143], v[172:175], v[72:75]
	s_setprio 0
	s_barrier
	s_add_i32 s39, 0, 0x1c000
	s_add_i32 s30, s38, s22
	v_add_u32_e32 v231, s39, v228
	v_lshl_add_u64 v[220:221], v[220:221], 0, s[34:35]
	s_mov_b32 m0, s30
	ds_read_b128 v[200:203], v231
	ds_read_b128 v[204:207], v231 offset:1024
	ds_read_b128 v[208:211], v231 offset:2048
	ds_read_b128 v[232:235], v231 offset:3072
	global_load_lds_dwordx4 v[220:221], off
	v_lshl_add_u64 v[220:221], v[222:223], 0, s[34:35]
	s_add_i32 m0, s30, 0x2000
	s_nop 0
	global_load_lds_dwordx4 v[220:221], off
	s_barrier
; #define PG8_STAGE(bufoff, gbase, voff) do { _Pragma("unroll") for (int _i = 0; _i < 2; ++_i) \
;         __builtin_amdgcn_global_load_lds((const unsigned*)((const char*)(gbase) + (voff)[_i]), (LAS unsigned*)(lds + (bufoff) + ldsw + _i * 8192), 16, 0, 0); } while (0)
; #define PG8_LDA(dst, b, h) do { _Pragma("unroll") for (int m = 0; m < 4; ++m) _Pragma("unroll") for (int k = 0; k < 2; ++k) dst[m][k] = *(const LAS bf16x8*)(lds + PG8_SA(b, h) + aoff + m * 2048 + k * 1024); } while (0)
; #define PG8_MMA(ai, bj, At, Bt) do { __builtin_amdgcn_s_setprio(1); _Pragma("unroll") for (int m = 0; m < 4; ++m) _Pragma("unroll") for (int n = 0; n < 2; ++n) _Pragma("unroll") for (int k = 0; k < 2; ++k) \
;         acc[ai][bj][m][n] = __builtin_amdgcn_mfma_f32_16x16x32_bf16(Bt[n][k], At[m][k], acc[ai][bj][m][n], 0, 0, 0); __builtin_amdgcn_s_setprio(0); } while (0)
; #define PG8_WAIT_V(n) asm volatile("s_waitcnt vmcnt(" #n ")" ::: "memory")
; #define PG8_WAIT_L(n) asm volatile("s_waitcnt lgkmcnt(" #n ")" ::: "memory")
; #define PG8_BAR __builtin_amdgcn_s_barrier()
; #define PG8_SCHED __builtin_amdgcn_sched_barrier(0)
; template <class Epi>
; __device__ __forceinline__ void gemm_phase(LAS unsigned char* lds, const Gemm g, const StaticOrder S, const Epi E) {
;     ...
;             PG8_BAR; PG8_WAIT_L(0); PG8_MMA(0, 1, At, B1); PG8_BAR;
;             PG8_LDA(At, 1, 1); PG8_STAGE(PG8_SA(1, 0), a3, voffA);
;             PG8_BAR; PG8_WAIT_L(0); PG8_MMA(1, 0, At, B0); PG8_BAR; PG8_SCHED;
;             PG8_STAGE(PG8_SB(1, 1), b3 + hstep, voffA);
;             PG8_WAIT_V(6); PG8_BAR; PG8_MMA(1, 1, At, B1); PG8_BAR;
;         }
;     __device__ __forceinline__ void operator()(AccRef acc, const pg8::Unit& u, int wr, int wc, int fr, int fq) const {
;         const int row0 = u.pm * 256 + wr * 64 + fr, col0 = u.pn * 256 + wc * 32 + 4 * fq;
;         const int v = u.pm < 32 ? (u.pm >> 3) : 4;
	s_waitcnt lgkmcnt(0)
	s_setprio 1
	v_mfma_f32_16x16x32_bf16 v[116:119], v[200:203], v[144:147], v[116:119]
	v_mfma_f32_16x16x32_bf16 v[108:111], v[208:211], v[144:147], v[108:111]
	v_mfma_f32_16x16x32_bf16 v[100:103], v[200:203], v[152:155], v[100:103]
	v_mfma_f32_16x16x32_bf16 v[96:99], v[208:211], v[152:155], v[96:99]
	v_mfma_f32_16x16x32_bf16 v[84:87], v[200:203], v[160:163], v[84:87]
	v_mfma_f32_16x16x32_bf16 v[76:79], v[208:211], v[160:163], v[76:79]
	v_mfma_f32_16x16x32_bf16 v[68:71], v[200:203], v[168:171], v[68:71]
	v_mfma_f32_16x16x32_bf16 v[64:67], v[208:211], v[168:171], v[64:67]
	v_mfma_f32_16x16x32_bf16 v[116:119], v[204:207], v[148:151], v[116:119]
	v_mfma_f32_16x16x32_bf16 v[108:111], v[232:235], v[148:151], v[108:111]
	v_mfma_f32_16x16x32_bf16 v[100:103], v[204:207], v[156:159], v[100:103]
	v_mfma_f32_16x16x32_bf16 v[96:99], v[232:235], v[156:159], v[96:99]
	v_mfma_f32_16x16x32_bf16 v[84:87], v[204:207], v[164:167], v[84:87]
	v_mfma_f32_16x16x32_bf16 v[76:79], v[232:235], v[164:167], v[76:79]
	v_mfma_f32_16x16x32_bf16 v[68:71], v[204:207], v[172:175], v[68:71]
	v_mfma_f32_16x16x32_bf16 v[64:67], v[232:235], v[172:175], v[64:67]
	s_setprio 0
	s_barrier
	s_mov_b32 m0, s57
	v_lshl_add_u64 v[220:221], v[236:237], 0, s[34:35]
	ds_read_b128 v[144:147], v230 offset:49152
	ds_read_b128 v[148:151], v230 offset:50176
	ds_read_b128 v[152:155], v230 offset:51200
	ds_read_b128 v[156:159], v230 offset:52224
	ds_read_b128 v[160:163], v230 offset:53248
	ds_read_b128 v[164:167], v230 offset:54272
	ds_read_b128 v[168:171], v230 offset:55296
	ds_read_b128 v[172:175], v230 offset:56320
	global_load_lds_dwordx4 v[220:221], off
	v_lshl_add_u64 v[220:221], v[238:239], 0, s[34:35]
	s_mov_b32 m0, s58
	s_nop 0
	global_load_lds_dwordx4 v[220:221], off
	s_barrier
	s_waitcnt lgkmcnt(0)
	s_setprio 1
	v_mfma_f32_16x16x32_bf16 v[60:63], v[128:131], v[144:147], v[60:63]
	v_mfma_f32_16x16x32_bf16 v[56:59], v[136:139], v[144:147], v[56:59]
	v_mfma_f32_16x16x32_bf16 v[48:51], v[128:131], v[152:155], v[48:51]
	v_mfma_f32_16x16x32_bf16 v[40:43], v[136:139], v[152:155], v[40:43]
	v_mfma_f32_16x16x32_bf16 v[28:31], v[128:131], v[160:163], v[28:31]
	v_mfma_f32_16x16x32_bf16 v[24:27], v[136:139], v[160:163], v[24:27]
	v_mfma_f32_16x16x32_bf16 v[16:19], v[128:131], v[168:171], v[16:19]
	v_mfma_f32_16x16x32_bf16 v[8:11], v[136:139], v[168:171], v[8:11]
	v_mfma_f32_16x16x32_bf16 v[60:63], v[132:135], v[148:151], v[60:63]
	v_mfma_f32_16x16x32_bf16 v[56:59], v[140:143], v[148:151], v[56:59]
	v_mfma_f32_16x16x32_bf16 v[48:51], v[132:135], v[156:159], v[48:51]
	v_mfma_f32_16x16x32_bf16 v[40:43], v[140:143], v[156:159], v[40:43]
	v_mfma_f32_16x16x32_bf16 v[28:31], v[132:135], v[164:167], v[28:31]
	v_mfma_f32_16x16x32_bf16 v[24:27], v[140:143], v[164:167], v[24:27]
	v_mfma_f32_16x16x32_bf16 v[16:19], v[132:135], v[172:175], v[16:19]
	v_mfma_f32_16x16x32_bf16 v[8:11], v[140:143], v[172:175], v[8:11]
	s_setprio 0
	s_barrier
	s_add_u32 s30, s50, 0x158080
	s_addc_u32 s31, s51, 0
	s_add_i32 s38, s39, s22
	v_lshl_add_u64 v[128:129], s[30:31], 0, v[178:179]
	s_mov_b32 m0, s38
	s_nop 0
	global_load_lds_dwordx4 v[128:129], off
	v_lshl_add_u64 v[128:129], s[30:31], 0, v[194:195]
	s_add_i32 m0, s38, 0x2000
	s_nop 0
	global_load_lds_dwordx4 v[128:129], off
	s_waitcnt vmcnt(6)
	s_barrier
	s_setprio 1
	v_mfma_f32_16x16x32_bf16 v[52:55], v[200:203], v[144:147], v[52:55]
	v_mfma_f32_16x16x32_bf16 v[44:47], v[208:211], v[144:147], v[44:47]
	v_mfma_f32_16x16x32_bf16 v[36:39], v[200:203], v[152:155], v[36:39]
	v_mfma_f32_16x16x32_bf16 v[32:35], v[208:211], v[152:155], v[32:35]
	v_mfma_f32_16x16x32_bf16 v[20:23], v[200:203], v[160:163], v[20:23]
	v_mfma_f32_16x16x32_bf16 v[12:15], v[208:211], v[160:163], v[12:15]
	v_mfma_f32_16x16x32_bf16 v[4:7], v[200:203], v[168:171], v[4:7]
	v_mfma_f32_16x16x32_bf16 v[0:3], v[208:211], v[168:171], v[0:3]
	v_mfma_f32_16x16x32_bf16 v[52:55], v[204:207], v[148:151], v[52:55]
	v_mfma_f32_16x16x32_bf16 v[44:47], v[232:235], v[148:151], v[44:47]
	v_mfma_f32_16x16x32_bf16 v[36:39], v[204:207], v[156:159], v[36:39]
	v_mfma_f32_16x16x32_bf16 v[32:35], v[232:235], v[156:159], v[32:35]
	v_mfma_f32_16x16x32_bf16 v[20:23], v[204:207], v[164:167], v[20:23]
	v_mfma_f32_16x16x32_bf16 v[12:15], v[232:235], v[164:167], v[12:15]
	v_mfma_f32_16x16x32_bf16 v[4:7], v[204:207], v[172:175], v[4:7]
	v_mfma_f32_16x16x32_bf16 v[0:3], v[232:235], v[172:175], v[0:3]
	s_setprio 0
	s_barrier
	s_add_u32 s64, s64, 0x100
	s_addc_u32 s65, s65, 0
	s_cmp_ge_i32 s66, s63
	s_mov_b64 s[38:39], s[48:49]
	s_mov_b32 s50, s66
	s_cbranch_scc0 .LBB0_2573
	s_cmp_gt_i32 s28, 31
	s_mov_b64 s[38:39], 0x12000
	s_cbranch_scc1 .LBB0_2576
	s_ashr_i32 s11, s28, 3
	s_mul_hi_i32 s39, s11, 0x4800
	s_mul_i32 s38, s11, 0x4800

; #define PG8_STAGE(bufoff, gbase, voff) do { _Pragma("unroll") for (int _i = 0; _i < 2; ++_i) \
;         __builtin_amdgcn_global_load_lds((const unsigned*)((const char*)(gbase) + (voff)[_i]), (LAS unsigned*)(lds + (bufoff) + ldsw + _i * 8192), 16, 0, 0); } while (0)
; #define PG8_LDA(dst, b, h) do { _Pragma("unroll") for (int m = 0; m < 4; ++m) _Pragma("unroll") for (int k = 0; k < 2; ++k) dst[m][k] = *(const LAS bf16x8*)(lds + PG8_SA(b, h) + aoff + m * 2048 + k * 1024); } while (0)
; #define PG8_LDB(dst, b, h) do { _Pragma("unroll") for (int n = 0; n < 2; ++n) _Pragma("unroll") for (int k = 0; k < 2; ++k) dst[n][k] = *(const LAS bf16x8*)(lds + PG8_SB(b, h) + boff + n * 2048 + k * 1024); } while (0)
; #define PG8_MMA(ai, bj, At, Bt) do { __builtin_amdgcn_s_setprio(1); _Pragma("unroll") for (int m = 0; m < 4; ++m) _Pragma("unroll") for (int n = 0; n < 2; ++n) _Pragma("unroll") for (int k = 0; k < 2; ++k) \
;         acc[ai][bj][m][n] = __builtin_amdgcn_mfma_f32_16x16x32_bf16(Bt[n][k], At[m][k], acc[ai][bj][m][n], 0, 0, 0); __builtin_amdgcn_s_setprio(0); } while (0)
; #define PG8_WAIT_L(n) asm volatile("s_waitcnt lgkmcnt(" #n ")" ::: "memory")
; #define PG8_BAR __builtin_amdgcn_s_barrier()
; #define PG8_SCHED __builtin_amdgcn_sched_barrier(0)
; template <class Epi>
; __device__ __forceinline__ void gemm_phase(LAS unsigned char* lds, const Gemm g, const StaticOrder S, const Epi E) {
;     ...
;         for (int t = 0; t < nt; t += 2) {
;             const bool last = (t == nt - 2);
;             const char* a1 = cA + (size_t)(t + 1) * kstep;
;             const char* a2 = last ? nA : cA + (size_t)(t + 2) * kstep; const char* b2 = last ? nB : cB + (size_t)(t + 2) * kstep;
;             const char* a3 = a2 + kstep; const char* b3 = b2 + kstep;
;             PG8_LDB(B0, 0, 0); PG8_SCHED; PG8_LDA(At, 0, 0); PG8_STAGE(PG8_SA(1, 1), a1 + hstep, voffA);
;             PG8_WAIT_L(8); PG8_BAR; PG8_WAIT_L(0); PG8_MMA(0, 0, At, B0); PG8_BAR; PG8_SCHED;
;             PG8_LDB(B1, 0, 1); PG8_STAGE(PG8_SB(0, 0), b2, voffA);
;             PG8_BAR; PG8_WAIT_L(0); PG8_MMA(0, 1, At, B1); PG8_BAR;
;             PG8_LDA(At, 0, 1); PG8_STAGE(PG8_SA(0, 0), a2, voffA);
;             PG8_BAR; PG8_WAIT_L(0); PG8_MMA(1, 0, At, B0); PG8_BAR; PG8_SCHED;
.LBB0_2721:
	s_add_u32 s48, s42, 0x100
	s_addc_u32 s49, s43, 0
	s_add_i32 s30, 0, 0x10000
	v_add_u32_e32 v132, s30, v151
	ds_read_b128 v[128:131], v132
	ds_read_b128 v[142:145], v132 offset:1024
	ds_read_b128 v[146:149], v132 offset:2048
	ds_read_b128 v[158:161], v132 offset:3072
	s_cmp_eq_u32 s57, 28
	s_cselect_b32 s53, s45, s49
	s_cselect_b32 s52, s44, s48
	s_cselect_b32 s51, s47, s11
	s_cselect_b32 s50, s46, s3
	v_lshl_add_u64 v[132:133], s[42:43], 0, v[138:139]
	s_add_i32 m0, s23, 0xc000
	ds_read_b128 v[162:165], v156
	ds_read_b128 v[166:169], v156 offset:1024
	ds_read_b128 v[170:173], v156 offset:2048
	ds_read_b128 v[194:197], v156 offset:3072
	ds_read_b128 v[198:201], v156 offset:4096
	ds_read_b128 v[202:205], v156 offset:5120
	ds_read_b128 v[206:209], v156 offset:6144
	ds_read_b128 v[228:231], v156 offset:7168
	global_load_lds_dwordx4 v[132:133], off
	v_lshl_add_u64 v[132:133], s[42:43], 0, v[140:141]
	s_add_i32 m0, s23, 0xe000
	s_nop 0
	global_load_lds_dwordx4 v[132:133], off
	s_waitcnt lgkmcnt(8)
	s_barrier
	s_waitcnt lgkmcnt(0)
	s_setprio 1
	v_mfma_f32_16x16x32_bf16 v[124:127], v[128:131], v[162:165], v[124:127]
	v_mfma_f32_16x16x32_bf16 v[120:123], v[146:149], v[162:165], v[120:123]
	v_mfma_f32_16x16x32_bf16 v[108:111], v[128:131], v[170:173], v[108:111]
	v_mfma_f32_16x16x32_bf16 v[104:107], v[146:149], v[170:173], v[104:107]
	v_mfma_f32_16x16x32_bf16 v[92:95], v[128:131], v[198:201], v[92:95]
	v_mfma_f32_16x16x32_bf16 v[88:91], v[146:149], v[198:201], v[88:91]
	v_mfma_f32_16x16x32_bf16 v[76:79], v[128:131], v[206:209], v[76:79]
	v_mfma_f32_16x16x32_bf16 v[72:75], v[146:149], v[206:209], v[72:75]
	v_mfma_f32_16x16x32_bf16 v[124:127], v[142:145], v[166:169], v[124:127]
	v_mfma_f32_16x16x32_bf16 v[120:123], v[158:161], v[166:169], v[120:123]
	v_mfma_f32_16x16x32_bf16 v[108:111], v[142:145], v[194:197], v[108:111]
	v_mfma_f32_16x16x32_bf16 v[104:107], v[158:161], v[194:197], v[104:107]
	v_mfma_f32_16x16x32_bf16 v[92:95], v[142:145], v[202:205], v[92:95]
	v_mfma_f32_16x16x32_bf16 v[88:91], v[158:161], v[202:205], v[88:91]
	v_mfma_f32_16x16x32_bf16 v[76:79], v[142:145], v[228:231], v[76:79]
	v_mfma_f32_16x16x32_bf16 v[72:75], v[158:161], v[228:231], v[72:75]
	s_setprio 0
	s_barrier
	s_add_i32 s42, 0, 0x14000
	v_add_u32_e32 v132, s42, v151
	s_add_i32 s30, s30, s22
	ds_read_b128 v[232:235], v132
	ds_read_b128 v[236:239], v132 offset:1024
	ds_read_b128 v[240:243], v132 offset:2048
	ds_read_b128 v[244:247], v132 offset:3072
	v_lshl_add_u64 v[132:133], s[50:51], 0, v[178:179]
	s_mov_b32 m0, s30
	v_lshl_add_u64 v[174:175], s[50:51], 0, v[134:135]
	global_load_lds_dwordx4 v[132:133], off
	s_add_i32 m0, s30, 0x2000
	s_nop 0
	global_load_lds_dwordx4 v[174:175], off
	s_barrier
	s_waitcnt lgkmcnt(0)
	s_setprio 1
	v_mfma_f32_16x16x32_bf16 v[116:119], v[232:235], v[162:165], v[116:119]
	v_mfma_f32_16x16x32_bf16 v[112:115], v[240:243], v[162:165], v[112:115]
	v_mfma_f32_16x16x32_bf16 v[100:103], v[232:235], v[170:173], v[100:103]
	v_mfma_f32_16x16x32_bf16 v[96:99], v[240:243], v[170:173], v[96:99]
	v_mfma_f32_16x16x32_bf16 v[84:87], v[232:235], v[198:201], v[84:87]
	v_mfma_f32_16x16x32_bf16 v[80:83], v[240:243], v[198:201], v[80:83]
	v_mfma_f32_16x16x32_bf16 v[68:71], v[232:235], v[206:209], v[68:71]
	v_mfma_f32_16x16x32_bf16 v[64:67], v[240:243], v[206:209], v[64:67]
	v_mfma_f32_16x16x32_bf16 v[116:119], v[236:239], v[166:169], v[116:119]
	v_mfma_f32_16x16x32_bf16 v[112:115], v[244:247], v[166:169], v[112:115]
	v_mfma_f32_16x16x32_bf16 v[100:103], v[236:239], v[194:197], v[100:103]
	v_mfma_f32_16x16x32_bf16 v[96:99], v[244:247], v[194:197], v[96:99]
	v_mfma_f32_16x16x32_bf16 v[84:87], v[236:239], v[202:205], v[84:87]
	v_mfma_f32_16x16x32_bf16 v[80:83], v[244:247], v[202:205], v[80:83]
	v_mfma_f32_16x16x32_bf16 v[68:71], v[236:239], v[228:231], v[68:71]
	v_mfma_f32_16x16x32_bf16 v[64:67], v[244:247], v[228:231], v[64:67]
	s_setprio 0
	s_barrier
	s_mov_b32 m0, s23
	v_lshl_add_u64 v[210:211], s[52:53], 0, v[178:179]
	ds_read_b128 v[162:165], v156 offset:16384
	ds_read_b128 v[166:169], v156 offset:17408
	ds_read_b128 v[170:173], v156 offset:18432
	ds_read_b128 v[194:197], v156 offset:19456
	ds_read_b128 v[198:201], v156 offset:20480
	ds_read_b128 v[202:205], v156 offset:21504
	ds_read_b128 v[206:209], v156 offset:22528
	ds_read_b128 v[228:231], v156 offset:23552
	global_load_lds_dwordx4 v[210:211], off
	v_lshl_add_u64 v[220:221], s[52:53], 0, v[134:135]
	s_mov_b32 m0, s24
	s_nop 0
	global_load_lds_dwordx4 v[220:221], off
	s_barrier
	s_waitcnt lgkmcnt(0)
	s_setprio 1
	v_mfma_f32_16x16x32_bf16 v[60:63], v[128:131], v[162:165], v[60:63]
	v_mfma_f32_16x16x32_bf16 v[56:59], v[146:149], v[162:165], v[56:59]
	v_mfma_f32_16x16x32_bf16 v[44:47], v[128:131], v[170:173], v[44:47]
	v_mfma_f32_16x16x32_bf16 v[40:43], v[146:149], v[170:173], v[40:43]
	v_mfma_f32_16x16x32_bf16 v[28:31], v[128:131], v[198:201], v[28:31]
	v_mfma_f32_16x16x32_bf16 v[24:27], v[146:149], v[198:201], v[24:27]
	v_mfma_f32_16x16x32_bf16 v[12:15], v[128:131], v[206:209], v[12:15]
	v_mfma_f32_16x16x32_bf16 v[8:11], v[146:149], v[206:209], v[8:11]
	v_mfma_f32_16x16x32_bf16 v[60:63], v[142:145], v[166:169], v[60:63]
	v_mfma_f32_16x16x32_bf16 v[56:59], v[158:161], v[166:169], v[56:59]
	v_mfma_f32_16x16x32_bf16 v[44:47], v[142:145], v[194:197], v[44:47]
	v_mfma_f32_16x16x32_bf16 v[40:43], v[158:161], v[194:197], v[40:43]
	v_mfma_f32_16x16x32_bf16 v[28:31], v[142:145], v[202:205], v[28:31]
	v_mfma_f32_16x16x32_bf16 v[24:27], v[158:161], v[202:205], v[24:27]
	v_mfma_f32_16x16x32_bf16 v[12:15], v[142:145], v[228:231], v[12:15]
	v_mfma_f32_16x16x32_bf16 v[8:11], v[158:161], v[228:231], v[8:11]
	s_setprio 0
	s_barrier
; #define PG8_STAGE(bufoff, gbase, voff) do { _Pragma("unroll") for (int _i = 0; _i < 2; ++_i) \
;         __builtin_amdgcn_global_load_lds((const unsigned*)((const char*)(gbase) + (voff)[_i]), (LAS unsigned*)(lds + (bufoff) + ldsw + _i * 8192), 16, 0, 0); } while (0)
; #define PG8_LDA(dst, b, h) do { _Pragma("unroll") for (int m = 0; m < 4; ++m) _Pragma("unroll") for (int k = 0; k < 2; ++k) dst[m][k] = *(const LAS bf16x8*)(lds + PG8_SA(b, h) + aoff + m * 2048 + k * 1024); } while (0)
; #define PG8_LDB(dst, b, h) do { _Pragma("unroll") for (int n = 0; n < 2; ++n) _Pragma("unroll") for (int k = 0; k < 2; ++k) dst[n][k] = *(const LAS bf16x8*)(lds + PG8_SB(b, h) + boff + n * 2048 + k * 1024); } while (0)
; #define PG8_MMA(ai, bj, At, Bt) do { __builtin_amdgcn_s_setprio(1); _Pragma("unroll") for (int m = 0; m < 4; ++m) _Pragma("unroll") for (int n = 0; n < 2; ++n) _Pragma("unroll") for (int k = 0; k < 2; ++k) \
;         acc[ai][bj][m][n] = __builtin_amdgcn_mfma_f32_16x16x32_bf16(Bt[n][k], At[m][k], acc[ai][bj][m][n], 0, 0, 0); __builtin_amdgcn_s_setprio(0); } while (0)
; #define PG8_WAIT_V(n) asm volatile("s_waitcnt vmcnt(" #n ")" ::: "memory")
; #define PG8_WAIT_L(n) asm volatile("s_waitcnt lgkmcnt(" #n ")" ::: "memory")
; #define PG8_BAR __builtin_amdgcn_s_barrier()
; #define PG8_SCHED __builtin_amdgcn_sched_barrier(0)
; template <class Epi>
; __device__ __forceinline__ void gemm_phase(LAS unsigned char* lds, const Gemm g, const StaticOrder S, const Epi E) {
;     ...
;             PG8_STAGE(PG8_SB(0, 1), b2 + hstep, voffA);
;             PG8_WAIT_V(6); PG8_BAR; PG8_MMA(1, 1, At, B1); PG8_BAR;
;             PG8_LDB(B0, 1, 0); PG8_SCHED; PG8_LDA(At, 1, 0); PG8_STAGE(PG8_SA(0, 1), a2 + hstep, voffA);
;             PG8_WAIT_L(8); PG8_BAR; PG8_WAIT_L(0); PG8_MMA(0, 0, At, B0); PG8_BAR; PG8_SCHED;
;             PG8_LDB(B1, 1, 1); PG8_STAGE(PG8_SB(1, 0), b3, voffA);
;             PG8_BAR; PG8_WAIT_L(0); PG8_MMA(0, 1, At, B1); PG8_BAR;
;             PG8_LDA(At, 1, 1); PG8_STAGE(PG8_SA(1, 0), a3, voffA);
;             PG8_BAR; PG8_WAIT_L(0); PG8_MMA(1, 0, At, B0); PG8_BAR; PG8_SCHED;
	s_add_u32 s30, s50, 0x80000
	s_addc_u32 s31, s51, 0
	s_add_i32 s42, s42, s22
	v_lshl_add_u64 v[128:129], s[30:31], 0, v[178:179]
	s_mov_b32 m0, s42
	s_nop 0
	global_load_lds_dwordx4 v[128:129], off
	v_lshl_add_u64 v[128:129], s[30:31], 0, v[134:135]
	s_add_i32 m0, s42, 0x2000
	s_nop 0
	global_load_lds_dwordx4 v[128:129], off
	s_waitcnt vmcnt(6)
	s_barrier
	s_setprio 1
	v_mfma_f32_16x16x32_bf16 v[52:55], v[232:235], v[162:165], v[52:55]
	v_mfma_f32_16x16x32_bf16 v[48:51], v[240:243], v[162:165], v[48:51]
	v_mfma_f32_16x16x32_bf16 v[36:39], v[232:235], v[170:173], v[36:39]
	v_mfma_f32_16x16x32_bf16 v[32:35], v[240:243], v[170:173], v[32:35]
	v_mfma_f32_16x16x32_bf16 v[20:23], v[232:235], v[198:201], v[20:23]
	v_mfma_f32_16x16x32_bf16 v[16:19], v[240:243], v[198:201], v[16:19]
	v_mfma_f32_16x16x32_bf16 v[4:7], v[232:235], v[206:209], v[4:7]
	v_mfma_f32_16x16x32_bf16 v[0:3], v[240:243], v[206:209], v[0:3]
	v_mfma_f32_16x16x32_bf16 v[52:55], v[236:239], v[166:169], v[52:55]
	v_mfma_f32_16x16x32_bf16 v[48:51], v[244:247], v[166:169], v[48:51]
	v_mfma_f32_16x16x32_bf16 v[36:39], v[236:239], v[194:197], v[36:39]
	v_mfma_f32_16x16x32_bf16 v[32:35], v[244:247], v[194:197], v[32:35]
	v_mfma_f32_16x16x32_bf16 v[20:23], v[236:239], v[202:205], v[20:23]
	v_mfma_f32_16x16x32_bf16 v[16:19], v[244:247], v[202:205], v[16:19]
	v_mfma_f32_16x16x32_bf16 v[4:7], v[236:239], v[228:231], v[4:7]
	v_mfma_f32_16x16x32_bf16 v[0:3], v[244:247], v[228:231], v[0:3]
	s_setprio 0
	s_barrier
	s_add_i32 s42, 0, 0x18000
	v_add_u32_e32 v157, s42, v151
	ds_read_b128 v[128:131], v157
	ds_read_b128 v[142:145], v157 offset:1024
	ds_read_b128 v[146:149], v157 offset:2048
	ds_read_b128 v[158:161], v157 offset:3072
	s_add_u32 s30, s52, 0x80000
	s_addc_u32 s31, s53, 0
	s_mov_b32 m0, s25
	v_lshl_add_u64 v[222:223], s[30:31], 0, v[178:179]
	ds_read_b128 v[162:165], v156 offset:32768
	ds_read_b128 v[166:169], v156 offset:33792
	ds_read_b128 v[170:173], v156 offset:34816
	ds_read_b128 v[194:197], v156 offset:35840
	ds_read_b128 v[198:201], v156 offset:36864
	ds_read_b128 v[202:205], v156 offset:37888
	ds_read_b128 v[206:209], v156 offset:38912
	ds_read_b128 v[228:231], v156 offset:39936
	global_load_lds_dwordx4 v[222:223], off
	v_lshl_add_u64 v[222:223], s[30:31], 0, v[134:135]
	s_mov_b32 m0, s26
	s_nop 0
	global_load_lds_dwordx4 v[222:223], off
	s_waitcnt lgkmcnt(8)
	s_barrier
	s_waitcnt lgkmcnt(0)
	s_setprio 1
	v_mfma_f32_16x16x32_bf16 v[124:127], v[128:131], v[162:165], v[124:127]
	v_mfma_f32_16x16x32_bf16 v[120:123], v[146:149], v[162:165], v[120:123]
	v_mfma_f32_16x16x32_bf16 v[108:111], v[128:131], v[170:173], v[108:111]
	v_mfma_f32_16x16x32_bf16 v[104:107], v[146:149], v[170:173], v[104:107]
	v_mfma_f32_16x16x32_bf16 v[92:95], v[128:131], v[198:201], v[92:95]
	v_mfma_f32_16x16x32_bf16 v[88:91], v[146:149], v[198:201], v[88:91]
	v_mfma_f32_16x16x32_bf16 v[76:79], v[128:131], v[206:209], v[76:79]
	v_mfma_f32_16x16x32_bf16 v[72:75], v[146:149], v[206:209], v[72:75]
	v_mfma_f32_16x16x32_bf16 v[124:127], v[142:145], v[166:169], v[124:127]
	v_mfma_f32_16x16x32_bf16 v[120:123], v[158:161], v[166:169], v[120:123]
	v_mfma_f32_16x16x32_bf16 v[108:111], v[142:145], v[194:197], v[108:111]
	v_mfma_f32_16x16x32_bf16 v[104:107], v[158:161], v[194:197], v[104:107]
	v_mfma_f32_16x16x32_bf16 v[92:95], v[142:145], v[202:205], v[92:95]
	v_mfma_f32_16x16x32_bf16 v[88:91], v[158:161], v[202:205], v[88:91]
	v_mfma_f32_16x16x32_bf16 v[76:79], v[142:145], v[228:231], v[76:79]
	v_mfma_f32_16x16x32_bf16 v[72:75], v[158:161], v[228:231], v[72:75]
	s_setprio 0
	s_barrier
	s_add_i32 s43, 0, 0x1c000
	s_add_i32 s30, s42, s22
	v_add_u32_e32 v157, s43, v151
	v_lshl_add_u64 v[132:133], v[132:133], 0, s[34:35]
	s_mov_b32 m0, s30
	ds_read_b128 v[232:235], v157
	ds_read_b128 v[236:239], v157 offset:1024
	ds_read_b128 v[240:243], v157 offset:2048
	ds_read_b128 v[244:247], v157 offset:3072
	global_load_lds_dwordx4 v[132:133], off
	v_lshl_add_u64 v[132:133], v[174:175], 0, s[34:35]
	s_add_i32 m0, s30, 0x2000
	s_nop 0
	global_load_lds_dwordx4 v[132:133], off
	s_barrier
	s_waitcnt lgkmcnt(0)
	s_setprio 1
	v_mfma_f32_16x16x32_bf16 v[116:119], v[232:235], v[162:165], v[116:119]
	v_mfma_f32_16x16x32_bf16 v[112:115], v[240:243], v[162:165], v[112:115]
	v_mfma_f32_16x16x32_bf16 v[100:103], v[232:235], v[170:173], v[100:103]
	v_mfma_f32_16x16x32_bf16 v[96:99], v[240:243], v[170:173], v[96:99]
	v_mfma_f32_16x16x32_bf16 v[84:87], v[232:235], v[198:201], v[84:87]
	v_mfma_f32_16x16x32_bf16 v[80:83], v[240:243], v[198:201], v[80:83]
	v_mfma_f32_16x16x32_bf16 v[68:71], v[232:235], v[206:209], v[68:71]
	v_mfma_f32_16x16x32_bf16 v[64:67], v[240:243], v[206:209], v[64:67]
	v_mfma_f32_16x16x32_bf16 v[116:119], v[236:239], v[166:169], v[116:119]
	v_mfma_f32_16x16x32_bf16 v[112:115], v[244:247], v[166:169], v[112:115]
	v_mfma_f32_16x16x32_bf16 v[100:103], v[236:239], v[194:197], v[100:103]
	v_mfma_f32_16x16x32_bf16 v[96:99], v[244:247], v[194:197], v[96:99]
	v_mfma_f32_16x16x32_bf16 v[84:87], v[236:239], v[202:205], v[84:87]
	v_mfma_f32_16x16x32_bf16 v[80:83], v[244:247], v[202:205], v[80:83]
	v_mfma_f32_16x16x32_bf16 v[68:71], v[236:239], v[228:231], v[68:71]
	v_mfma_f32_16x16x32_bf16 v[64:67], v[244:247], v[228:231], v[64:67]
	s_setprio 0
	s_barrier
; #define PG8_STAGE(bufoff, gbase, voff) do { _Pragma("unroll") for (int _i = 0; _i < 2; ++_i) \
;         __builtin_amdgcn_global_load_lds((const unsigned*)((const char*)(gbase) + (voff)[_i]), (LAS unsigned*)(lds + (bufoff) + ldsw + _i * 8192), 16, 0, 0); } while (0)
; #define PG8_MMA(ai, bj, At, Bt) do { __builtin_amdgcn_s_setprio(1); _Pragma("unroll") for (int m = 0; m < 4; ++m) _Pragma("unroll") for (int n = 0; n < 2; ++n) _Pragma("unroll") for (int k = 0; k < 2; ++k) \
;         acc[ai][bj][m][n] = __builtin_amdgcn_mfma_f32_16x16x32_bf16(Bt[n][k], At[m][k], acc[ai][bj][m][n], 0, 0, 0); __builtin_amdgcn_s_setprio(0); } while (0)
; #define PG8_WAIT_V(n) asm volatile("s_waitcnt vmcnt(" #n ")" ::: "memory")
; #define PG8_WAIT_L(n) asm volatile("s_waitcnt lgkmcnt(" #n ")" ::: "memory")
; #define PG8_BAR __builtin_amdgcn_s_barrier()
; #define PG8_SCHED __builtin_amdgcn_sched_barrier(0)
; template <class Epi>
; __device__ __forceinline__ void gemm_phase(LAS unsigned char* lds, const Gemm g, const StaticOrder S, const Epi E) {
;     ...
;             PG8_BAR; PG8_WAIT_L(0); PG8_MMA(1, 0, At, B0); PG8_BAR; PG8_SCHED;
;             PG8_STAGE(PG8_SB(1, 1), b3 + hstep, voffA);
;             PG8_WAIT_V(6); PG8_BAR; PG8_MMA(1, 1, At, B1); PG8_BAR;
;         }
;     __device__ __forceinline__ void operator()(AccRef acc, const pg8::Unit& u, int wr, int wc, int fr, int fq) const {
;         const int row0 = u.pm * 256 + wr * 64 + fr, col0 = u.pn * 256 + wc * 32 + 4 * fq;
;         const bool rope = (u.pn == rope_pn) && (u.pm < 32);
; #pragma unroll
;         for (int ai = 0; ai < 2; ++ai)
; #pragma unroll
;             for (int m = 0; m < 4; ++m) { const int row = row0 + ai * 128 + m * 16; bf16_t* rowp = O + (size_t)row * ldc + col0;
;                 f32x4 cs = {1.f, 1.f, 1.f, 1.f}, sn = {0.f, 0.f, 0.f, 0.f};
;                 if (rope) { const int t = row & 2047; const int pos = (wc & 1) ? (t & 63) : (t >> 6); cs = *(const f32x4*)(cos64 + pos * 16 + 4 * fq); sn = *(const f32x4*)(sin64 + pos * 16 + 4 * fq); }
	s_mov_b32 m0, s28
	v_lshl_add_u64 v[132:133], v[210:211], 0, s[34:35]
	ds_read_b128 v[162:165], v156 offset:49152
	ds_read_b128 v[166:169], v156 offset:50176
	ds_read_b128 v[170:173], v156 offset:51200
	ds_read_b128 v[194:197], v156 offset:52224
	ds_read_b128 v[198:201], v156 offset:53248
	ds_read_b128 v[202:205], v156 offset:54272
	ds_read_b128 v[206:209], v156 offset:55296
	ds_read_b128 v[228:231], v156 offset:56320
	global_load_lds_dwordx4 v[132:133], off
	v_lshl_add_u64 v[132:133], v[220:221], 0, s[34:35]
	s_mov_b32 m0, s29
	s_nop 0
	global_load_lds_dwordx4 v[132:133], off
	s_barrier
	s_waitcnt lgkmcnt(0)
	s_setprio 1
	v_mfma_f32_16x16x32_bf16 v[60:63], v[128:131], v[162:165], v[60:63]
	v_mfma_f32_16x16x32_bf16 v[56:59], v[146:149], v[162:165], v[56:59]
	v_mfma_f32_16x16x32_bf16 v[44:47], v[128:131], v[170:173], v[44:47]
	v_mfma_f32_16x16x32_bf16 v[40:43], v[146:149], v[170:173], v[40:43]
	v_mfma_f32_16x16x32_bf16 v[28:31], v[128:131], v[198:201], v[28:31]
	v_mfma_f32_16x16x32_bf16 v[24:27], v[146:149], v[198:201], v[24:27]
	v_mfma_f32_16x16x32_bf16 v[12:15], v[128:131], v[206:209], v[12:15]
	v_mfma_f32_16x16x32_bf16 v[8:11], v[146:149], v[206:209], v[8:11]
	v_mfma_f32_16x16x32_bf16 v[60:63], v[142:145], v[166:169], v[60:63]
	v_mfma_f32_16x16x32_bf16 v[56:59], v[158:161], v[166:169], v[56:59]
	v_mfma_f32_16x16x32_bf16 v[44:47], v[142:145], v[194:197], v[44:47]
	v_mfma_f32_16x16x32_bf16 v[40:43], v[158:161], v[194:197], v[40:43]
	v_mfma_f32_16x16x32_bf16 v[28:31], v[142:145], v[202:205], v[28:31]
	v_mfma_f32_16x16x32_bf16 v[24:27], v[158:161], v[202:205], v[24:27]
	v_mfma_f32_16x16x32_bf16 v[12:15], v[142:145], v[228:231], v[12:15]
	v_mfma_f32_16x16x32_bf16 v[8:11], v[158:161], v[228:231], v[8:11]
	s_setprio 0
	s_barrier
	s_add_u32 s30, s50, 0x80080
	s_addc_u32 s31, s51, 0
	s_add_i32 s42, s43, s22
	v_lshl_add_u64 v[128:129], s[30:31], 0, v[178:179]
	s_mov_b32 m0, s42
	s_nop 0
	global_load_lds_dwordx4 v[128:129], off
	v_lshl_add_u64 v[128:129], s[30:31], 0, v[134:135]
	s_add_i32 m0, s42, 0x2000
	s_nop 0
	global_load_lds_dwordx4 v[128:129], off
	s_waitcnt vmcnt(6)
	s_barrier
	s_setprio 1
	v_mfma_f32_16x16x32_bf16 v[52:55], v[232:235], v[162:165], v[52:55]
	v_mfma_f32_16x16x32_bf16 v[48:51], v[240:243], v[162:165], v[48:51]
	v_mfma_f32_16x16x32_bf16 v[36:39], v[232:235], v[170:173], v[36:39]
	v_mfma_f32_16x16x32_bf16 v[32:35], v[240:243], v[170:173], v[32:35]
	v_mfma_f32_16x16x32_bf16 v[20:23], v[232:235], v[198:201], v[20:23]
	v_mfma_f32_16x16x32_bf16 v[16:19], v[240:243], v[198:201], v[16:19]
	v_mfma_f32_16x16x32_bf16 v[4:7], v[232:235], v[206:209], v[4:7]
	v_mfma_f32_16x16x32_bf16 v[0:3], v[240:243], v[206:209], v[0:3]
	v_mfma_f32_16x16x32_bf16 v[52:55], v[236:239], v[166:169], v[52:55]
	v_mfma_f32_16x16x32_bf16 v[48:51], v[244:247], v[166:169], v[48:51]
	v_mfma_f32_16x16x32_bf16 v[36:39], v[236:239], v[194:197], v[36:39]
	v_mfma_f32_16x16x32_bf16 v[32:35], v[244:247], v[194:197], v[32:35]
	v_mfma_f32_16x16x32_bf16 v[20:23], v[236:239], v[202:205], v[20:23]
	v_mfma_f32_16x16x32_bf16 v[16:19], v[244:247], v[202:205], v[16:19]
	v_mfma_f32_16x16x32_bf16 v[4:7], v[236:239], v[228:231], v[4:7]
	v_mfma_f32_16x16x32_bf16 v[0:3], v[244:247], v[228:231], v[0:3]
	s_setprio 0
	s_barrier
	s_add_i32 s57, s57, 2
	s_add_u32 s3, s3, 0x100
	s_addc_u32 s11, s11, 0
	s_cmp_gt_u32 s57, 29
	s_mov_b64 s[42:43], s[48:49]
	s_cbranch_scc0 .LBB0_2721
	s_lshl_b32 s11, s56, 8
	s_add_i32 s11, s11, s27
	s_cmp_eq_u32 s55, -1
	s_cselect_b64 s[30:31], -1, 0
	s_cmp_lt_i32 s56, 32
	s_cselect_b64 s[42:43], -1, 0
	s_and_b64 s[30:31], s[30:31], s[42:43]
	v_cndmask_b32_e64 v129, 0, 1, s[30:31]
	s_bfe_u32 s3, s11, 0x50006
	v_mov_b32_e32 v144, 1.0
	v_mov_b32_e32 v128, 0
	v_cmp_ne_u32_e64 s[42:43], 1, v129
	s_andn2_b64 vcc, exec, s[30:31]
	v_mov_b32_e32 v130, 0
	v_mov_b32_e32 v131, 0
	v_mov_b32_e32 v132, 0
	v_mov_b32_e32 v133, 0
	v_mov_b32_e32 v146, 1.0
	v_mov_b32_e32 v147, 1.0
	v_mov_b32_e32 v148, 1.0
	v_mov_b32_e32 v149, 1.0
	s_cbranch_vccnz .LBB0_2724
	v_mov_b32_e32 v129, s3
	v_cndmask_b32_e64 v129, v150, v129, s[38:39]
	v_lshl_or_b32 v130, v129, 6, v136
	v_mov_b32_e32 v131, v137
	flat_load_dwordx4 v[130:133], v[130:131]
	s_waitcnt vmcnt(0) lgkmcnt(0)
	v_mov_b32_e32 v146, v130
	v_mov_b32_e32 v147, v131
	v_mov_b32_e32 v148, v132
	v_mov_b32_e32 v149, v133

; #define PG8_STAGE(bufoff, gbase, voff) do { _Pragma("unroll") for (int _i = 0; _i < 2; ++_i) \
;         __builtin_amdgcn_global_load_lds((const unsigned*)((const char*)(gbase) + (voff)[_i]), (LAS unsigned*)(lds + (bufoff) + ldsw + _i * 8192), 16, 0, 0); } while (0)
; #define PG8_LDA(dst, b, h) do { _Pragma("unroll") for (int m = 0; m < 4; ++m) _Pragma("unroll") for (int k = 0; k < 2; ++k) dst[m][k] = *(const LAS bf16x8*)(lds + PG8_SA(b, h) + aoff + m * 2048 + k * 1024); } while (0)
; #define PG8_LDB(dst, b, h) do { _Pragma("unroll") for (int n = 0; n < 2; ++n) _Pragma("unroll") for (int k = 0; k < 2; ++k) dst[n][k] = *(const LAS bf16x8*)(lds + PG8_SB(b, h) + boff + n * 2048 + k * 1024); } while (0)
; #define PG8_MMA(ai, bj, At, Bt) do { __builtin_amdgcn_s_setprio(1); _Pragma("unroll") for (int m = 0; m < 4; ++m) _Pragma("unroll") for (int n = 0; n < 2; ++n) _Pragma("unroll") for (int k = 0; k < 2; ++k) \
;         acc[ai][bj][m][n] = __builtin_amdgcn_mfma_f32_16x16x32_bf16(Bt[n][k], At[m][k], acc[ai][bj][m][n], 0, 0, 0); __builtin_amdgcn_s_setprio(0); } while (0)
; #define PG8_WAIT_L(n) asm volatile("s_waitcnt lgkmcnt(" #n ")" ::: "memory")
; #define PG8_BAR __builtin_amdgcn_s_barrier()
; #define PG8_SCHED __builtin_amdgcn_sched_barrier(0)
; template <class Epi>
; __device__ __forceinline__ void gemm_phase(LAS unsigned char* lds, const Gemm g, const StaticOrder S, const Epi E) {
;     ...
;         for (int t = 0; t < nt; t += 2) {
;             const bool last = (t == nt - 2);
;             const char* a1 = cA + (size_t)(t + 1) * kstep;
;             const char* a2 = last ? nA : cA + (size_t)(t + 2) * kstep; const char* b2 = last ? nB : cB + (size_t)(t + 2) * kstep;
;             const char* a3 = a2 + kstep; const char* b3 = b2 + kstep;
;             PG8_LDB(B0, 0, 0); PG8_SCHED; PG8_LDA(At, 0, 0); PG8_STAGE(PG8_SA(1, 1), a1 + hstep, voffA);
;             PG8_WAIT_L(8); PG8_BAR; PG8_WAIT_L(0); PG8_MMA(0, 0, At, B0); PG8_BAR; PG8_SCHED;
;             PG8_LDB(B1, 0, 1); PG8_STAGE(PG8_SB(0, 0), b2, voffA);
;             PG8_BAR; PG8_WAIT_L(0); PG8_MMA(0, 1, At, B1); PG8_BAR;
;             PG8_LDA(At, 0, 1); PG8_STAGE(PG8_SA(0, 0), a2, voffA);
;             PG8_BAR; PG8_WAIT_L(0); PG8_MMA(1, 0, At, B0); PG8_BAR; PG8_SCHED;
.LBB0_3278:
	s_add_u32 s54, s52, 0x100
	s_addc_u32 s55, s53, 0
	s_add_i32 s28, 0, 0x10000
	v_add_u32_e32 v140, s28, v157
	ds_read_b128 v[128:131], v140
	ds_read_b128 v[132:135], v140 offset:1024
	ds_read_b128 v[136:139], v140 offset:2048
	ds_read_b128 v[164:167], v140 offset:3072
	s_cmp_eq_u32 s27, 4
	s_cselect_b32 s59, s47, s55
	s_cselect_b32 s58, s46, s54
	s_cselect_b32 s57, s49, s3
	s_cselect_b32 s56, s48, s1
	v_lshl_add_u64 v[140:141], s[52:53], 0, v[150:151]
	s_add_i32 m0, s23, 0xc000
	ds_read_b128 v[168:171], v162
	ds_read_b128 v[172:175], v162 offset:1024
	ds_read_b128 v[194:197], v162 offset:2048
	ds_read_b128 v[198:201], v162 offset:3072
	ds_read_b128 v[202:205], v162 offset:4096
	ds_read_b128 v[206:209], v162 offset:5120
	ds_read_b128 v[228:231], v162 offset:6144
	ds_read_b128 v[232:235], v162 offset:7168
	global_load_lds_dwordx4 v[140:141], off
	v_lshl_add_u64 v[140:141], s[52:53], 0, v[152:153]
	s_add_i32 m0, s23, 0xe000
	s_nop 0
	global_load_lds_dwordx4 v[140:141], off
	s_waitcnt lgkmcnt(8)
	s_barrier
	s_waitcnt lgkmcnt(0)
	s_setprio 1
	v_mfma_f32_16x16x32_bf16 v[124:127], v[128:131], v[168:171], v[124:127]
	v_mfma_f32_16x16x32_bf16 v[120:123], v[136:139], v[168:171], v[120:123]
	v_mfma_f32_16x16x32_bf16 v[108:111], v[128:131], v[194:197], v[108:111]
	v_mfma_f32_16x16x32_bf16 v[104:107], v[136:139], v[194:197], v[104:107]
	v_mfma_f32_16x16x32_bf16 v[92:95], v[128:131], v[202:205], v[92:95]
	v_mfma_f32_16x16x32_bf16 v[88:91], v[136:139], v[202:205], v[88:91]
	v_mfma_f32_16x16x32_bf16 v[76:79], v[128:131], v[228:231], v[76:79]
	v_mfma_f32_16x16x32_bf16 v[72:75], v[136:139], v[228:231], v[72:75]
	v_mfma_f32_16x16x32_bf16 v[124:127], v[132:135], v[172:175], v[124:127]
	v_mfma_f32_16x16x32_bf16 v[120:123], v[164:167], v[172:175], v[120:123]
	v_mfma_f32_16x16x32_bf16 v[108:111], v[132:135], v[198:201], v[108:111]
	v_mfma_f32_16x16x32_bf16 v[104:107], v[164:167], v[198:201], v[104:107]
	v_mfma_f32_16x16x32_bf16 v[92:95], v[132:135], v[206:209], v[92:95]
	v_mfma_f32_16x16x32_bf16 v[88:91], v[164:167], v[206:209], v[88:91]
	v_mfma_f32_16x16x32_bf16 v[76:79], v[132:135], v[232:235], v[76:79]
	v_mfma_f32_16x16x32_bf16 v[72:75], v[164:167], v[232:235], v[72:75]
	s_setprio 0
	s_barrier
	s_add_i32 s30, 0, 0x14000
	v_add_u32_e32 v140, s30, v157
	s_add_i32 s28, s28, s22
	ds_read_b128 v[236:239], v140
	ds_read_b128 v[240:243], v140 offset:1024
	ds_read_b128 v[244:247], v140 offset:2048
	ds_read_b128 v[220:223], v140 offset:3072
	v_lshl_add_u64 v[140:141], s[56:57], 0, v[142:143]
	s_mov_b32 m0, s28
	v_lshl_add_u64 v[154:155], s[56:57], 0, v[144:145]
	global_load_lds_dwordx4 v[140:141], off
	s_add_i32 m0, s28, 0x2000
	s_nop 0
	global_load_lds_dwordx4 v[154:155], off
	s_barrier
	s_waitcnt lgkmcnt(0)
	s_setprio 1
	v_mfma_f32_16x16x32_bf16 v[116:119], v[236:239], v[168:171], v[116:119]
	v_mfma_f32_16x16x32_bf16 v[112:115], v[244:247], v[168:171], v[112:115]
	v_mfma_f32_16x16x32_bf16 v[100:103], v[236:239], v[194:197], v[100:103]
	v_mfma_f32_16x16x32_bf16 v[96:99], v[244:247], v[194:197], v[96:99]
	v_mfma_f32_16x16x32_bf16 v[84:87], v[236:239], v[202:205], v[84:87]
	v_mfma_f32_16x16x32_bf16 v[80:83], v[244:247], v[202:205], v[80:83]
	v_mfma_f32_16x16x32_bf16 v[68:71], v[236:239], v[228:231], v[68:71]
	v_mfma_f32_16x16x32_bf16 v[64:67], v[244:247], v[228:231], v[64:67]
	v_mfma_f32_16x16x32_bf16 v[116:119], v[240:243], v[172:175], v[116:119]
	v_mfma_f32_16x16x32_bf16 v[112:115], v[220:223], v[172:175], v[112:115]
	v_mfma_f32_16x16x32_bf16 v[100:103], v[240:243], v[198:201], v[100:103]
	v_mfma_f32_16x16x32_bf16 v[96:99], v[220:223], v[198:201], v[96:99]
	v_mfma_f32_16x16x32_bf16 v[84:87], v[240:243], v[206:209], v[84:87]
	v_mfma_f32_16x16x32_bf16 v[80:83], v[220:223], v[206:209], v[80:83]
	v_mfma_f32_16x16x32_bf16 v[68:71], v[240:243], v[232:235], v[68:71]
	v_mfma_f32_16x16x32_bf16 v[64:67], v[220:223], v[232:235], v[64:67]
	s_setprio 0
	s_barrier
	s_mov_b32 m0, s23
	v_lshl_add_u64 v[210:211], s[58:59], 0, v[142:143]
	ds_read_b128 v[168:171], v162 offset:16384
	ds_read_b128 v[172:175], v162 offset:17408
	ds_read_b128 v[194:197], v162 offset:18432
	ds_read_b128 v[198:201], v162 offset:19456
	ds_read_b128 v[202:205], v162 offset:20480
	ds_read_b128 v[206:209], v162 offset:21504
	ds_read_b128 v[228:231], v162 offset:22528
	ds_read_b128 v[232:235], v162 offset:23552
	global_load_lds_dwordx4 v[210:211], off
	v_lshl_add_u64 v[248:249], s[58:59], 0, v[144:145]
	s_mov_b32 m0, s24
	s_nop 0
	global_load_lds_dwordx4 v[248:249], off
	s_barrier
	s_waitcnt lgkmcnt(0)
	s_setprio 1
	v_mfma_f32_16x16x32_bf16 v[60:63], v[128:131], v[168:171], v[60:63]
	v_mfma_f32_16x16x32_bf16 v[56:59], v[136:139], v[168:171], v[56:59]
	v_mfma_f32_16x16x32_bf16 v[44:47], v[128:131], v[194:197], v[44:47]
	v_mfma_f32_16x16x32_bf16 v[40:43], v[136:139], v[194:197], v[40:43]
	v_mfma_f32_16x16x32_bf16 v[28:31], v[128:131], v[202:205], v[28:31]
	v_mfma_f32_16x16x32_bf16 v[24:27], v[136:139], v[202:205], v[24:27]
	v_mfma_f32_16x16x32_bf16 v[12:15], v[128:131], v[228:231], v[12:15]
	v_mfma_f32_16x16x32_bf16 v[8:11], v[136:139], v[228:231], v[8:11]
	v_mfma_f32_16x16x32_bf16 v[60:63], v[132:135], v[172:175], v[60:63]
	v_mfma_f32_16x16x32_bf16 v[56:59], v[164:167], v[172:175], v[56:59]
	v_mfma_f32_16x16x32_bf16 v[44:47], v[132:135], v[198:201], v[44:47]
	v_mfma_f32_16x16x32_bf16 v[40:43], v[164:167], v[198:201], v[40:43]
	v_mfma_f32_16x16x32_bf16 v[28:31], v[132:135], v[206:209], v[28:31]
	v_mfma_f32_16x16x32_bf16 v[24:27], v[164:167], v[206:209], v[24:27]
	v_mfma_f32_16x16x32_bf16 v[12:15], v[132:135], v[232:235], v[12:15]
	v_mfma_f32_16x16x32_bf16 v[8:11], v[164:167], v[232:235], v[8:11]
	s_setprio 0
	s_barrier
; #define PG8_STAGE(bufoff, gbase, voff) do { _Pragma("unroll") for (int _i = 0; _i < 2; ++_i) \
;         __builtin_amdgcn_global_load_lds((const unsigned*)((const char*)(gbase) + (voff)[_i]), (LAS unsigned*)(lds + (bufoff) + ldsw + _i * 8192), 16, 0, 0); } while (0)
; #define PG8_LDA(dst, b, h) do { _Pragma("unroll") for (int m = 0; m < 4; ++m) _Pragma("unroll") for (int k = 0; k < 2; ++k) dst[m][k] = *(const LAS bf16x8*)(lds + PG8_SA(b, h) + aoff + m * 2048 + k * 1024); } while (0)
; #define PG8_LDB(dst, b, h) do { _Pragma("unroll") for (int n = 0; n < 2; ++n) _Pragma("unroll") for (int k = 0; k < 2; ++k) dst[n][k] = *(const LAS bf16x8*)(lds + PG8_SB(b, h) + boff + n * 2048 + k * 1024); } while (0)
; #define PG8_MMA(ai, bj, At, Bt) do { __builtin_amdgcn_s_setprio(1); _Pragma("unroll") for (int m = 0; m < 4; ++m) _Pragma("unroll") for (int n = 0; n < 2; ++n) _Pragma("unroll") for (int k = 0; k < 2; ++k) \
;         acc[ai][bj][m][n] = __builtin_amdgcn_mfma_f32_16x16x32_bf16(Bt[n][k], At[m][k], acc[ai][bj][m][n], 0, 0, 0); __builtin_amdgcn_s_setprio(0); } while (0)
; #define PG8_WAIT_V(n) asm volatile("s_waitcnt vmcnt(" #n ")" ::: "memory")
; #define PG8_WAIT_L(n) asm volatile("s_waitcnt lgkmcnt(" #n ")" ::: "memory")
; #define PG8_BAR __builtin_amdgcn_s_barrier()
; #define PG8_SCHED __builtin_amdgcn_sched_barrier(0)
; template <class Epi>
; __device__ __forceinline__ void gemm_phase(LAS unsigned char* lds, const Gemm g, const StaticOrder S, const Epi E) {
;     ...
;             PG8_STAGE(PG8_SB(0, 1), b2 + hstep, voffA);
;             PG8_WAIT_V(6); PG8_BAR; PG8_MMA(1, 1, At, B1); PG8_BAR;
;             PG8_LDB(B0, 1, 0); PG8_SCHED; PG8_LDA(At, 1, 0); PG8_STAGE(PG8_SA(0, 1), a2 + hstep, voffA);
;             PG8_WAIT_L(8); PG8_BAR; PG8_WAIT_L(0); PG8_MMA(0, 0, At, B0); PG8_BAR; PG8_SCHED;
;             PG8_LDB(B1, 1, 1); PG8_STAGE(PG8_SB(1, 0), b3, voffA);
;             PG8_BAR; PG8_WAIT_L(0); PG8_MMA(0, 1, At, B1); PG8_BAR;
;             PG8_LDA(At, 1, 1); PG8_STAGE(PG8_SA(1, 0), a3, voffA);
;             PG8_BAR; PG8_WAIT_L(0); PG8_MMA(1, 0, At, B0); PG8_BAR; PG8_SCHED;
	s_add_u32 s28, s56, 0x20000
	s_addc_u32 s29, s57, 0
	s_add_i32 s30, s30, s22
	v_lshl_add_u64 v[128:129], s[28:29], 0, v[142:143]
	s_mov_b32 m0, s30
	s_nop 0
	global_load_lds_dwordx4 v[128:129], off
	v_lshl_add_u64 v[128:129], s[28:29], 0, v[144:145]
	s_add_i32 m0, s30, 0x2000
	s_nop 0
	global_load_lds_dwordx4 v[128:129], off
	s_waitcnt vmcnt(6)
	s_barrier
	s_setprio 1
	v_mfma_f32_16x16x32_bf16 v[52:55], v[236:239], v[168:171], v[52:55]
	v_mfma_f32_16x16x32_bf16 v[48:51], v[244:247], v[168:171], v[48:51]
	v_mfma_f32_16x16x32_bf16 v[36:39], v[236:239], v[194:197], v[36:39]
	v_mfma_f32_16x16x32_bf16 v[32:35], v[244:247], v[194:197], v[32:35]
	v_mfma_f32_16x16x32_bf16 v[20:23], v[236:239], v[202:205], v[20:23]
	v_mfma_f32_16x16x32_bf16 v[16:19], v[244:247], v[202:205], v[16:19]
	v_mfma_f32_16x16x32_bf16 v[4:7], v[236:239], v[228:231], v[4:7]
	v_mfma_f32_16x16x32_bf16 v[0:3], v[244:247], v[228:231], v[0:3]
	v_mfma_f32_16x16x32_bf16 v[52:55], v[240:243], v[172:175], v[52:55]
	v_mfma_f32_16x16x32_bf16 v[48:51], v[220:223], v[172:175], v[48:51]
	v_mfma_f32_16x16x32_bf16 v[36:39], v[240:243], v[198:201], v[36:39]
	v_mfma_f32_16x16x32_bf16 v[32:35], v[220:223], v[198:201], v[32:35]
	v_mfma_f32_16x16x32_bf16 v[20:23], v[240:243], v[206:209], v[20:23]
	v_mfma_f32_16x16x32_bf16 v[16:19], v[220:223], v[206:209], v[16:19]
	v_mfma_f32_16x16x32_bf16 v[4:7], v[240:243], v[232:235], v[4:7]
	v_mfma_f32_16x16x32_bf16 v[0:3], v[220:223], v[232:235], v[0:3]
	s_setprio 0
	s_barrier
	s_add_i32 s30, 0, 0x18000
	v_add_u32_e32 v163, s30, v157
	ds_read_b128 v[128:131], v163
	ds_read_b128 v[132:135], v163 offset:1024
	ds_read_b128 v[136:139], v163 offset:2048
	ds_read_b128 v[164:167], v163 offset:3072
	s_add_u32 s28, s58, 0x20000
	s_addc_u32 s29, s59, 0
	s_mov_b32 m0, s25
	v_lshl_add_u64 v[232:233], s[28:29], 0, v[142:143]
	ds_read_b128 v[168:171], v162 offset:32768
	ds_read_b128 v[172:175], v162 offset:33792
	ds_read_b128 v[194:197], v162 offset:34816
	ds_read_b128 v[198:201], v162 offset:35840
	ds_read_b128 v[202:205], v162 offset:36864
	ds_read_b128 v[206:209], v162 offset:37888
	ds_read_b128 v[220:223], v162 offset:38912
	ds_read_b128 v[228:231], v162 offset:39936
	global_load_lds_dwordx4 v[232:233], off
	v_lshl_add_u64 v[232:233], s[28:29], 0, v[144:145]
	s_mov_b32 m0, s51
	s_nop 0
	global_load_lds_dwordx4 v[232:233], off
	s_waitcnt lgkmcnt(8)
	s_barrier
	s_waitcnt lgkmcnt(0)
	s_setprio 1
	v_mfma_f32_16x16x32_bf16 v[124:127], v[128:131], v[168:171], v[124:127]
	v_mfma_f32_16x16x32_bf16 v[120:123], v[136:139], v[168:171], v[120:123]
	v_mfma_f32_16x16x32_bf16 v[108:111], v[128:131], v[194:197], v[108:111]
	v_mfma_f32_16x16x32_bf16 v[104:107], v[136:139], v[194:197], v[104:107]
	v_mfma_f32_16x16x32_bf16 v[92:95], v[128:131], v[202:205], v[92:95]
	v_mfma_f32_16x16x32_bf16 v[88:91], v[136:139], v[202:205], v[88:91]
	v_mfma_f32_16x16x32_bf16 v[76:79], v[128:131], v[220:223], v[76:79]
	v_mfma_f32_16x16x32_bf16 v[72:75], v[136:139], v[220:223], v[72:75]
	v_mfma_f32_16x16x32_bf16 v[124:127], v[132:135], v[172:175], v[124:127]
	v_mfma_f32_16x16x32_bf16 v[120:123], v[164:167], v[172:175], v[120:123]
	v_mfma_f32_16x16x32_bf16 v[108:111], v[132:135], v[198:201], v[108:111]
	v_mfma_f32_16x16x32_bf16 v[104:107], v[164:167], v[198:201], v[104:107]
	v_mfma_f32_16x16x32_bf16 v[92:95], v[132:135], v[206:209], v[92:95]
	v_mfma_f32_16x16x32_bf16 v[88:91], v[164:167], v[206:209], v[88:91]
	v_mfma_f32_16x16x32_bf16 v[76:79], v[132:135], v[228:231], v[76:79]
	v_mfma_f32_16x16x32_bf16 v[72:75], v[164:167], v[228:231], v[72:75]
	s_setprio 0
	s_barrier
	s_add_i32 s31, 0, 0x1c000
	s_add_i32 s28, s30, s22
	v_add_u32_e32 v163, s31, v157
	v_lshl_add_u64 v[140:141], v[140:141], 0, s[34:35]
	s_mov_b32 m0, s28
	ds_read_b128 v[232:235], v163
	ds_read_b128 v[236:239], v163 offset:1024
	ds_read_b128 v[240:243], v163 offset:2048
	ds_read_b128 v[244:247], v163 offset:3072
	global_load_lds_dwordx4 v[140:141], off
	v_lshl_add_u64 v[140:141], v[154:155], 0, s[34:35]
	s_add_i32 m0, s28, 0x2000
	s_nop 0
	global_load_lds_dwordx4 v[140:141], off
	s_barrier
	s_waitcnt lgkmcnt(0)
	s_setprio 1
	v_mfma_f32_16x16x32_bf16 v[116:119], v[232:235], v[168:171], v[116:119]
	v_mfma_f32_16x16x32_bf16 v[112:115], v[240:243], v[168:171], v[112:115]
	v_mfma_f32_16x16x32_bf16 v[100:103], v[232:235], v[194:197], v[100:103]
	v_mfma_f32_16x16x32_bf16 v[96:99], v[240:243], v[194:197], v[96:99]
	v_mfma_f32_16x16x32_bf16 v[84:87], v[232:235], v[202:205], v[84:87]
	v_mfma_f32_16x16x32_bf16 v[80:83], v[240:243], v[202:205], v[80:83]
	v_mfma_f32_16x16x32_bf16 v[68:71], v[232:235], v[220:223], v[68:71]
	v_mfma_f32_16x16x32_bf16 v[64:67], v[240:243], v[220:223], v[64:67]
	v_mfma_f32_16x16x32_bf16 v[116:119], v[236:239], v[172:175], v[116:119]
	v_mfma_f32_16x16x32_bf16 v[112:115], v[244:247], v[172:175], v[112:115]
	v_mfma_f32_16x16x32_bf16 v[100:103], v[236:239], v[198:201], v[100:103]
	v_mfma_f32_16x16x32_bf16 v[96:99], v[244:247], v[198:201], v[96:99]
	v_mfma_f32_16x16x32_bf16 v[84:87], v[236:239], v[206:209], v[84:87]
	v_mfma_f32_16x16x32_bf16 v[80:83], v[244:247], v[206:209], v[80:83]
	v_mfma_f32_16x16x32_bf16 v[68:71], v[236:239], v[228:231], v[68:71]
	v_mfma_f32_16x16x32_bf16 v[64:67], v[244:247], v[228:231], v[64:67]
	s_setprio 0
	s_barrier
; #define PG8_STAGE(bufoff, gbase, voff) do { _Pragma("unroll") for (int _i = 0; _i < 2; ++_i) \
;         __builtin_amdgcn_global_load_lds((const unsigned*)((const char*)(gbase) + (voff)[_i]), (LAS unsigned*)(lds + (bufoff) + ldsw + _i * 8192), 16, 0, 0); } while (0)
; #define PG8_MMA(ai, bj, At, Bt) do { __builtin_amdgcn_s_setprio(1); _Pragma("unroll") for (int m = 0; m < 4; ++m) _Pragma("unroll") for (int n = 0; n < 2; ++n) _Pragma("unroll") for (int k = 0; k < 2; ++k) \
;         acc[ai][bj][m][n] = __builtin_amdgcn_mfma_f32_16x16x32_bf16(Bt[n][k], At[m][k], acc[ai][bj][m][n], 0, 0, 0); __builtin_amdgcn_s_setprio(0); } while (0)
; #define PG8_WAIT_V(n) asm volatile("s_waitcnt vmcnt(" #n ")" ::: "memory")
; #define PG8_WAIT_L(n) asm volatile("s_waitcnt lgkmcnt(" #n ")" ::: "memory")
; #define PG8_BAR __builtin_amdgcn_s_barrier()
; #define PG8_SCHED __builtin_amdgcn_sched_barrier(0)
; template <class Epi>
; __device__ __forceinline__ void gemm_phase(LAS unsigned char* lds, const Gemm g, const StaticOrder S, const Epi E) {
;     ...
;             PG8_BAR; PG8_WAIT_L(0); PG8_MMA(1, 0, At, B0); PG8_BAR; PG8_SCHED;
;             PG8_STAGE(PG8_SB(1, 1), b3 + hstep, voffA);
;             PG8_WAIT_V(6); PG8_BAR; PG8_MMA(1, 1, At, B1); PG8_BAR;
;         }
;     __device__ __forceinline__ void operator()(AccRef acc, const pg8::Unit& u, int wr, int wc, int fr, int fq) const {
;         const int row0 = u.pm * 256 + wr * 64 + fr, col0 = u.pn * 256 + wc * 32 + 4 * fq;
;         const bool rope = (u.pn == rope_pn) && (u.pm < 32);
; #pragma unroll
;         for (int ai = 0; ai < 2; ++ai)
; #pragma unroll
;             for (int m = 0; m < 4; ++m) { const int row = row0 + ai * 128 + m * 16; bf16_t* rowp = O + (size_t)row * ldc + col0;
;                 f32x4 cs = {1.f, 1.f, 1.f, 1.f}, sn = {0.f, 0.f, 0.f, 0.f};
;                 if (rope) { const int t = row & 2047; const int pos = (wc & 1) ? (t & 63) : (t >> 6); cs = *(const f32x4*)(cos64 + pos * 16 + 4 * fq); sn = *(const f32x4*)(sin64 + pos * 16 + 4 * fq); }
	s_mov_b32 m0, s61
	v_lshl_add_u64 v[140:141], v[210:211], 0, s[34:35]
	ds_read_b128 v[168:171], v162 offset:49152
	ds_read_b128 v[172:175], v162 offset:50176
	ds_read_b128 v[194:197], v162 offset:51200
	ds_read_b128 v[198:201], v162 offset:52224
	ds_read_b128 v[202:205], v162 offset:53248
	ds_read_b128 v[206:209], v162 offset:54272
	ds_read_b128 v[220:223], v162 offset:55296
	ds_read_b128 v[228:231], v162 offset:56320
	global_load_lds_dwordx4 v[140:141], off
	v_lshl_add_u64 v[140:141], v[248:249], 0, s[34:35]
	s_mov_b32 m0, s62
	s_nop 0
	global_load_lds_dwordx4 v[140:141], off
	s_barrier
	s_waitcnt lgkmcnt(0)
	s_setprio 1
	v_mfma_f32_16x16x32_bf16 v[60:63], v[128:131], v[168:171], v[60:63]
	v_mfma_f32_16x16x32_bf16 v[56:59], v[136:139], v[168:171], v[56:59]
	v_mfma_f32_16x16x32_bf16 v[44:47], v[128:131], v[194:197], v[44:47]
	v_mfma_f32_16x16x32_bf16 v[40:43], v[136:139], v[194:197], v[40:43]
	v_mfma_f32_16x16x32_bf16 v[28:31], v[128:131], v[202:205], v[28:31]
	v_mfma_f32_16x16x32_bf16 v[24:27], v[136:139], v[202:205], v[24:27]
	v_mfma_f32_16x16x32_bf16 v[12:15], v[128:131], v[220:223], v[12:15]
	v_mfma_f32_16x16x32_bf16 v[8:11], v[136:139], v[220:223], v[8:11]
	v_mfma_f32_16x16x32_bf16 v[60:63], v[132:135], v[172:175], v[60:63]
	v_mfma_f32_16x16x32_bf16 v[56:59], v[164:167], v[172:175], v[56:59]
	v_mfma_f32_16x16x32_bf16 v[44:47], v[132:135], v[198:201], v[44:47]
	v_mfma_f32_16x16x32_bf16 v[40:43], v[164:167], v[198:201], v[40:43]
	v_mfma_f32_16x16x32_bf16 v[28:31], v[132:135], v[206:209], v[28:31]
	v_mfma_f32_16x16x32_bf16 v[24:27], v[164:167], v[206:209], v[24:27]
	v_mfma_f32_16x16x32_bf16 v[12:15], v[132:135], v[228:231], v[12:15]
	v_mfma_f32_16x16x32_bf16 v[8:11], v[164:167], v[228:231], v[8:11]
	s_setprio 0
	s_barrier
	s_add_u32 s28, s56, 0x20080
	s_addc_u32 s29, s57, 0
	s_add_i32 s30, s31, s22
	v_lshl_add_u64 v[128:129], s[28:29], 0, v[142:143]
	s_mov_b32 m0, s30
	s_nop 0
	global_load_lds_dwordx4 v[128:129], off
	v_lshl_add_u64 v[128:129], s[28:29], 0, v[144:145]
	s_add_i32 m0, s30, 0x2000
	s_nop 0
	global_load_lds_dwordx4 v[128:129], off
	s_waitcnt vmcnt(6)
	s_barrier
	s_setprio 1
	v_mfma_f32_16x16x32_bf16 v[52:55], v[232:235], v[168:171], v[52:55]
	v_mfma_f32_16x16x32_bf16 v[48:51], v[240:243], v[168:171], v[48:51]
	v_mfma_f32_16x16x32_bf16 v[36:39], v[232:235], v[194:197], v[36:39]
	v_mfma_f32_16x16x32_bf16 v[32:35], v[240:243], v[194:197], v[32:35]
	v_mfma_f32_16x16x32_bf16 v[20:23], v[232:235], v[202:205], v[20:23]
	v_mfma_f32_16x16x32_bf16 v[16:19], v[240:243], v[202:205], v[16:19]
	v_mfma_f32_16x16x32_bf16 v[4:7], v[232:235], v[220:223], v[4:7]
	v_mfma_f32_16x16x32_bf16 v[0:3], v[240:243], v[220:223], v[0:3]
	v_mfma_f32_16x16x32_bf16 v[52:55], v[236:239], v[172:175], v[52:55]
	v_mfma_f32_16x16x32_bf16 v[48:51], v[244:247], v[172:175], v[48:51]
	v_mfma_f32_16x16x32_bf16 v[36:39], v[236:239], v[198:201], v[36:39]
	v_mfma_f32_16x16x32_bf16 v[32:35], v[244:247], v[198:201], v[32:35]
	v_mfma_f32_16x16x32_bf16 v[20:23], v[236:239], v[206:209], v[20:23]
	v_mfma_f32_16x16x32_bf16 v[16:19], v[244:247], v[206:209], v[16:19]
	v_mfma_f32_16x16x32_bf16 v[4:7], v[236:239], v[228:231], v[4:7]
	v_mfma_f32_16x16x32_bf16 v[0:3], v[244:247], v[228:231], v[0:3]
	s_setprio 0
	s_barrier
	s_add_i32 s27, s27, 2
	s_add_u32 s1, s1, 0x100
	s_addc_u32 s3, s3, 0
	s_cmp_gt_u32 s27, 5
	s_mov_b64 s[52:53], s[54:55]
	s_cbranch_scc0 .LBB0_3278
	s_lshl_b32 s3, s42, 8
	s_add_i32 s3, s3, s60
	s_cmp_eq_u32 s50, 2
	s_cselect_b64 s[28:29], -1, 0
	s_cmp_lt_i32 s42, 32
	s_cselect_b64 s[30:31], -1, 0
	s_and_b64 s[28:29], s[28:29], s[30:31]
	v_cndmask_b32_e64 v129, 0, 1, s[28:29]
	s_bfe_u32 s1, s3, 0x50006
	v_mov_b32_e32 v128, 1.0
	v_mov_b32_e32 v132, 0
	v_cmp_ne_u32_e64 s[42:43], 1, v129
	s_andn2_b64 vcc, exec, s[28:29]
	v_mov_b32_e32 v134, 0
	v_mov_b32_e32 v135, 0
	v_mov_b32_e32 v136, 0
	v_mov_b32_e32 v137, 0
	v_mov_b32_e32 v138, 1.0
	v_mov_b32_e32 v139, 1.0
	v_mov_b32_e32 v140, 1.0
	v_mov_b32_e32 v141, 1.0
	s_cbranch_vccnz .LBB0_3281
	v_mov_b32_e32 v129, s1
	v_cndmask_b32_e64 v129, v156, v129, s[38:39]
	v_lshlrev_b32_e32 v178, 6, v129
	v_lshl_add_u64 v[130:131], v[148:149], 0, v[178:179]
	v_lshl_add_u64 v[134:135], v[146:147], 0, v[178:179]
	global_load_dwordx4 v[138:141], v[130:131], off
	s_nop 0
	global_load_dwordx4 v[134:137], v[134:135], off

; #define PG8_STAGE(bufoff, gbase, voff) do { _Pragma("unroll") for (int _i = 0; _i < 2; ++_i) \
;         __builtin_amdgcn_global_load_lds((const unsigned*)((const char*)(gbase) + (voff)[_i]), (LAS unsigned*)(lds + (bufoff) + ldsw + _i * 8192), 16, 0, 0); } while (0)
; #define PG8_LDA(dst, b, h) do { _Pragma("unroll") for (int m = 0; m < 4; ++m) _Pragma("unroll") for (int k = 0; k < 2; ++k) dst[m][k] = *(const LAS bf16x8*)(lds + PG8_SA(b, h) + aoff + m * 2048 + k * 1024); } while (0)
; #define PG8_LDB(dst, b, h) do { _Pragma("unroll") for (int n = 0; n < 2; ++n) _Pragma("unroll") for (int k = 0; k < 2; ++k) dst[n][k] = *(const LAS bf16x8*)(lds + PG8_SB(b, h) + boff + n * 2048 + k * 1024); } while (0)
; #define PG8_MMA(ai, bj, At, Bt) do { __builtin_amdgcn_s_setprio(1); _Pragma("unroll") for (int m = 0; m < 4; ++m) _Pragma("unroll") for (int n = 0; n < 2; ++n) _Pragma("unroll") for (int k = 0; k < 2; ++k) \
;         acc[ai][bj][m][n] = __builtin_amdgcn_mfma_f32_16x16x32_bf16(Bt[n][k], At[m][k], acc[ai][bj][m][n], 0, 0, 0); __builtin_amdgcn_s_setprio(0); } while (0)
; #define PG8_WAIT_L(n) asm volatile("s_waitcnt lgkmcnt(" #n ")" ::: "memory")
; #define PG8_BAR __builtin_amdgcn_s_barrier()
; #define PG8_SCHED __builtin_amdgcn_sched_barrier(0)
; template <class Epi>
; __device__ __forceinline__ void gemm_phase(LAS unsigned char* lds, const Gemm g, const StaticOrder S, const Epi E) {
;     ...
;         for (int t = 0; t < nt; t += 2) {
;             const bool last = (t == nt - 2);
;             const char* a1 = cA + (size_t)(t + 1) * kstep;
;             const char* a2 = last ? nA : cA + (size_t)(t + 2) * kstep; const char* b2 = last ? nB : cB + (size_t)(t + 2) * kstep;
;             const char* a3 = a2 + kstep; const char* b3 = b2 + kstep;
;             PG8_LDB(B0, 0, 0); PG8_SCHED; PG8_LDA(At, 0, 0); PG8_STAGE(PG8_SA(1, 1), a1 + hstep, voffA);
;             PG8_WAIT_L(8); PG8_BAR; PG8_WAIT_L(0); PG8_MMA(0, 0, At, B0); PG8_BAR; PG8_SCHED;
;             PG8_LDB(B1, 0, 1); PG8_STAGE(PG8_SB(0, 0), b2, voffA);
;             PG8_BAR; PG8_WAIT_L(0); PG8_MMA(0, 1, At, B1); PG8_BAR;
;             PG8_LDA(At, 0, 1); PG8_STAGE(PG8_SA(0, 0), a2, voffA);
;             PG8_BAR; PG8_WAIT_L(0); PG8_MMA(1, 0, At, B0); PG8_BAR; PG8_SCHED;
.LBB0_3306:
	s_add_u32 s3, s50, s1
	s_addc_u32 s29, s51, 0
	s_add_u32 s44, s3, 0x100
	s_addc_u32 s45, s29, 0
	s_and_b64 s[30:31], s[54:55], exec
	s_cselect_b32 s61, s47, s45
	s_cselect_b32 s60, s46, s44
	s_add_u32 s1, s42, s1
	s_addc_u32 s30, s43, 0
	s_add_u32 s1, s1, 0x100
	s_addc_u32 s44, s30, 0
	s_add_i32 s45, 0, 0x10000
	s_and_b64 s[30:31], s[54:55], exec
	s_cselect_b32 s63, s49, s44
	s_cselect_b32 s62, s48, s1
	s_add_u32 s64, s3, 0x10080
	s_addc_u32 s65, s29, 0
	s_add_i32 s73, s45, s22
	s_add_i32 m0, s14, 0xc000
	s_add_i32 s23, s14, 0xe000
	s_add_i32 vcc_hi, 0, 0x14000
	s_add_i32 s31, s73, 0x2000
	s_add_u32 s58, s62, 0x10000
	v_add_u32_e32 v140, s45, v155
	s_addc_u32 s59, s63, 0
	s_add_i32 s44, vcc_hi, s22
	ds_read_b128 v[128:131], v140
	ds_read_b128 v[132:135], v140 offset:1024
	ds_read_b128 v[136:139], v140 offset:2048
	ds_read_b128 v[150:153], v140 offset:3072
	s_add_i32 s72, s44, 0x2000
	s_add_i32 vcc_lo, 0, 0x18000
	s_add_u32 s56, s60, 0x10000
	s_addc_u32 s57, s61, 0
	s_add_i32 s29, vcc_lo, s22
	s_add_i32 s3, 0, 0x1c000
	s_add_i32 s1, s29, 0x2000
	s_add_u32 s54, s62, 0x10080
	s_addc_u32 s55, s63, 0
	s_add_i32 s45, s3, s22
	s_add_i32 s30, s45, 0x2000
	v_lshl_add_u64 v[140:141], s[64:65], 0, v[144:145]
	ds_read_b128 v[162:165], v160
	ds_read_b128 v[166:169], v160 offset:1024
	ds_read_b128 v[170:173], v160 offset:2048
	ds_read_b128 v[194:197], v160 offset:3072
	ds_read_b128 v[198:201], v160 offset:4096
	ds_read_b128 v[202:205], v160 offset:5120
	ds_read_b128 v[206:209], v160 offset:6144
	ds_read_b128 v[220:223], v160 offset:7168
	global_load_lds_dwordx4 v[140:141], off
	v_lshl_add_u64 v[140:141], s[64:65], 0, v[142:143]
	s_mov_b32 m0, s23
	s_nop 0
	global_load_lds_dwordx4 v[140:141], off
	s_waitcnt lgkmcnt(8)
	s_barrier
	s_waitcnt lgkmcnt(0)
	s_setprio 1
	v_mfma_f32_16x16x32_bf16 v[124:127], v[128:131], v[162:165], v[124:127]
	v_mfma_f32_16x16x32_bf16 v[120:123], v[136:139], v[162:165], v[120:123]
	v_mfma_f32_16x16x32_bf16 v[108:111], v[128:131], v[170:173], v[108:111]
	v_mfma_f32_16x16x32_bf16 v[104:107], v[136:139], v[170:173], v[104:107]
	v_mfma_f32_16x16x32_bf16 v[92:95], v[128:131], v[198:201], v[92:95]
	v_mfma_f32_16x16x32_bf16 v[88:91], v[136:139], v[198:201], v[88:91]
	v_mfma_f32_16x16x32_bf16 v[76:79], v[128:131], v[206:209], v[76:79]
	v_mfma_f32_16x16x32_bf16 v[72:75], v[136:139], v[206:209], v[72:75]
	v_mfma_f32_16x16x32_bf16 v[124:127], v[132:135], v[166:169], v[124:127]
	v_mfma_f32_16x16x32_bf16 v[120:123], v[150:153], v[166:169], v[120:123]
	v_mfma_f32_16x16x32_bf16 v[108:111], v[132:135], v[194:197], v[108:111]
	v_mfma_f32_16x16x32_bf16 v[104:107], v[150:153], v[194:197], v[104:107]
	v_mfma_f32_16x16x32_bf16 v[92:95], v[132:135], v[202:205], v[92:95]
	v_mfma_f32_16x16x32_bf16 v[88:91], v[150:153], v[202:205], v[88:91]
	v_mfma_f32_16x16x32_bf16 v[76:79], v[132:135], v[220:223], v[76:79]
	v_mfma_f32_16x16x32_bf16 v[72:75], v[150:153], v[220:223], v[72:75]
	s_setprio 0
	s_barrier
	v_add_u32_e32 v140, vcc_hi, v155
	s_mov_b32 m0, s73
	ds_read_b128 v[228:231], v140
	ds_read_b128 v[232:235], v140 offset:1024
	ds_read_b128 v[236:239], v140 offset:2048
	ds_read_b128 v[240:243], v140 offset:3072
	v_lshl_add_u64 v[140:141], s[62:63], 0, v[144:145]
	global_load_lds_dwordx4 v[140:141], off
	v_lshl_add_u64 v[174:175], s[62:63], 0, v[142:143]
	s_mov_b32 m0, s31
	s_nop 0
	global_load_lds_dwordx4 v[174:175], off
	s_barrier
	s_waitcnt lgkmcnt(0)
	s_setprio 1
	v_mfma_f32_16x16x32_bf16 v[116:119], v[228:231], v[162:165], v[116:119]
	v_mfma_f32_16x16x32_bf16 v[112:115], v[236:239], v[162:165], v[112:115]
	v_mfma_f32_16x16x32_bf16 v[100:103], v[228:231], v[170:173], v[100:103]
	v_mfma_f32_16x16x32_bf16 v[96:99], v[236:239], v[170:173], v[96:99]
	v_mfma_f32_16x16x32_bf16 v[84:87], v[228:231], v[198:201], v[84:87]
	v_mfma_f32_16x16x32_bf16 v[80:83], v[236:239], v[198:201], v[80:83]
	v_mfma_f32_16x16x32_bf16 v[68:71], v[228:231], v[206:209], v[68:71]
	v_mfma_f32_16x16x32_bf16 v[64:67], v[236:239], v[206:209], v[64:67]
	v_mfma_f32_16x16x32_bf16 v[116:119], v[232:235], v[166:169], v[116:119]
	v_mfma_f32_16x16x32_bf16 v[112:115], v[240:243], v[166:169], v[112:115]
	v_mfma_f32_16x16x32_bf16 v[100:103], v[232:235], v[194:197], v[100:103]
	v_mfma_f32_16x16x32_bf16 v[96:99], v[240:243], v[194:197], v[96:99]
	v_mfma_f32_16x16x32_bf16 v[84:87], v[232:235], v[202:205], v[84:87]
	v_mfma_f32_16x16x32_bf16 v[80:83], v[240:243], v[202:205], v[80:83]
	v_mfma_f32_16x16x32_bf16 v[68:71], v[232:235], v[220:223], v[68:71]
	v_mfma_f32_16x16x32_bf16 v[64:67], v[240:243], v[220:223], v[64:67]
	s_setprio 0
	s_barrier
	s_mov_b32 m0, s14
	v_lshl_add_u64 v[210:211], s[60:61], 0, v[144:145]
	ds_read_b128 v[162:165], v160 offset:16384
	ds_read_b128 v[166:169], v160 offset:17408
	ds_read_b128 v[170:173], v160 offset:18432
	ds_read_b128 v[194:197], v160 offset:19456
	ds_read_b128 v[198:201], v160 offset:20480
	ds_read_b128 v[202:205], v160 offset:21504
	ds_read_b128 v[206:209], v160 offset:22528
	ds_read_b128 v[220:223], v160 offset:23552
	global_load_lds_dwordx4 v[210:211], off
	v_lshl_add_u64 v[244:245], s[60:61], 0, v[142:143]
	s_mov_b32 m0, s24
	s_nop 0
	global_load_lds_dwordx4 v[244:245], off
	s_barrier
; #define PG8_STAGE(bufoff, gbase, voff) do { _Pragma("unroll") for (int _i = 0; _i < 2; ++_i) \
;         __builtin_amdgcn_global_load_lds((const unsigned*)((const char*)(gbase) + (voff)[_i]), (LAS unsigned*)(lds + (bufoff) + ldsw + _i * 8192), 16, 0, 0); } while (0)
; #define PG8_LDA(dst, b, h) do { _Pragma("unroll") for (int m = 0; m < 4; ++m) _Pragma("unroll") for (int k = 0; k < 2; ++k) dst[m][k] = *(const LAS bf16x8*)(lds + PG8_SA(b, h) + aoff + m * 2048 + k * 1024); } while (0)
; #define PG8_LDB(dst, b, h) do { _Pragma("unroll") for (int n = 0; n < 2; ++n) _Pragma("unroll") for (int k = 0; k < 2; ++k) dst[n][k] = *(const LAS bf16x8*)(lds + PG8_SB(b, h) + boff + n * 2048 + k * 1024); } while (0)
; #define PG8_MMA(ai, bj, At, Bt) do { __builtin_amdgcn_s_setprio(1); _Pragma("unroll") for (int m = 0; m < 4; ++m) _Pragma("unroll") for (int n = 0; n < 2; ++n) _Pragma("unroll") for (int k = 0; k < 2; ++k) \
;         acc[ai][bj][m][n] = __builtin_amdgcn_mfma_f32_16x16x32_bf16(Bt[n][k], At[m][k], acc[ai][bj][m][n], 0, 0, 0); __builtin_amdgcn_s_setprio(0); } while (0)
; #define PG8_WAIT_V(n) asm volatile("s_waitcnt vmcnt(" #n ")" ::: "memory")
; #define PG8_WAIT_L(n) asm volatile("s_waitcnt lgkmcnt(" #n ")" ::: "memory")
; #define PG8_BAR __builtin_amdgcn_s_barrier()
; #define PG8_SCHED __builtin_amdgcn_sched_barrier(0)
; template <class Epi>
; __device__ __forceinline__ void gemm_phase(LAS unsigned char* lds, const Gemm g, const StaticOrder S, const Epi E) {
;     ...
;             PG8_BAR; PG8_WAIT_L(0); PG8_MMA(1, 0, At, B0); PG8_BAR; PG8_SCHED;
;             PG8_STAGE(PG8_SB(0, 1), b2 + hstep, voffA);
;             PG8_WAIT_V(6); PG8_BAR; PG8_MMA(1, 1, At, B1); PG8_BAR;
;             PG8_LDB(B0, 1, 0); PG8_SCHED; PG8_LDA(At, 1, 0); PG8_STAGE(PG8_SA(0, 1), a2 + hstep, voffA);
;             PG8_WAIT_L(8); PG8_BAR; PG8_WAIT_L(0); PG8_MMA(0, 0, At, B0); PG8_BAR; PG8_SCHED;
;             PG8_LDB(B1, 1, 1); PG8_STAGE(PG8_SB(1, 0), b3, voffA);
;             PG8_BAR; PG8_WAIT_L(0); PG8_MMA(0, 1, At, B1); PG8_BAR;
;             PG8_LDA(At, 1, 1); PG8_STAGE(PG8_SA(1, 0), a3, voffA);
	s_waitcnt lgkmcnt(0)
	s_setprio 1
	v_mfma_f32_16x16x32_bf16 v[60:63], v[128:131], v[162:165], v[60:63]
	v_mfma_f32_16x16x32_bf16 v[56:59], v[136:139], v[162:165], v[56:59]
	v_mfma_f32_16x16x32_bf16 v[44:47], v[128:131], v[170:173], v[44:47]
	v_mfma_f32_16x16x32_bf16 v[40:43], v[136:139], v[170:173], v[40:43]
	v_mfma_f32_16x16x32_bf16 v[28:31], v[128:131], v[198:201], v[28:31]
	v_mfma_f32_16x16x32_bf16 v[24:27], v[136:139], v[198:201], v[24:27]
	v_mfma_f32_16x16x32_bf16 v[12:15], v[128:131], v[206:209], v[12:15]
	v_mfma_f32_16x16x32_bf16 v[8:11], v[136:139], v[206:209], v[8:11]
	v_mfma_f32_16x16x32_bf16 v[60:63], v[132:135], v[166:169], v[60:63]
	v_mfma_f32_16x16x32_bf16 v[56:59], v[150:153], v[166:169], v[56:59]
	v_mfma_f32_16x16x32_bf16 v[44:47], v[132:135], v[194:197], v[44:47]
	v_mfma_f32_16x16x32_bf16 v[40:43], v[150:153], v[194:197], v[40:43]
	v_mfma_f32_16x16x32_bf16 v[28:31], v[132:135], v[202:205], v[28:31]
	v_mfma_f32_16x16x32_bf16 v[24:27], v[150:153], v[202:205], v[24:27]
	v_mfma_f32_16x16x32_bf16 v[12:15], v[132:135], v[220:223], v[12:15]
	v_mfma_f32_16x16x32_bf16 v[8:11], v[150:153], v[220:223], v[8:11]
	s_setprio 0
	s_barrier
	s_mov_b32 m0, s44
	v_lshl_add_u64 v[128:129], s[58:59], 0, v[144:145]
	global_load_lds_dwordx4 v[128:129], off
	v_lshl_add_u64 v[128:129], s[58:59], 0, v[142:143]
	s_mov_b32 m0, s72
	s_nop 0
	global_load_lds_dwordx4 v[128:129], off
	s_waitcnt vmcnt(6)
	s_barrier
	s_setprio 1
	v_mfma_f32_16x16x32_bf16 v[52:55], v[228:231], v[162:165], v[52:55]
	v_mfma_f32_16x16x32_bf16 v[48:51], v[236:239], v[162:165], v[48:51]
	v_mfma_f32_16x16x32_bf16 v[36:39], v[228:231], v[170:173], v[36:39]
	v_mfma_f32_16x16x32_bf16 v[32:35], v[236:239], v[170:173], v[32:35]
	v_mfma_f32_16x16x32_bf16 v[20:23], v[228:231], v[198:201], v[20:23]
	v_mfma_f32_16x16x32_bf16 v[16:19], v[236:239], v[198:201], v[16:19]
	v_mfma_f32_16x16x32_bf16 v[4:7], v[228:231], v[206:209], v[4:7]
	v_mfma_f32_16x16x32_bf16 v[0:3], v[236:239], v[206:209], v[0:3]
	v_mfma_f32_16x16x32_bf16 v[52:55], v[232:235], v[166:169], v[52:55]
	v_mfma_f32_16x16x32_bf16 v[48:51], v[240:243], v[166:169], v[48:51]
	v_mfma_f32_16x16x32_bf16 v[36:39], v[232:235], v[194:197], v[36:39]
	v_mfma_f32_16x16x32_bf16 v[32:35], v[240:243], v[194:197], v[32:35]
	v_mfma_f32_16x16x32_bf16 v[20:23], v[232:235], v[202:205], v[20:23]
	v_mfma_f32_16x16x32_bf16 v[16:19], v[240:243], v[202:205], v[16:19]
	v_mfma_f32_16x16x32_bf16 v[4:7], v[232:235], v[220:223], v[4:7]
	v_mfma_f32_16x16x32_bf16 v[0:3], v[240:243], v[220:223], v[0:3]
	s_setprio 0
	s_barrier
	v_add_u32_e32 v150, vcc_lo, v155
	ds_read_b128 v[128:131], v150
	ds_read_b128 v[132:135], v150 offset:1024
	ds_read_b128 v[136:139], v150 offset:2048
	ds_read_b128 v[150:153], v150 offset:3072
	s_mov_b32 m0, s25
	v_lshl_add_u64 v[228:229], s[56:57], 0, v[144:145]
	ds_read_b128 v[162:165], v160 offset:32768
	ds_read_b128 v[166:169], v160 offset:33792
	ds_read_b128 v[170:173], v160 offset:34816
	ds_read_b128 v[194:197], v160 offset:35840
	ds_read_b128 v[198:201], v160 offset:36864
	ds_read_b128 v[202:205], v160 offset:37888
	ds_read_b128 v[206:209], v160 offset:38912
	ds_read_b128 v[220:223], v160 offset:39936
	global_load_lds_dwordx4 v[228:229], off
	v_lshl_add_u64 v[228:229], s[56:57], 0, v[142:143]
	s_mov_b32 m0, s66
	s_nop 0
	global_load_lds_dwordx4 v[228:229], off
	s_waitcnt lgkmcnt(8)
	s_barrier
	s_waitcnt lgkmcnt(0)
	s_setprio 1
	v_mfma_f32_16x16x32_bf16 v[124:127], v[128:131], v[162:165], v[124:127]
	v_mfma_f32_16x16x32_bf16 v[120:123], v[136:139], v[162:165], v[120:123]
	v_mfma_f32_16x16x32_bf16 v[108:111], v[128:131], v[170:173], v[108:111]
	v_mfma_f32_16x16x32_bf16 v[104:107], v[136:139], v[170:173], v[104:107]
	v_mfma_f32_16x16x32_bf16 v[92:95], v[128:131], v[198:201], v[92:95]
	v_mfma_f32_16x16x32_bf16 v[88:91], v[136:139], v[198:201], v[88:91]
	v_mfma_f32_16x16x32_bf16 v[76:79], v[128:131], v[206:209], v[76:79]
	v_mfma_f32_16x16x32_bf16 v[72:75], v[136:139], v[206:209], v[72:75]
	v_mfma_f32_16x16x32_bf16 v[124:127], v[132:135], v[166:169], v[124:127]
	v_mfma_f32_16x16x32_bf16 v[120:123], v[150:153], v[166:169], v[120:123]
	v_mfma_f32_16x16x32_bf16 v[108:111], v[132:135], v[194:197], v[108:111]
	v_mfma_f32_16x16x32_bf16 v[104:107], v[150:153], v[194:197], v[104:107]
	v_mfma_f32_16x16x32_bf16 v[92:95], v[132:135], v[202:205], v[92:95]
	v_mfma_f32_16x16x32_bf16 v[88:91], v[150:153], v[202:205], v[88:91]
	v_mfma_f32_16x16x32_bf16 v[76:79], v[132:135], v[220:223], v[76:79]
	v_mfma_f32_16x16x32_bf16 v[72:75], v[150:153], v[220:223], v[72:75]
	s_setprio 0
	s_barrier
	s_mov_b32 m0, s29
	v_add_u32_e32 v161, s3, v155
	v_lshl_add_u64 v[140:141], v[140:141], 0, s[34:35]
	ds_read_b128 v[228:231], v161
	ds_read_b128 v[232:235], v161 offset:1024
	ds_read_b128 v[236:239], v161 offset:2048
	ds_read_b128 v[240:243], v161 offset:3072
	global_load_lds_dwordx4 v[140:141], off
	v_lshl_add_u64 v[140:141], v[174:175], 0, s[34:35]
	s_mov_b32 m0, s1
	s_nop 0
	global_load_lds_dwordx4 v[140:141], off
	s_barrier
; #define PG8_STAGE(bufoff, gbase, voff) do { _Pragma("unroll") for (int _i = 0; _i < 2; ++_i) \
;         __builtin_amdgcn_global_load_lds((const unsigned*)((const char*)(gbase) + (voff)[_i]), (LAS unsigned*)(lds + (bufoff) + ldsw + _i * 8192), 16, 0, 0); } while (0)
; #define PG8_LDA(dst, b, h) do { _Pragma("unroll") for (int m = 0; m < 4; ++m) _Pragma("unroll") for (int k = 0; k < 2; ++k) dst[m][k] = *(const LAS bf16x8*)(lds + PG8_SA(b, h) + aoff + m * 2048 + k * 1024); } while (0)
; #define PG8_MMA(ai, bj, At, Bt) do { __builtin_amdgcn_s_setprio(1); _Pragma("unroll") for (int m = 0; m < 4; ++m) _Pragma("unroll") for (int n = 0; n < 2; ++n) _Pragma("unroll") for (int k = 0; k < 2; ++k) \
;         acc[ai][bj][m][n] = __builtin_amdgcn_mfma_f32_16x16x32_bf16(Bt[n][k], At[m][k], acc[ai][bj][m][n], 0, 0, 0); __builtin_amdgcn_s_setprio(0); } while (0)
; #define PG8_WAIT_V(n) asm volatile("s_waitcnt vmcnt(" #n ")" ::: "memory")
; #define PG8_WAIT_L(n) asm volatile("s_waitcnt lgkmcnt(" #n ")" ::: "memory")
; #define PG8_BAR __builtin_amdgcn_s_barrier()
; #define PG8_SCHED __builtin_amdgcn_sched_barrier(0)
; template <class Epi>
; __device__ __forceinline__ void gemm_phase(LAS unsigned char* lds, const Gemm g, const StaticOrder S, const Epi E) {
;     ...
;             PG8_LDA(At, 1, 1); PG8_STAGE(PG8_SA(1, 0), a3, voffA);
;             PG8_BAR; PG8_WAIT_L(0); PG8_MMA(1, 0, At, B0); PG8_BAR; PG8_SCHED;
;             PG8_STAGE(PG8_SB(1, 1), b3 + hstep, voffA);
;             PG8_WAIT_V(6); PG8_BAR; PG8_MMA(1, 1, At, B1); PG8_BAR;
;         }
;     __device__ __forceinline__ void operator()(AccRef acc, const pg8::Unit& u, int wr, int wc, int fr, int fq) const {
;         const int row0 = u.pm * 256 + wr * 64 + fr, col0 = u.pn * 256 + wc * 32 + 4 * fq;
;         const bool rope = (u.pn == rope_pn) && (u.pm < 32);
; #pragma unroll
;         for (int ai = 0; ai < 2; ++ai)
; #pragma unroll
;             for (int m = 0; m < 4; ++m) { const int row = row0 + ai * 128 + m * 16; bf16_t* rowp = O + (size_t)row * ldc + col0;
;                 f32x4 cs = {1.f, 1.f, 1.f, 1.f}, sn = {0.f, 0.f, 0.f, 0.f};
;                 if (rope) { const int t = row & 2047; const int pos = (wc & 1) ? (t & 63) : (t >> 6); cs = *(const f32x4*)(cos64 + pos * 16 + 4 * fq); sn = *(const f32x4*)(sin64 + pos * 16 + 4 * fq); }
	s_waitcnt lgkmcnt(0)
	s_setprio 1
	v_mfma_f32_16x16x32_bf16 v[116:119], v[228:231], v[162:165], v[116:119]
	v_mfma_f32_16x16x32_bf16 v[112:115], v[236:239], v[162:165], v[112:115]
	v_mfma_f32_16x16x32_bf16 v[100:103], v[228:231], v[170:173], v[100:103]
	v_mfma_f32_16x16x32_bf16 v[96:99], v[236:239], v[170:173], v[96:99]
	v_mfma_f32_16x16x32_bf16 v[84:87], v[228:231], v[198:201], v[84:87]
	v_mfma_f32_16x16x32_bf16 v[80:83], v[236:239], v[198:201], v[80:83]
	v_mfma_f32_16x16x32_bf16 v[68:71], v[228:231], v[206:209], v[68:71]
	v_mfma_f32_16x16x32_bf16 v[64:67], v[236:239], v[206:209], v[64:67]
	v_mfma_f32_16x16x32_bf16 v[116:119], v[232:235], v[166:169], v[116:119]
	v_mfma_f32_16x16x32_bf16 v[112:115], v[240:243], v[166:169], v[112:115]
	v_mfma_f32_16x16x32_bf16 v[100:103], v[232:235], v[194:197], v[100:103]
	v_mfma_f32_16x16x32_bf16 v[96:99], v[240:243], v[194:197], v[96:99]
	v_mfma_f32_16x16x32_bf16 v[84:87], v[232:235], v[202:205], v[84:87]
	v_mfma_f32_16x16x32_bf16 v[80:83], v[240:243], v[202:205], v[80:83]
	v_mfma_f32_16x16x32_bf16 v[68:71], v[232:235], v[220:223], v[68:71]
	v_mfma_f32_16x16x32_bf16 v[64:67], v[240:243], v[220:223], v[64:67]
	s_setprio 0
	s_barrier
	s_mov_b32 m0, s68
	v_lshl_add_u64 v[140:141], v[210:211], 0, s[34:35]
	ds_read_b128 v[162:165], v160 offset:49152
	ds_read_b128 v[166:169], v160 offset:50176
	ds_read_b128 v[170:173], v160 offset:51200
	ds_read_b128 v[194:197], v160 offset:52224
	ds_read_b128 v[198:201], v160 offset:53248
	ds_read_b128 v[202:205], v160 offset:54272
	ds_read_b128 v[206:209], v160 offset:55296
	ds_read_b128 v[220:223], v160 offset:56320
	global_load_lds_dwordx4 v[140:141], off
	v_lshl_add_u64 v[140:141], v[244:245], 0, s[34:35]
	s_mov_b32 m0, s69
	s_nop 0
	global_load_lds_dwordx4 v[140:141], off
	s_barrier
	s_waitcnt lgkmcnt(0)
	s_setprio 1
	v_mfma_f32_16x16x32_bf16 v[60:63], v[128:131], v[162:165], v[60:63]
	v_mfma_f32_16x16x32_bf16 v[56:59], v[136:139], v[162:165], v[56:59]
	v_mfma_f32_16x16x32_bf16 v[44:47], v[128:131], v[170:173], v[44:47]
	v_mfma_f32_16x16x32_bf16 v[40:43], v[136:139], v[170:173], v[40:43]
	v_mfma_f32_16x16x32_bf16 v[28:31], v[128:131], v[198:201], v[28:31]
	v_mfma_f32_16x16x32_bf16 v[24:27], v[136:139], v[198:201], v[24:27]
	v_mfma_f32_16x16x32_bf16 v[12:15], v[128:131], v[206:209], v[12:15]
	v_mfma_f32_16x16x32_bf16 v[8:11], v[136:139], v[206:209], v[8:11]
	v_mfma_f32_16x16x32_bf16 v[60:63], v[132:135], v[166:169], v[60:63]
	v_mfma_f32_16x16x32_bf16 v[56:59], v[150:153], v[166:169], v[56:59]
	v_mfma_f32_16x16x32_bf16 v[44:47], v[132:135], v[194:197], v[44:47]
	v_mfma_f32_16x16x32_bf16 v[40:43], v[150:153], v[194:197], v[40:43]
	v_mfma_f32_16x16x32_bf16 v[28:31], v[132:135], v[202:205], v[28:31]
	v_mfma_f32_16x16x32_bf16 v[24:27], v[150:153], v[202:205], v[24:27]
	v_mfma_f32_16x16x32_bf16 v[12:15], v[132:135], v[220:223], v[12:15]
	v_mfma_f32_16x16x32_bf16 v[8:11], v[150:153], v[220:223], v[8:11]
	s_setprio 0
	s_barrier
	s_mov_b32 m0, s45
	v_lshl_add_u64 v[128:129], s[54:55], 0, v[144:145]
	global_load_lds_dwordx4 v[128:129], off
	v_lshl_add_u64 v[128:129], s[54:55], 0, v[142:143]
	s_mov_b32 m0, s30
	s_nop 0
	global_load_lds_dwordx4 v[128:129], off
	s_waitcnt vmcnt(6)
	s_barrier
	s_setprio 1
	v_mfma_f32_16x16x32_bf16 v[52:55], v[228:231], v[162:165], v[52:55]
	v_mfma_f32_16x16x32_bf16 v[48:51], v[236:239], v[162:165], v[48:51]
	v_mfma_f32_16x16x32_bf16 v[36:39], v[228:231], v[170:173], v[36:39]
	v_mfma_f32_16x16x32_bf16 v[32:35], v[236:239], v[170:173], v[32:35]
	v_mfma_f32_16x16x32_bf16 v[20:23], v[228:231], v[198:201], v[20:23]
	v_mfma_f32_16x16x32_bf16 v[16:19], v[236:239], v[198:201], v[16:19]
	v_mfma_f32_16x16x32_bf16 v[4:7], v[228:231], v[206:209], v[4:7]
	v_mfma_f32_16x16x32_bf16 v[0:3], v[236:239], v[206:209], v[0:3]
	v_mfma_f32_16x16x32_bf16 v[52:55], v[232:235], v[166:169], v[52:55]
	v_mfma_f32_16x16x32_bf16 v[48:51], v[240:243], v[166:169], v[48:51]
	v_mfma_f32_16x16x32_bf16 v[36:39], v[232:235], v[194:197], v[36:39]
	v_mfma_f32_16x16x32_bf16 v[32:35], v[240:243], v[194:197], v[32:35]
	v_mfma_f32_16x16x32_bf16 v[20:23], v[232:235], v[202:205], v[20:23]
	v_mfma_f32_16x16x32_bf16 v[16:19], v[240:243], v[202:205], v[16:19]
	v_mfma_f32_16x16x32_bf16 v[4:7], v[232:235], v[220:223], v[4:7]
	v_mfma_f32_16x16x32_bf16 v[0:3], v[240:243], v[220:223], v[0:3]
	s_setprio 0
	s_barrier
	s_movk_i32 s1, 0x100
	s_andn2_b64 vcc, exec, s[52:53]
	s_mov_b64 s[54:55], -1
	s_mov_b64 s[52:53], 0
	s_cbranch_vccz .LBB0_3306
	s_lshl_b32 s3, s28, 8
	s_add_i32 s3, s3, s67
	s_cmp_eq_u32 s27, -1
	s_cselect_b64 s[30:31], -1, 0
	s_cmp_lt_i32 s28, 32
	s_cselect_b64 s[28:29], -1, 0
	s_and_b64 s[28:29], s[30:31], s[28:29]
	v_cndmask_b32_e64 v129, 0, 1, s[28:29]
	s_bfe_u32 s1, s3, 0x50006
	v_mov_b32_e32 v128, 1.0
	v_mov_b32_e32 v132, 0
	v_cmp_ne_u32_e64 s[42:43], 1, v129
	s_andn2_b64 vcc, exec, s[28:29]
	v_mov_b32_e32 v134, 0
	v_mov_b32_e32 v135, 0
	v_mov_b32_e32 v136, 0
	v_mov_b32_e32 v137, 0
	v_mov_b32_e32 v138, 1.0
	v_mov_b32_e32 v139, 1.0
	v_mov_b32_e32 v140, 1.0
	v_mov_b32_e32 v141, 1.0
	s_cbranch_vccnz .LBB0_3309
	v_mov_b32_e32 v129, s1
	v_cndmask_b32_e64 v129, v154, v129, s[38:39]
	v_lshlrev_b32_e32 v178, 6, v129
	v_lshl_add_u64 v[130:131], v[148:149], 0, v[178:179]
	v_lshl_add_u64 v[134:135], v[146:147], 0, v[178:179]
	global_load_dwordx4 v[138:141], v[130:131], off
	s_nop 0
	global_load_dwordx4 v[134:137], v[134:135], off

; __device__ __forceinline__ void partialSM(f32x16& p0, f32x16& p1, float& m_reg, float& mn, float& alpha, const float C, const float thr_raw) {
;     ...
;     const float mnC = -mn * C;
; #pragma unroll
;     for (int r = 0; r < 16; ++r) p0[r] = fmaf(p0[r], C, mnC);
; #pragma unroll
;     for (int r = 0; r < 16; ++r) p1[r] = fmaf(p1[r], C, mnC);
.LBB0_3448:
	v_cndmask_b32_e64 v172, v128, v142, s[42:43]
	v_mul_f32_e32 v142, 0xbe0293ee, v172
	v_mov_b32_e32 v143, v142
	v_fmamk_f32 v80, v80, 0x3e0293ee, v142
	v_fmamk_f32 v81, v81, 0x3e0293ee, v142
	v_fmamk_f32 v82, v82, 0x3e0293ee, v142
	v_fmamk_f32 v83, v83, 0x3e0293ee, v142
	v_fmamk_f32 v84, v84, 0x3e0293ee, v142
	v_fmamk_f32 v85, v85, 0x3e0293ee, v142
	v_fmamk_f32 v86, v86, 0x3e0293ee, v142
	v_fmamk_f32 v87, v87, 0x3e0293ee, v142
	v_fmamk_f32 v88, v88, 0x3e0293ee, v142
	v_fmamk_f32 v89, v89, 0x3e0293ee, v142
	v_fmamk_f32 v90, v90, 0x3e0293ee, v142
	v_fmamk_f32 v91, v91, 0x3e0293ee, v142
	v_fmamk_f32 v92, v92, 0x3e0293ee, v142
	v_fmamk_f32 v93, v93, 0x3e0293ee, v142
	v_fmamk_f32 v94, v94, 0x3e0293ee, v142
	v_fmac_f32_e32 v143, 0x3e0293ee, v95
	v_exp_f32_e32 v206, v80
	v_exp_f32_e32 v209, v81
	v_exp_f32_e32 v207, v82
	v_exp_f32_e32 v210, v83
	v_exp_f32_e32 v208, v84
	v_exp_f32_e32 v211, v85
	v_exp_f32_e32 v204, v86
	v_exp_f32_e32 v205, v87
	v_exp_f32_e32 v200, v88
	v_exp_f32_e32 v202, v89
	v_exp_f32_e32 v201, v90
	v_exp_f32_e32 v203, v91
	v_exp_f32_e32 v196, v92
	v_exp_f32_e32 v198, v93
	v_exp_f32_e32 v197, v94
	v_exp_f32_e32 v199, v143
	v_fma_f32 v153, v65, s8, v142
	v_fma_f32 v152, v64, s8, v142
	s_and_b64 s[28:29], exec, s[40:41]
	v_add_f32_e32 v64, v174, v175
	s_or_b64 s[46:47], s[28:29], s[46:47]
	v_fmac_f32_e32 v64, v173, v133
	v_add_f32_e32 v133, v227, v228
	v_fma_f32 v151, v67, s8, v142
	v_fma_f32 v150, v66, s8, v142
	v_fma_f32 v149, v69, s8, v142
	v_fma_f32 v148, v68, s8, v142
	v_fma_f32 v147, v71, s8, v142
	v_fma_f32 v146, v70, s8, v142
	v_fma_f32 v145, v73, s8, v142
	v_fma_f32 v144, v72, s8, v142
	v_fma_f32 v131, v75, s8, v142
	v_fma_f32 v130, v74, s8, v142
	v_fma_f32 v129, v77, s8, v142
	v_fma_f32 v128, v76, s8, v142
	v_fma_f32 v143, v79, s8, v142
	v_fma_f32 v142, v78, s8, v142
	v_fmac_f32_e32 v133, v64, v195
	s_addk_i32 s23, 0x80
	s_add_i32 s22, s22, 2
	v_mov_b32_e32 v174, s27
	v_mov_b32_e32 v64, s26
	s_mov_b32 s25, s7
	s_mov_b32 s7, s44
	s_mov_b32 s44, s24
	v_mov_b32_e32 v173, v194
	s_andn2_b64 exec, exec, s[46:47]
	s_cbranch_execz .LBB0_3460

; #define PG8_STAGE(bufoff, gbase, voff) do { _Pragma("unroll") for (int _i = 0; _i < 2; ++_i) \
;         __builtin_amdgcn_global_load_lds((const unsigned*)((const char*)(gbase) + (voff)[_i]), (LAS unsigned*)(lds + (bufoff) + ldsw + _i * 8192), 16, 0, 0); } while (0)
; #define PG8_LDA(dst, b, h) do { _Pragma("unroll") for (int m = 0; m < 4; ++m) _Pragma("unroll") for (int k = 0; k < 2; ++k) dst[m][k] = *(const LAS bf16x8*)(lds + PG8_SA(b, h) + aoff + m * 2048 + k * 1024); } while (0)
; #define PG8_LDB(dst, b, h) do { _Pragma("unroll") for (int n = 0; n < 2; ++n) _Pragma("unroll") for (int k = 0; k < 2; ++k) dst[n][k] = *(const LAS bf16x8*)(lds + PG8_SB(b, h) + boff + n * 2048 + k * 1024); } while (0)
; #define PG8_MMA(ai, bj, At, Bt) do { __builtin_amdgcn_s_setprio(1); _Pragma("unroll") for (int m = 0; m < 4; ++m) _Pragma("unroll") for (int n = 0; n < 2; ++n) _Pragma("unroll") for (int k = 0; k < 2; ++k) \
;         acc[ai][bj][m][n] = __builtin_amdgcn_mfma_f32_16x16x32_bf16(Bt[n][k], At[m][k], acc[ai][bj][m][n], 0, 0, 0); __builtin_amdgcn_s_setprio(0); } while (0)
; #define PG8_WAIT_L(n) asm volatile("s_waitcnt lgkmcnt(" #n ")" ::: "memory")
; #define PG8_BAR __builtin_amdgcn_s_barrier()
; #define PG8_SCHED __builtin_amdgcn_sched_barrier(0)
; template <class Epi>
; __device__ __forceinline__ void gemm_phase(LAS unsigned char* lds, const Gemm g, const StaticOrder S, const Epi E) {
;     ...
;         for (int t = 0; t < nt; t += 2) {
;             const bool last = (t == nt - 2);
;             const char* a1 = cA + (size_t)(t + 1) * kstep;
;             const char* a2 = last ? nA : cA + (size_t)(t + 2) * kstep; const char* b2 = last ? nB : cB + (size_t)(t + 2) * kstep;
;             const char* a3 = a2 + kstep; const char* b3 = b2 + kstep;
;             PG8_LDB(B0, 0, 0); PG8_SCHED; PG8_LDA(At, 0, 0); PG8_STAGE(PG8_SA(1, 1), a1 + hstep, voffA);
;             PG8_WAIT_L(8); PG8_BAR; PG8_WAIT_L(0); PG8_MMA(0, 0, At, B0); PG8_BAR; PG8_SCHED;
;             PG8_LDB(B1, 0, 1); PG8_STAGE(PG8_SB(0, 0), b2, voffA);
;             PG8_BAR; PG8_WAIT_L(0); PG8_MMA(0, 1, At, B1); PG8_BAR;
;             PG8_LDA(At, 0, 1); PG8_STAGE(PG8_SA(0, 0), a2, voffA);
;             PG8_BAR; PG8_WAIT_L(0); PG8_MMA(1, 0, At, B0); PG8_BAR; PG8_SCHED;
.LBB0_3568:
	s_add_i32 vcc_lo, s55, 2
	s_add_u32 s58, s56, 0x100
	s_addc_u32 s59, s57, 0
	s_add_i32 s14, 0, 0x10000
	v_add_u32_e32 v132, s14, v228
	ds_read_b128 v[116:119], v132
	ds_read_b128 v[124:127], v132 offset:1024
	ds_read_b128 v[128:131], v132 offset:2048
	ds_read_b128 v[132:135], v132 offset:3072
	s_cmp_eq_u32 s43, s55
	s_cselect_b32 s63, s51, s59
	s_cselect_b32 s62, s50, s58
	s_cselect_b32 s61, s53, s47
	s_cselect_b32 s60, s52, s45
	v_lshl_add_u64 v[200:201], s[56:57], 0, v[196:197]
	s_add_i32 m0, s25, 0xc000
	ds_read_b128 v[144:147], v230
	ds_read_b128 v[148:151], v230 offset:1024
	ds_read_b128 v[152:155], v230 offset:2048
	ds_read_b128 v[156:159], v230 offset:3072
	ds_read_b128 v[160:163], v230 offset:4096
	ds_read_b128 v[164:167], v230 offset:5120
	ds_read_b128 v[168:171], v230 offset:6144
	ds_read_b128 v[172:175], v230 offset:7168
	global_load_lds_dwordx4 v[200:201], off
	v_lshl_add_u64 v[200:201], s[56:57], 0, v[198:199]
	s_add_i32 m0, s25, 0xe000
	s_nop 0
	global_load_lds_dwordx4 v[200:201], off
	s_waitcnt lgkmcnt(8)
	s_barrier
	s_waitcnt lgkmcnt(0)
	s_setprio 1
	v_mfma_f32_16x16x32_bf16 v[140:143], v[116:119], v[144:147], v[140:143]
	v_mfma_f32_16x16x32_bf16 v[136:139], v[128:131], v[144:147], v[136:139]
	v_mfma_f32_16x16x32_bf16 v[112:115], v[116:119], v[152:155], v[112:115]
	v_mfma_f32_16x16x32_bf16 v[104:107], v[128:131], v[152:155], v[104:107]
	v_mfma_f32_16x16x32_bf16 v[92:95], v[116:119], v[160:163], v[92:95]
	v_mfma_f32_16x16x32_bf16 v[88:91], v[128:131], v[160:163], v[88:91]
	v_mfma_f32_16x16x32_bf16 v[80:83], v[116:119], v[168:171], v[80:83]
	v_mfma_f32_16x16x32_bf16 v[72:75], v[128:131], v[168:171], v[72:75]
	v_mfma_f32_16x16x32_bf16 v[140:143], v[124:127], v[148:151], v[140:143]
	v_mfma_f32_16x16x32_bf16 v[136:139], v[132:135], v[148:151], v[136:139]
	v_mfma_f32_16x16x32_bf16 v[112:115], v[124:127], v[156:159], v[112:115]
	v_mfma_f32_16x16x32_bf16 v[104:107], v[132:135], v[156:159], v[104:107]
	v_mfma_f32_16x16x32_bf16 v[92:95], v[124:127], v[164:167], v[92:95]
	v_mfma_f32_16x16x32_bf16 v[88:91], v[132:135], v[164:167], v[88:91]
	v_mfma_f32_16x16x32_bf16 v[80:83], v[124:127], v[172:175], v[80:83]
	v_mfma_f32_16x16x32_bf16 v[72:75], v[132:135], v[172:175], v[72:75]
	s_setprio 0
	s_barrier
	s_add_i32 s55, 0, 0x14000
	s_add_i32 s14, s14, s24
	v_add_u32_e32 v220, s55, v228
	v_lshl_add_u64 v[232:233], s[60:61], 0, v[178:179]
	s_mov_b32 m0, s14
	ds_read_b128 v[200:203], v220
	ds_read_b128 v[204:207], v220 offset:1024
	ds_read_b128 v[208:211], v220 offset:2048
	ds_read_b128 v[220:223], v220 offset:3072
	global_load_lds_dwordx4 v[232:233], off
	v_lshl_add_u64 v[234:235], s[60:61], 0, v[194:195]
	s_add_i32 m0, s14, 0x2000
	s_nop 0
	global_load_lds_dwordx4 v[234:235], off
	s_barrier
	s_waitcnt lgkmcnt(0)
	s_setprio 1
	v_mfma_f32_16x16x32_bf16 v[120:123], v[200:203], v[144:147], v[120:123]
	v_mfma_f32_16x16x32_bf16 v[108:111], v[208:211], v[144:147], v[108:111]
	v_mfma_f32_16x16x32_bf16 v[100:103], v[200:203], v[152:155], v[100:103]
	v_mfma_f32_16x16x32_bf16 v[96:99], v[208:211], v[152:155], v[96:99]
	v_mfma_f32_16x16x32_bf16 v[84:87], v[200:203], v[160:163], v[84:87]
	v_mfma_f32_16x16x32_bf16 v[76:79], v[208:211], v[160:163], v[76:79]
	v_mfma_f32_16x16x32_bf16 v[68:71], v[200:203], v[168:171], v[68:71]
	v_mfma_f32_16x16x32_bf16 v[64:67], v[208:211], v[168:171], v[64:67]
	v_mfma_f32_16x16x32_bf16 v[120:123], v[204:207], v[148:151], v[120:123]
	v_mfma_f32_16x16x32_bf16 v[108:111], v[220:223], v[148:151], v[108:111]
	v_mfma_f32_16x16x32_bf16 v[100:103], v[204:207], v[156:159], v[100:103]
	v_mfma_f32_16x16x32_bf16 v[96:99], v[220:223], v[156:159], v[96:99]
	v_mfma_f32_16x16x32_bf16 v[84:87], v[204:207], v[164:167], v[84:87]
	v_mfma_f32_16x16x32_bf16 v[76:79], v[220:223], v[164:167], v[76:79]
	v_mfma_f32_16x16x32_bf16 v[68:71], v[204:207], v[172:175], v[68:71]
	v_mfma_f32_16x16x32_bf16 v[64:67], v[220:223], v[172:175], v[64:67]
	s_setprio 0
	s_barrier
	s_mov_b32 m0, s25
	v_lshl_add_u64 v[236:237], s[62:63], 0, v[178:179]
	ds_read_b128 v[144:147], v230 offset:16384
	ds_read_b128 v[148:151], v230 offset:17408
	ds_read_b128 v[152:155], v230 offset:18432
	ds_read_b128 v[156:159], v230 offset:19456
	ds_read_b128 v[160:163], v230 offset:20480
	ds_read_b128 v[164:167], v230 offset:21504
	ds_read_b128 v[168:171], v230 offset:22528
	ds_read_b128 v[172:175], v230 offset:23552
	global_load_lds_dwordx4 v[236:237], off
	v_lshl_add_u64 v[238:239], s[62:63], 0, v[194:195]
	s_mov_b32 m0, s64
	s_nop 0
	global_load_lds_dwordx4 v[238:239], off
	s_barrier
	s_waitcnt lgkmcnt(0)
	s_setprio 1
	v_mfma_f32_16x16x32_bf16 v[60:63], v[116:119], v[144:147], v[60:63]
	v_mfma_f32_16x16x32_bf16 v[56:59], v[128:131], v[144:147], v[56:59]
	v_mfma_f32_16x16x32_bf16 v[48:51], v[116:119], v[152:155], v[48:51]
	v_mfma_f32_16x16x32_bf16 v[40:43], v[128:131], v[152:155], v[40:43]
	v_mfma_f32_16x16x32_bf16 v[28:31], v[116:119], v[160:163], v[28:31]
	v_mfma_f32_16x16x32_bf16 v[24:27], v[128:131], v[160:163], v[24:27]
	v_mfma_f32_16x16x32_bf16 v[16:19], v[116:119], v[168:171], v[16:19]
	v_mfma_f32_16x16x32_bf16 v[8:11], v[128:131], v[168:171], v[8:11]
	v_mfma_f32_16x16x32_bf16 v[60:63], v[124:127], v[148:151], v[60:63]
	v_mfma_f32_16x16x32_bf16 v[56:59], v[132:135], v[148:151], v[56:59]
	v_mfma_f32_16x16x32_bf16 v[48:51], v[124:127], v[156:159], v[48:51]
	v_mfma_f32_16x16x32_bf16 v[40:43], v[132:135], v[156:159], v[40:43]
	v_mfma_f32_16x16x32_bf16 v[28:31], v[124:127], v[164:167], v[28:31]
	v_mfma_f32_16x16x32_bf16 v[24:27], v[132:135], v[164:167], v[24:27]
	v_mfma_f32_16x16x32_bf16 v[16:19], v[124:127], v[172:175], v[16:19]
	v_mfma_f32_16x16x32_bf16 v[8:11], v[132:135], v[172:175], v[8:11]
	s_setprio 0
	s_barrier
; #define PG8_STAGE(bufoff, gbase, voff) do { _Pragma("unroll") for (int _i = 0; _i < 2; ++_i) \
;         __builtin_amdgcn_global_load_lds((const unsigned*)((const char*)(gbase) + (voff)[_i]), (LAS unsigned*)(lds + (bufoff) + ldsw + _i * 8192), 16, 0, 0); } while (0)
; #define PG8_LDA(dst, b, h) do { _Pragma("unroll") for (int m = 0; m < 4; ++m) _Pragma("unroll") for (int k = 0; k < 2; ++k) dst[m][k] = *(const LAS bf16x8*)(lds + PG8_SA(b, h) + aoff + m * 2048 + k * 1024); } while (0)
; #define PG8_LDB(dst, b, h) do { _Pragma("unroll") for (int n = 0; n < 2; ++n) _Pragma("unroll") for (int k = 0; k < 2; ++k) dst[n][k] = *(const LAS bf16x8*)(lds + PG8_SB(b, h) + boff + n * 2048 + k * 1024); } while (0)
; #define PG8_MMA(ai, bj, At, Bt) do { __builtin_amdgcn_s_setprio(1); _Pragma("unroll") for (int m = 0; m < 4; ++m) _Pragma("unroll") for (int n = 0; n < 2; ++n) _Pragma("unroll") for (int k = 0; k < 2; ++k) \
;         acc[ai][bj][m][n] = __builtin_amdgcn_mfma_f32_16x16x32_bf16(Bt[n][k], At[m][k], acc[ai][bj][m][n], 0, 0, 0); __builtin_amdgcn_s_setprio(0); } while (0)
; #define PG8_WAIT_V(n) asm volatile("s_waitcnt vmcnt(" #n ")" ::: "memory")
; #define PG8_WAIT_L(n) asm volatile("s_waitcnt lgkmcnt(" #n ")" ::: "memory")
; #define PG8_BAR __builtin_amdgcn_s_barrier()
; #define PG8_SCHED __builtin_amdgcn_sched_barrier(0)
; template <class Epi>
; __device__ __forceinline__ void gemm_phase(LAS unsigned char* lds, const Gemm g, const StaticOrder S, const Epi E) {
;     ...
;             PG8_STAGE(PG8_SB(0, 1), b2 + hstep, voffA);
;             PG8_WAIT_V(6); PG8_BAR; PG8_MMA(1, 1, At, B1); PG8_BAR;
;             PG8_LDB(B0, 1, 0); PG8_SCHED; PG8_LDA(At, 1, 0); PG8_STAGE(PG8_SA(0, 1), a2 + hstep, voffA);
;             PG8_WAIT_L(8); PG8_BAR; PG8_WAIT_L(0); PG8_MMA(0, 0, At, B0); PG8_BAR; PG8_SCHED;
;             PG8_LDB(B1, 1, 1); PG8_STAGE(PG8_SB(1, 0), b3, voffA);
;             PG8_BAR; PG8_WAIT_L(0); PG8_MMA(0, 1, At, B1); PG8_BAR;
;             PG8_LDA(At, 1, 1); PG8_STAGE(PG8_SA(1, 0), a3, voffA);
	s_add_u32 s30, s60, 0x80000
	s_addc_u32 s31, s61, 0
	s_add_i32 s14, s55, s24
	v_lshl_add_u64 v[116:117], s[30:31], 0, v[178:179]
	s_mov_b32 m0, s14
	s_nop 0
	global_load_lds_dwordx4 v[116:117], off
	v_lshl_add_u64 v[116:117], s[30:31], 0, v[194:195]
	s_add_i32 m0, s14, 0x2000
	s_nop 0
	global_load_lds_dwordx4 v[116:117], off
	s_waitcnt vmcnt(6)
	s_barrier
	s_setprio 1
	v_mfma_f32_16x16x32_bf16 v[52:55], v[200:203], v[144:147], v[52:55]
	v_mfma_f32_16x16x32_bf16 v[44:47], v[208:211], v[144:147], v[44:47]
	v_mfma_f32_16x16x32_bf16 v[36:39], v[200:203], v[152:155], v[36:39]
	v_mfma_f32_16x16x32_bf16 v[32:35], v[208:211], v[152:155], v[32:35]
	v_mfma_f32_16x16x32_bf16 v[20:23], v[200:203], v[160:163], v[20:23]
	v_mfma_f32_16x16x32_bf16 v[12:15], v[208:211], v[160:163], v[12:15]
	v_mfma_f32_16x16x32_bf16 v[4:7], v[200:203], v[168:171], v[4:7]
	v_mfma_f32_16x16x32_bf16 v[0:3], v[208:211], v[168:171], v[0:3]
	v_mfma_f32_16x16x32_bf16 v[52:55], v[204:207], v[148:151], v[52:55]
	v_mfma_f32_16x16x32_bf16 v[44:47], v[220:223], v[148:151], v[44:47]
	v_mfma_f32_16x16x32_bf16 v[36:39], v[204:207], v[156:159], v[36:39]
	v_mfma_f32_16x16x32_bf16 v[32:35], v[220:223], v[156:159], v[32:35]
	v_mfma_f32_16x16x32_bf16 v[20:23], v[204:207], v[164:167], v[20:23]
	v_mfma_f32_16x16x32_bf16 v[12:15], v[220:223], v[164:167], v[12:15]
	v_mfma_f32_16x16x32_bf16 v[4:7], v[204:207], v[172:175], v[4:7]
	v_mfma_f32_16x16x32_bf16 v[0:3], v[220:223], v[172:175], v[0:3]
	s_setprio 0
	s_barrier
	s_add_i32 s14, 0, 0x18000
	v_add_u32_e32 v132, s14, v228
	ds_read_b128 v[116:119], v132
	ds_read_b128 v[124:127], v132 offset:1024
	ds_read_b128 v[128:131], v132 offset:2048
	ds_read_b128 v[132:135], v132 offset:3072
	s_add_u32 s30, s62, 0x80000
	s_addc_u32 s31, s63, 0
	s_mov_b32 m0, s65
	v_lshl_add_u64 v[200:201], s[30:31], 0, v[178:179]
	ds_read_b128 v[144:147], v230 offset:32768
	ds_read_b128 v[148:151], v230 offset:33792
	ds_read_b128 v[152:155], v230 offset:34816
	ds_read_b128 v[156:159], v230 offset:35840
	ds_read_b128 v[160:163], v230 offset:36864
	ds_read_b128 v[164:167], v230 offset:37888
	ds_read_b128 v[168:171], v230 offset:38912
	ds_read_b128 v[172:175], v230 offset:39936
	global_load_lds_dwordx4 v[200:201], off
	v_lshl_add_u64 v[200:201], s[30:31], 0, v[194:195]
	s_mov_b32 m0, s66
	s_nop 0
	global_load_lds_dwordx4 v[200:201], off
	s_waitcnt lgkmcnt(8)
	s_barrier
	s_waitcnt lgkmcnt(0)
	s_setprio 1
	v_mfma_f32_16x16x32_bf16 v[140:143], v[116:119], v[144:147], v[140:143]
	v_mfma_f32_16x16x32_bf16 v[136:139], v[128:131], v[144:147], v[136:139]
	v_mfma_f32_16x16x32_bf16 v[112:115], v[116:119], v[152:155], v[112:115]
	v_mfma_f32_16x16x32_bf16 v[104:107], v[128:131], v[152:155], v[104:107]
	v_mfma_f32_16x16x32_bf16 v[92:95], v[116:119], v[160:163], v[92:95]
	v_mfma_f32_16x16x32_bf16 v[88:91], v[128:131], v[160:163], v[88:91]
	v_mfma_f32_16x16x32_bf16 v[80:83], v[116:119], v[168:171], v[80:83]
	v_mfma_f32_16x16x32_bf16 v[72:75], v[128:131], v[168:171], v[72:75]
	v_mfma_f32_16x16x32_bf16 v[140:143], v[124:127], v[148:151], v[140:143]
	v_mfma_f32_16x16x32_bf16 v[136:139], v[132:135], v[148:151], v[136:139]
	v_mfma_f32_16x16x32_bf16 v[112:115], v[124:127], v[156:159], v[112:115]
	v_mfma_f32_16x16x32_bf16 v[104:107], v[132:135], v[156:159], v[104:107]
	v_mfma_f32_16x16x32_bf16 v[92:95], v[124:127], v[164:167], v[92:95]
	v_mfma_f32_16x16x32_bf16 v[88:91], v[132:135], v[164:167], v[88:91]
	v_mfma_f32_16x16x32_bf16 v[80:83], v[124:127], v[172:175], v[80:83]
	v_mfma_f32_16x16x32_bf16 v[72:75], v[132:135], v[172:175], v[72:75]
	s_setprio 0
	s_barrier
	s_add_i32 s55, 0, 0x1c000
	s_add_i32 s14, s14, s24
	v_add_u32_e32 v220, s55, v228
	v_lshl_add_u64 v[232:233], v[232:233], 0, s[34:35]
	s_mov_b32 m0, s14
	ds_read_b128 v[200:203], v220
	ds_read_b128 v[204:207], v220 offset:1024
	ds_read_b128 v[208:211], v220 offset:2048
	ds_read_b128 v[220:223], v220 offset:3072
	global_load_lds_dwordx4 v[232:233], off
	v_lshl_add_u64 v[232:233], v[234:235], 0, s[34:35]
	s_add_i32 m0, s14, 0x2000
	s_nop 0
	global_load_lds_dwordx4 v[232:233], off
	s_barrier
; #define PG8_STAGE(bufoff, gbase, voff) do { _Pragma("unroll") for (int _i = 0; _i < 2; ++_i) \
;         __builtin_amdgcn_global_load_lds((const unsigned*)((const char*)(gbase) + (voff)[_i]), (LAS unsigned*)(lds + (bufoff) + ldsw + _i * 8192), 16, 0, 0); } while (0)
; #define PG8_MMA(ai, bj, At, Bt) do { __builtin_amdgcn_s_setprio(1); _Pragma("unroll") for (int m = 0; m < 4; ++m) _Pragma("unroll") for (int n = 0; n < 2; ++n) _Pragma("unroll") for (int k = 0; k < 2; ++k) \
;         acc[ai][bj][m][n] = __builtin_amdgcn_mfma_f32_16x16x32_bf16(Bt[n][k], At[m][k], acc[ai][bj][m][n], 0, 0, 0); __builtin_amdgcn_s_setprio(0); } while (0)
; #define PG8_WAIT_V(n) asm volatile("s_waitcnt vmcnt(" #n ")" ::: "memory")
; #define PG8_WAIT_L(n) asm volatile("s_waitcnt lgkmcnt(" #n ")" ::: "memory")
; #define PG8_BAR __builtin_amdgcn_s_barrier()
; #define PG8_SCHED __builtin_amdgcn_sched_barrier(0)
; template <class Epi>
; __device__ __forceinline__ void gemm_phase(LAS unsigned char* lds, const Gemm g, const StaticOrder S, const Epi E) {
;     ...
;             PG8_BAR; PG8_WAIT_L(0); PG8_MMA(1, 0, At, B0); PG8_BAR; PG8_SCHED;
;             PG8_STAGE(PG8_SB(1, 1), b3 + hstep, voffA);
;             PG8_WAIT_V(6); PG8_BAR; PG8_MMA(1, 1, At, B1); PG8_BAR;
;         }
;     __device__ __forceinline__ void operator()(AccRef acc, const pg8::Unit& u, int wr, int wc, int fr, int fq) const {
;         const int row0 = u.pm * 256 + wr * 64 + fr, col0 = u.pn * 256 + wc * 32 + 4 * fq;
;         const int v = u.pm < 32 ? (u.pm >> 3) : 4;
	s_waitcnt lgkmcnt(0)
	s_setprio 1
	v_mfma_f32_16x16x32_bf16 v[120:123], v[200:203], v[144:147], v[120:123]
	v_mfma_f32_16x16x32_bf16 v[108:111], v[208:211], v[144:147], v[108:111]
	v_mfma_f32_16x16x32_bf16 v[100:103], v[200:203], v[152:155], v[100:103]
	v_mfma_f32_16x16x32_bf16 v[96:99], v[208:211], v[152:155], v[96:99]
	v_mfma_f32_16x16x32_bf16 v[84:87], v[200:203], v[160:163], v[84:87]
	v_mfma_f32_16x16x32_bf16 v[76:79], v[208:211], v[160:163], v[76:79]
	v_mfma_f32_16x16x32_bf16 v[68:71], v[200:203], v[168:171], v[68:71]
	v_mfma_f32_16x16x32_bf16 v[64:67], v[208:211], v[168:171], v[64:67]
	v_mfma_f32_16x16x32_bf16 v[120:123], v[204:207], v[148:151], v[120:123]
	v_mfma_f32_16x16x32_bf16 v[108:111], v[220:223], v[148:151], v[108:111]
	v_mfma_f32_16x16x32_bf16 v[100:103], v[204:207], v[156:159], v[100:103]
	v_mfma_f32_16x16x32_bf16 v[96:99], v[220:223], v[156:159], v[96:99]
	v_mfma_f32_16x16x32_bf16 v[84:87], v[204:207], v[164:167], v[84:87]
	v_mfma_f32_16x16x32_bf16 v[76:79], v[220:223], v[164:167], v[76:79]
	v_mfma_f32_16x16x32_bf16 v[68:71], v[204:207], v[172:175], v[68:71]
	v_mfma_f32_16x16x32_bf16 v[64:67], v[220:223], v[172:175], v[64:67]
	s_setprio 0
	s_barrier
	s_mov_b32 m0, s69
	v_lshl_add_u64 v[232:233], v[236:237], 0, s[34:35]
	ds_read_b128 v[144:147], v230 offset:49152
	ds_read_b128 v[148:151], v230 offset:50176
	ds_read_b128 v[152:155], v230 offset:51200
	ds_read_b128 v[156:159], v230 offset:52224
	ds_read_b128 v[160:163], v230 offset:53248
	ds_read_b128 v[164:167], v230 offset:54272
	ds_read_b128 v[168:171], v230 offset:55296
	ds_read_b128 v[172:175], v230 offset:56320
	global_load_lds_dwordx4 v[232:233], off
	v_lshl_add_u64 v[232:233], v[238:239], 0, s[34:35]
	s_mov_b32 m0, s7
	s_nop 0
	global_load_lds_dwordx4 v[232:233], off
	s_barrier
	s_waitcnt lgkmcnt(0)
	s_setprio 1
	v_mfma_f32_16x16x32_bf16 v[60:63], v[116:119], v[144:147], v[60:63]
	v_mfma_f32_16x16x32_bf16 v[56:59], v[128:131], v[144:147], v[56:59]
	v_mfma_f32_16x16x32_bf16 v[48:51], v[116:119], v[152:155], v[48:51]
	v_mfma_f32_16x16x32_bf16 v[40:43], v[128:131], v[152:155], v[40:43]
	v_mfma_f32_16x16x32_bf16 v[28:31], v[116:119], v[160:163], v[28:31]
	v_mfma_f32_16x16x32_bf16 v[24:27], v[128:131], v[160:163], v[24:27]
	v_mfma_f32_16x16x32_bf16 v[16:19], v[116:119], v[168:171], v[16:19]
	v_mfma_f32_16x16x32_bf16 v[8:11], v[128:131], v[168:171], v[8:11]
	v_mfma_f32_16x16x32_bf16 v[60:63], v[124:127], v[148:151], v[60:63]
	v_mfma_f32_16x16x32_bf16 v[56:59], v[132:135], v[148:151], v[56:59]
	v_mfma_f32_16x16x32_bf16 v[48:51], v[124:127], v[156:159], v[48:51]
	v_mfma_f32_16x16x32_bf16 v[40:43], v[132:135], v[156:159], v[40:43]
	v_mfma_f32_16x16x32_bf16 v[28:31], v[124:127], v[164:167], v[28:31]
	v_mfma_f32_16x16x32_bf16 v[24:27], v[132:135], v[164:167], v[24:27]
	v_mfma_f32_16x16x32_bf16 v[16:19], v[124:127], v[172:175], v[16:19]
	v_mfma_f32_16x16x32_bf16 v[8:11], v[132:135], v[172:175], v[8:11]
	s_setprio 0
	s_barrier
	s_add_u32 s30, s60, 0x80080
	s_addc_u32 s31, s61, 0
	s_add_i32 s14, s55, s24
	v_lshl_add_u64 v[116:117], s[30:31], 0, v[178:179]
	s_mov_b32 m0, s14
	s_nop 0
	global_load_lds_dwordx4 v[116:117], off
	v_lshl_add_u64 v[116:117], s[30:31], 0, v[194:195]
	s_add_i32 m0, s14, 0x2000
	s_nop 0
	global_load_lds_dwordx4 v[116:117], off
	s_waitcnt vmcnt(6)
	s_barrier
	s_setprio 1
	v_mfma_f32_16x16x32_bf16 v[52:55], v[200:203], v[144:147], v[52:55]
	v_mfma_f32_16x16x32_bf16 v[44:47], v[208:211], v[144:147], v[44:47]
	v_mfma_f32_16x16x32_bf16 v[36:39], v[200:203], v[152:155], v[36:39]
	v_mfma_f32_16x16x32_bf16 v[32:35], v[208:211], v[152:155], v[32:35]
	v_mfma_f32_16x16x32_bf16 v[20:23], v[200:203], v[160:163], v[20:23]
	v_mfma_f32_16x16x32_bf16 v[12:15], v[208:211], v[160:163], v[12:15]
	v_mfma_f32_16x16x32_bf16 v[4:7], v[200:203], v[168:171], v[4:7]
	v_mfma_f32_16x16x32_bf16 v[0:3], v[208:211], v[168:171], v[0:3]
	v_mfma_f32_16x16x32_bf16 v[52:55], v[204:207], v[148:151], v[52:55]
	v_mfma_f32_16x16x32_bf16 v[44:47], v[220:223], v[148:151], v[44:47]
	v_mfma_f32_16x16x32_bf16 v[36:39], v[204:207], v[156:159], v[36:39]
	v_mfma_f32_16x16x32_bf16 v[32:35], v[220:223], v[156:159], v[32:35]
	v_mfma_f32_16x16x32_bf16 v[20:23], v[204:207], v[164:167], v[20:23]
	v_mfma_f32_16x16x32_bf16 v[12:15], v[220:223], v[164:167], v[12:15]
	v_mfma_f32_16x16x32_bf16 v[4:7], v[204:207], v[172:175], v[4:7]
	v_mfma_f32_16x16x32_bf16 v[0:3], v[220:223], v[172:175], v[0:3]
	s_setprio 0
	s_barrier
	s_add_u32 s45, s45, 0x100
	s_addc_u32 s47, s47, 0
	s_cmp_ge_i32 vcc_lo, s39
	s_mov_b64 s[56:57], s[58:59]
	s_mov_b32 s55, vcc_lo
	s_cbranch_scc0 .LBB0_3568
	s_cmp_gt_i32 s38, 31
	s_mov_b64 s[56:57], 0x12000
	s_cbranch_scc1 .LBB0_3571
	s_ashr_i32 s14, s38, 3
	s_mul_hi_i32 s57, s14, 0x4800
	s_mul_i32 s56, s14, 0x4800

; #define PG8_STAGE(bufoff, gbase, voff) do { _Pragma("unroll") for (int _i = 0; _i < 2; ++_i) \
;         __builtin_amdgcn_global_load_lds((const unsigned*)((const char*)(gbase) + (voff)[_i]), (LAS unsigned*)(lds + (bufoff) + ldsw + _i * 8192), 16, 0, 0); } while (0)
; #define PG8_LDA(dst, b, h) do { _Pragma("unroll") for (int m = 0; m < 4; ++m) _Pragma("unroll") for (int k = 0; k < 2; ++k) dst[m][k] = *(const LAS bf16x8*)(lds + PG8_SA(b, h) + aoff + m * 2048 + k * 1024); } while (0)
; #define PG8_LDB(dst, b, h) do { _Pragma("unroll") for (int n = 0; n < 2; ++n) _Pragma("unroll") for (int k = 0; k < 2; ++k) dst[n][k] = *(const LAS bf16x8*)(lds + PG8_SB(b, h) + boff + n * 2048 + k * 1024); } while (0)
; #define PG8_MMA(ai, bj, At, Bt) do { __builtin_amdgcn_s_setprio(1); _Pragma("unroll") for (int m = 0; m < 4; ++m) _Pragma("unroll") for (int n = 0; n < 2; ++n) _Pragma("unroll") for (int k = 0; k < 2; ++k) \
;         acc[ai][bj][m][n] = __builtin_amdgcn_mfma_f32_16x16x32_bf16(Bt[n][k], At[m][k], acc[ai][bj][m][n], 0, 0, 0); __builtin_amdgcn_s_setprio(0); } while (0)
; #define PG8_WAIT_L(n) asm volatile("s_waitcnt lgkmcnt(" #n ")" ::: "memory")
; #define PG8_BAR __builtin_amdgcn_s_barrier()
; #define PG8_SCHED __builtin_amdgcn_sched_barrier(0)
; template <class Epi>
; __device__ __forceinline__ void gemm_phase(LAS unsigned char* lds, const Gemm g, const StaticOrder S, const Epi E) {
;     ...
;         for (int t = 0; t < nt; t += 2) {
;             const bool last = (t == nt - 2);
;             const char* a1 = cA + (size_t)(t + 1) * kstep;
;             const char* a2 = last ? nA : cA + (size_t)(t + 2) * kstep; const char* b2 = last ? nB : cB + (size_t)(t + 2) * kstep;
;             const char* a3 = a2 + kstep; const char* b3 = b2 + kstep;
;             PG8_LDB(B0, 0, 0); PG8_SCHED; PG8_LDA(At, 0, 0); PG8_STAGE(PG8_SA(1, 1), a1 + hstep, voffA);
;             PG8_WAIT_L(8); PG8_BAR; PG8_WAIT_L(0); PG8_MMA(0, 0, At, B0); PG8_BAR; PG8_SCHED;
;             PG8_LDB(B1, 0, 1); PG8_STAGE(PG8_SB(0, 0), b2, voffA);
;             PG8_BAR; PG8_WAIT_L(0); PG8_MMA(0, 1, At, B1); PG8_BAR;
;             PG8_LDA(At, 0, 1); PG8_STAGE(PG8_SA(0, 0), a2, voffA);
;             PG8_BAR; PG8_WAIT_L(0); PG8_MMA(1, 0, At, B0); PG8_BAR; PG8_SCHED;
.LBB0_3723:
	s_add_u32 s14, s50, 0xfff80080
	s_addc_u32 s30, s51, -1
	s_add_i32 s31, 0, 0x10000
	v_add_u32_e32 v134, s31, v137
	ds_read_b128 v[140:143], v134
	ds_read_b128 v[144:147], v134 offset:1024
	ds_read_b128 v[148:151], v134 offset:2048
	ds_read_b128 v[152:155], v134 offset:3072
	s_cmp_eq_u32 s64, 28
	s_cselect_b32 s55, s3, s30
	s_cselect_b32 s54, s26, s14
	s_cselect_b32 s53, s1, s29
	s_cselect_b32 s52, s27, s28
	v_lshl_add_u64 v[134:135], s[50:51], 0, v[130:131]
	s_add_i32 m0, s47, 0xc000
	ds_read_b128 v[156:159], v139
	ds_read_b128 v[160:163], v139 offset:1024
	ds_read_b128 v[164:167], v139 offset:2048
	ds_read_b128 v[168:171], v139 offset:3072
	ds_read_b128 v[172:175], v139 offset:4096
	ds_read_b128 v[194:197], v139 offset:5120
	ds_read_b128 v[198:201], v139 offset:6144
	ds_read_b128 v[202:205], v139 offset:7168
	global_load_lds_dwordx4 v[134:135], off
	v_lshl_add_u64 v[134:135], s[50:51], 0, v[132:133]
	s_add_i32 m0, s47, 0xe000
	s_nop 0
	global_load_lds_dwordx4 v[134:135], off
	s_waitcnt lgkmcnt(8)
	s_barrier
	s_waitcnt lgkmcnt(0)
	s_setprio 1
	v_mfma_f32_16x16x32_bf16 v[120:123], v[140:143], v[156:159], v[120:123]
	v_mfma_f32_16x16x32_bf16 v[124:127], v[148:151], v[156:159], v[124:127]
	v_mfma_f32_16x16x32_bf16 v[104:107], v[140:143], v[164:167], v[104:107]
	v_mfma_f32_16x16x32_bf16 v[108:111], v[148:151], v[164:167], v[108:111]
	v_mfma_f32_16x16x32_bf16 v[88:91], v[140:143], v[172:175], v[88:91]
	v_mfma_f32_16x16x32_bf16 v[92:95], v[148:151], v[172:175], v[92:95]
	v_mfma_f32_16x16x32_bf16 v[72:75], v[140:143], v[198:201], v[72:75]
	v_mfma_f32_16x16x32_bf16 v[76:79], v[148:151], v[198:201], v[76:79]
	v_mfma_f32_16x16x32_bf16 v[120:123], v[144:147], v[160:163], v[120:123]
	v_mfma_f32_16x16x32_bf16 v[124:127], v[152:155], v[160:163], v[124:127]
	v_mfma_f32_16x16x32_bf16 v[104:107], v[144:147], v[168:171], v[104:107]
	v_mfma_f32_16x16x32_bf16 v[108:111], v[152:155], v[168:171], v[108:111]
	v_mfma_f32_16x16x32_bf16 v[88:91], v[144:147], v[194:197], v[88:91]
	v_mfma_f32_16x16x32_bf16 v[92:95], v[152:155], v[194:197], v[92:95]
	v_mfma_f32_16x16x32_bf16 v[72:75], v[144:147], v[202:205], v[72:75]
	v_mfma_f32_16x16x32_bf16 v[76:79], v[152:155], v[202:205], v[76:79]
	s_setprio 0
	s_barrier
	s_add_i32 s14, 0, 0x14000
	v_add_u32_e32 v134, s14, v137
	s_add_i32 s30, s31, s58
	ds_read_b128 v[206:209], v134
	ds_read_b128 v[220:223], v134 offset:1024
	ds_read_b128 v[228:231], v134 offset:2048
	ds_read_b128 v[232:235], v134 offset:3072
	v_lshl_add_u64 v[134:135], s[52:53], 0, v[178:179]
	s_mov_b32 m0, s30
	v_lshl_add_u64 v[210:211], s[52:53], 0, v[128:129]
	global_load_lds_dwordx4 v[134:135], off
	s_add_i32 m0, s30, 0x2000
	s_nop 0
	global_load_lds_dwordx4 v[210:211], off
	s_barrier
	s_waitcnt lgkmcnt(0)
	s_setprio 1
	v_mfma_f32_16x16x32_bf16 v[112:115], v[206:209], v[156:159], v[112:115]
	v_mfma_f32_16x16x32_bf16 v[116:119], v[228:231], v[156:159], v[116:119]
	v_mfma_f32_16x16x32_bf16 v[96:99], v[206:209], v[164:167], v[96:99]
	v_mfma_f32_16x16x32_bf16 v[100:103], v[228:231], v[164:167], v[100:103]
	v_mfma_f32_16x16x32_bf16 v[80:83], v[206:209], v[172:175], v[80:83]
	v_mfma_f32_16x16x32_bf16 v[84:87], v[228:231], v[172:175], v[84:87]
	v_mfma_f32_16x16x32_bf16 v[64:67], v[206:209], v[198:201], v[64:67]
	v_mfma_f32_16x16x32_bf16 v[68:71], v[228:231], v[198:201], v[68:71]
	v_mfma_f32_16x16x32_bf16 v[112:115], v[220:223], v[160:163], v[112:115]
	v_mfma_f32_16x16x32_bf16 v[116:119], v[232:235], v[160:163], v[116:119]
	v_mfma_f32_16x16x32_bf16 v[96:99], v[220:223], v[168:171], v[96:99]
	v_mfma_f32_16x16x32_bf16 v[100:103], v[232:235], v[168:171], v[100:103]
	v_mfma_f32_16x16x32_bf16 v[80:83], v[220:223], v[194:197], v[80:83]
	v_mfma_f32_16x16x32_bf16 v[84:87], v[232:235], v[194:197], v[84:87]
	v_mfma_f32_16x16x32_bf16 v[64:67], v[220:223], v[202:205], v[64:67]
	v_mfma_f32_16x16x32_bf16 v[68:71], v[232:235], v[202:205], v[68:71]
	s_setprio 0
	s_barrier
	s_mov_b32 m0, s47
	v_lshl_add_u64 v[236:237], s[54:55], 0, v[178:179]
	ds_read_b128 v[156:159], v139 offset:16384
	ds_read_b128 v[160:163], v139 offset:17408
	ds_read_b128 v[164:167], v139 offset:18432
	ds_read_b128 v[168:171], v139 offset:19456
	ds_read_b128 v[172:175], v139 offset:20480
	ds_read_b128 v[194:197], v139 offset:21504
	ds_read_b128 v[198:201], v139 offset:22528
	ds_read_b128 v[202:205], v139 offset:23552
	global_load_lds_dwordx4 v[236:237], off
	v_lshl_add_u64 v[238:239], s[54:55], 0, v[128:129]
	s_mov_b32 m0, s49
	s_nop 0
	global_load_lds_dwordx4 v[238:239], off
	s_barrier
	s_waitcnt lgkmcnt(0)
	s_setprio 1
	v_mfma_f32_16x16x32_bf16 v[56:59], v[140:143], v[156:159], v[56:59]
	v_mfma_f32_16x16x32_bf16 v[60:63], v[148:151], v[156:159], v[60:63]
	v_mfma_f32_16x16x32_bf16 v[40:43], v[140:143], v[164:167], v[40:43]
	v_mfma_f32_16x16x32_bf16 v[44:47], v[148:151], v[164:167], v[44:47]
	v_mfma_f32_16x16x32_bf16 v[24:27], v[140:143], v[172:175], v[24:27]
	v_mfma_f32_16x16x32_bf16 v[28:31], v[148:151], v[172:175], v[28:31]
	v_mfma_f32_16x16x32_bf16 v[8:11], v[140:143], v[198:201], v[8:11]
	v_mfma_f32_16x16x32_bf16 v[12:15], v[148:151], v[198:201], v[12:15]
	v_mfma_f32_16x16x32_bf16 v[56:59], v[144:147], v[160:163], v[56:59]
	v_mfma_f32_16x16x32_bf16 v[60:63], v[152:155], v[160:163], v[60:63]
	v_mfma_f32_16x16x32_bf16 v[40:43], v[144:147], v[168:171], v[40:43]
	v_mfma_f32_16x16x32_bf16 v[44:47], v[152:155], v[168:171], v[44:47]
	v_mfma_f32_16x16x32_bf16 v[24:27], v[144:147], v[194:197], v[24:27]
	v_mfma_f32_16x16x32_bf16 v[28:31], v[152:155], v[194:197], v[28:31]
	v_mfma_f32_16x16x32_bf16 v[8:11], v[144:147], v[202:205], v[8:11]
	v_mfma_f32_16x16x32_bf16 v[12:15], v[152:155], v[202:205], v[12:15]
	s_setprio 0
	s_barrier
; #define PG8_STAGE(bufoff, gbase, voff) do { _Pragma("unroll") for (int _i = 0; _i < 2; ++_i) \
;         __builtin_amdgcn_global_load_lds((const unsigned*)((const char*)(gbase) + (voff)[_i]), (LAS unsigned*)(lds + (bufoff) + ldsw + _i * 8192), 16, 0, 0); } while (0)
; #define PG8_LDA(dst, b, h) do { _Pragma("unroll") for (int m = 0; m < 4; ++m) _Pragma("unroll") for (int k = 0; k < 2; ++k) dst[m][k] = *(const LAS bf16x8*)(lds + PG8_SA(b, h) + aoff + m * 2048 + k * 1024); } while (0)
; #define PG8_LDB(dst, b, h) do { _Pragma("unroll") for (int n = 0; n < 2; ++n) _Pragma("unroll") for (int k = 0; k < 2; ++k) dst[n][k] = *(const LAS bf16x8*)(lds + PG8_SB(b, h) + boff + n * 2048 + k * 1024); } while (0)
; #define PG8_MMA(ai, bj, At, Bt) do { __builtin_amdgcn_s_setprio(1); _Pragma("unroll") for (int m = 0; m < 4; ++m) _Pragma("unroll") for (int n = 0; n < 2; ++n) _Pragma("unroll") for (int k = 0; k < 2; ++k) \
;         acc[ai][bj][m][n] = __builtin_amdgcn_mfma_f32_16x16x32_bf16(Bt[n][k], At[m][k], acc[ai][bj][m][n], 0, 0, 0); __builtin_amdgcn_s_setprio(0); } while (0)
; #define PG8_WAIT_V(n) asm volatile("s_waitcnt vmcnt(" #n ")" ::: "memory")
; #define PG8_WAIT_L(n) asm volatile("s_waitcnt lgkmcnt(" #n ")" ::: "memory")
; #define PG8_BAR __builtin_amdgcn_s_barrier()
; #define PG8_SCHED __builtin_amdgcn_sched_barrier(0)
; template <class Epi>
; __device__ __forceinline__ void gemm_phase(LAS unsigned char* lds, const Gemm g, const StaticOrder S, const Epi E) {
;     ...
;             PG8_STAGE(PG8_SB(0, 1), b2 + hstep, voffA);
;             PG8_WAIT_V(6); PG8_BAR; PG8_MMA(1, 1, At, B1); PG8_BAR;
;             PG8_LDB(B0, 1, 0); PG8_SCHED; PG8_LDA(At, 1, 0); PG8_STAGE(PG8_SA(0, 1), a2 + hstep, voffA);
;             PG8_WAIT_L(8); PG8_BAR; PG8_WAIT_L(0); PG8_MMA(0, 0, At, B0); PG8_BAR; PG8_SCHED;
;             PG8_LDB(B1, 1, 1); PG8_STAGE(PG8_SB(1, 0), b3, voffA);
;             PG8_BAR; PG8_WAIT_L(0); PG8_MMA(0, 1, At, B1); PG8_BAR;
;             PG8_LDA(At, 1, 1); PG8_STAGE(PG8_SA(1, 0), a3, voffA);
;             PG8_BAR; PG8_WAIT_L(0); PG8_MMA(1, 0, At, B0); PG8_BAR; PG8_SCHED;
	s_add_u32 s30, s52, 0x80000
	s_addc_u32 s31, s53, 0
	s_add_i32 s14, s14, s58
	v_lshl_add_u64 v[140:141], s[30:31], 0, v[178:179]
	s_mov_b32 m0, s14
	s_nop 0
	global_load_lds_dwordx4 v[140:141], off
	v_lshl_add_u64 v[140:141], s[30:31], 0, v[128:129]
	s_add_i32 m0, s14, 0x2000
	s_nop 0
	global_load_lds_dwordx4 v[140:141], off
	s_waitcnt vmcnt(6)
	s_barrier
	s_setprio 1
	v_mfma_f32_16x16x32_bf16 v[48:51], v[206:209], v[156:159], v[48:51]
	v_mfma_f32_16x16x32_bf16 v[52:55], v[228:231], v[156:159], v[52:55]
	v_mfma_f32_16x16x32_bf16 v[32:35], v[206:209], v[164:167], v[32:35]
	v_mfma_f32_16x16x32_bf16 v[36:39], v[228:231], v[164:167], v[36:39]
	v_mfma_f32_16x16x32_bf16 v[16:19], v[206:209], v[172:175], v[16:19]
	v_mfma_f32_16x16x32_bf16 v[20:23], v[228:231], v[172:175], v[20:23]
	v_mfma_f32_16x16x32_bf16 v[0:3], v[206:209], v[198:201], v[0:3]
	v_mfma_f32_16x16x32_bf16 v[4:7], v[228:231], v[198:201], v[4:7]
	v_mfma_f32_16x16x32_bf16 v[48:51], v[220:223], v[160:163], v[48:51]
	v_mfma_f32_16x16x32_bf16 v[52:55], v[232:235], v[160:163], v[52:55]
	v_mfma_f32_16x16x32_bf16 v[32:35], v[220:223], v[168:171], v[32:35]
	v_mfma_f32_16x16x32_bf16 v[36:39], v[232:235], v[168:171], v[36:39]
	v_mfma_f32_16x16x32_bf16 v[16:19], v[220:223], v[194:197], v[16:19]
	v_mfma_f32_16x16x32_bf16 v[20:23], v[232:235], v[194:197], v[20:23]
	v_mfma_f32_16x16x32_bf16 v[0:3], v[220:223], v[202:205], v[0:3]
	v_mfma_f32_16x16x32_bf16 v[4:7], v[232:235], v[202:205], v[4:7]
	s_setprio 0
	s_barrier
	s_add_i32 s14, 0, 0x18000
	v_add_u32_e32 v152, s14, v137
	ds_read_b128 v[140:143], v152
	ds_read_b128 v[144:147], v152 offset:1024
	ds_read_b128 v[148:151], v152 offset:2048
	ds_read_b128 v[152:155], v152 offset:3072
	s_add_u32 s30, s54, 0x80000
	s_addc_u32 s31, s55, 0
	s_mov_b32 m0, s59
	v_lshl_add_u64 v[206:207], s[30:31], 0, v[178:179]
	ds_read_b128 v[156:159], v139 offset:32768
	ds_read_b128 v[160:163], v139 offset:33792
	ds_read_b128 v[164:167], v139 offset:34816
	ds_read_b128 v[168:171], v139 offset:35840
	ds_read_b128 v[172:175], v139 offset:36864
	ds_read_b128 v[194:197], v139 offset:37888
	ds_read_b128 v[198:201], v139 offset:38912
	ds_read_b128 v[202:205], v139 offset:39936
	global_load_lds_dwordx4 v[206:207], off
	v_lshl_add_u64 v[206:207], s[30:31], 0, v[128:129]
	s_mov_b32 m0, s60
	s_nop 0
	global_load_lds_dwordx4 v[206:207], off
	s_waitcnt lgkmcnt(8)
	s_barrier
	s_waitcnt lgkmcnt(0)
	s_setprio 1
	v_mfma_f32_16x16x32_bf16 v[120:123], v[140:143], v[156:159], v[120:123]
	v_mfma_f32_16x16x32_bf16 v[124:127], v[148:151], v[156:159], v[124:127]
	v_mfma_f32_16x16x32_bf16 v[104:107], v[140:143], v[164:167], v[104:107]
	v_mfma_f32_16x16x32_bf16 v[108:111], v[148:151], v[164:167], v[108:111]
	v_mfma_f32_16x16x32_bf16 v[88:91], v[140:143], v[172:175], v[88:91]
	v_mfma_f32_16x16x32_bf16 v[92:95], v[148:151], v[172:175], v[92:95]
	v_mfma_f32_16x16x32_bf16 v[72:75], v[140:143], v[198:201], v[72:75]
	v_mfma_f32_16x16x32_bf16 v[76:79], v[148:151], v[198:201], v[76:79]
	v_mfma_f32_16x16x32_bf16 v[120:123], v[144:147], v[160:163], v[120:123]
	v_mfma_f32_16x16x32_bf16 v[124:127], v[152:155], v[160:163], v[124:127]
	v_mfma_f32_16x16x32_bf16 v[104:107], v[144:147], v[168:171], v[104:107]
	v_mfma_f32_16x16x32_bf16 v[108:111], v[152:155], v[168:171], v[108:111]
	v_mfma_f32_16x16x32_bf16 v[88:91], v[144:147], v[194:197], v[88:91]
	v_mfma_f32_16x16x32_bf16 v[92:95], v[152:155], v[194:197], v[92:95]
	v_mfma_f32_16x16x32_bf16 v[72:75], v[144:147], v[202:205], v[72:75]
	v_mfma_f32_16x16x32_bf16 v[76:79], v[152:155], v[202:205], v[76:79]
	s_setprio 0
	s_barrier
	s_add_i32 s54, 0, 0x1c000
	s_add_i32 s14, s14, s58
	v_add_u32_e32 v227, s54, v137
	v_lshl_add_u64 v[134:135], v[134:135], 0, s[34:35]
	s_mov_b32 m0, s14
	ds_read_b128 v[206:209], v227
	ds_read_b128 v[220:223], v227 offset:1024
	ds_read_b128 v[228:231], v227 offset:2048
	ds_read_b128 v[232:235], v227 offset:3072
	global_load_lds_dwordx4 v[134:135], off
	v_lshl_add_u64 v[134:135], v[210:211], 0, s[34:35]
	s_add_i32 m0, s14, 0x2000
	s_nop 0
	global_load_lds_dwordx4 v[134:135], off
	s_barrier
	s_waitcnt lgkmcnt(0)
	s_setprio 1
	v_mfma_f32_16x16x32_bf16 v[112:115], v[206:209], v[156:159], v[112:115]
	v_mfma_f32_16x16x32_bf16 v[116:119], v[228:231], v[156:159], v[116:119]
	v_mfma_f32_16x16x32_bf16 v[96:99], v[206:209], v[164:167], v[96:99]
	v_mfma_f32_16x16x32_bf16 v[100:103], v[228:231], v[164:167], v[100:103]
	v_mfma_f32_16x16x32_bf16 v[80:83], v[206:209], v[172:175], v[80:83]
	v_mfma_f32_16x16x32_bf16 v[84:87], v[228:231], v[172:175], v[84:87]
	v_mfma_f32_16x16x32_bf16 v[64:67], v[206:209], v[198:201], v[64:67]
	v_mfma_f32_16x16x32_bf16 v[68:71], v[228:231], v[198:201], v[68:71]
	v_mfma_f32_16x16x32_bf16 v[112:115], v[220:223], v[160:163], v[112:115]
	v_mfma_f32_16x16x32_bf16 v[116:119], v[232:235], v[160:163], v[116:119]
	v_mfma_f32_16x16x32_bf16 v[96:99], v[220:223], v[168:171], v[96:99]
	v_mfma_f32_16x16x32_bf16 v[100:103], v[232:235], v[168:171], v[100:103]
	v_mfma_f32_16x16x32_bf16 v[80:83], v[220:223], v[194:197], v[80:83]
	v_mfma_f32_16x16x32_bf16 v[84:87], v[232:235], v[194:197], v[84:87]
	v_mfma_f32_16x16x32_bf16 v[64:67], v[220:223], v[202:205], v[64:67]
	v_mfma_f32_16x16x32_bf16 v[68:71], v[232:235], v[202:205], v[68:71]
	s_setprio 0
	s_barrier
	s_mov_b32 m0, s61
	v_lshl_add_u64 v[134:135], v[236:237], 0, s[34:35]
	ds_read_b128 v[156:159], v139 offset:49152
	ds_read_b128 v[160:163], v139 offset:50176
	ds_read_b128 v[164:167], v139 offset:51200
	ds_read_b128 v[168:171], v139 offset:52224
	ds_read_b128 v[172:175], v139 offset:53248
	ds_read_b128 v[194:197], v139 offset:54272
	ds_read_b128 v[198:201], v139 offset:55296
	ds_read_b128 v[202:205], v139 offset:56320
	global_load_lds_dwordx4 v[134:135], off
	v_lshl_add_u64 v[134:135], v[238:239], 0, s[34:35]
	s_mov_b32 m0, s62
	s_nop 0
	global_load_lds_dwordx4 v[134:135], off
	s_barrier
; #define PG8_STAGE(bufoff, gbase, voff) do { _Pragma("unroll") for (int _i = 0; _i < 2; ++_i) \
;         __builtin_amdgcn_global_load_lds((const unsigned*)((const char*)(gbase) + (voff)[_i]), (LAS unsigned*)(lds + (bufoff) + ldsw + _i * 8192), 16, 0, 0); } while (0)
; #define PG8_LDA(dst, b, h) do { _Pragma("unroll") for (int m = 0; m < 4; ++m) _Pragma("unroll") for (int k = 0; k < 2; ++k) dst[m][k] = *(const LAS bf16x8*)(lds + PG8_SA(b, h) + aoff + m * 2048 + k * 1024); } while (0)
; #define PG8_MMA(ai, bj, At, Bt) do { __builtin_amdgcn_s_setprio(1); _Pragma("unroll") for (int m = 0; m < 4; ++m) _Pragma("unroll") for (int n = 0; n < 2; ++n) _Pragma("unroll") for (int k = 0; k < 2; ++k) \
;         acc[ai][bj][m][n] = __builtin_amdgcn_mfma_f32_16x16x32_bf16(Bt[n][k], At[m][k], acc[ai][bj][m][n], 0, 0, 0); __builtin_amdgcn_s_setprio(0); } while (0)
; #define PG8_WAIT_V(n) asm volatile("s_waitcnt vmcnt(" #n ")" ::: "memory")
; #define PG8_WAIT_L(n) asm volatile("s_waitcnt lgkmcnt(" #n ")" ::: "memory")
; #define PG8_BAR __builtin_amdgcn_s_barrier()
; #define PG8_SCHED __builtin_amdgcn_sched_barrier(0)
; template <class Epi>
; __device__ __forceinline__ void gemm_phase(LAS unsigned char* lds, const Gemm g, const StaticOrder S, const Epi E) {
;     ...
;             PG8_BAR; PG8_WAIT_L(0); PG8_MMA(0, 1, At, B1); PG8_BAR;
;             PG8_LDA(At, 1, 1); PG8_STAGE(PG8_SA(1, 0), a3, voffA);
;             PG8_BAR; PG8_WAIT_L(0); PG8_MMA(1, 0, At, B0); PG8_BAR; PG8_SCHED;
;             PG8_STAGE(PG8_SB(1, 1), b3 + hstep, voffA);
;             PG8_WAIT_V(6); PG8_BAR; PG8_MMA(1, 1, At, B1); PG8_BAR;
;         }
;     __device__ __forceinline__ void operator()(AccRef acc, const pg8::Unit& u, int wr, int wc, int fr, int fq) const {
;     ...
;             for (int m = 0; m < 4; ++m) { bf16_t* rowp = G + (size_t)(row0 + ai * 128 + m * 16) * FH + col0;
; #pragma unroll
;                 for (int bj = 0; bj < 2; ++bj) { const f32x4 gq = acc[ai][bj][m][0], uq = acc[ai][bj][m][1]; float v[4];
; #pragma unroll
;                     for (int i = 0; i < 4; ++i) v[i] = gq[i] * uq[i] * __builtin_amdgcn_rcpf(1.f + __builtin_amdgcn_exp2f(-gq[i] * LOG2E));
	s_waitcnt lgkmcnt(0)
	s_setprio 1
	v_mfma_f32_16x16x32_bf16 v[56:59], v[140:143], v[156:159], v[56:59]
	v_mfma_f32_16x16x32_bf16 v[60:63], v[148:151], v[156:159], v[60:63]
	v_mfma_f32_16x16x32_bf16 v[40:43], v[140:143], v[164:167], v[40:43]
	v_mfma_f32_16x16x32_bf16 v[44:47], v[148:151], v[164:167], v[44:47]
	v_mfma_f32_16x16x32_bf16 v[24:27], v[140:143], v[172:175], v[24:27]
	v_mfma_f32_16x16x32_bf16 v[28:31], v[148:151], v[172:175], v[28:31]
	v_mfma_f32_16x16x32_bf16 v[8:11], v[140:143], v[198:201], v[8:11]
	v_mfma_f32_16x16x32_bf16 v[12:15], v[148:151], v[198:201], v[12:15]
	v_mfma_f32_16x16x32_bf16 v[56:59], v[144:147], v[160:163], v[56:59]
	v_mfma_f32_16x16x32_bf16 v[60:63], v[152:155], v[160:163], v[60:63]
	v_mfma_f32_16x16x32_bf16 v[40:43], v[144:147], v[168:171], v[40:43]
	v_mfma_f32_16x16x32_bf16 v[44:47], v[152:155], v[168:171], v[44:47]
	v_mfma_f32_16x16x32_bf16 v[24:27], v[144:147], v[194:197], v[24:27]
	v_mfma_f32_16x16x32_bf16 v[28:31], v[152:155], v[194:197], v[28:31]
	v_mfma_f32_16x16x32_bf16 v[8:11], v[144:147], v[202:205], v[8:11]
	v_mfma_f32_16x16x32_bf16 v[12:15], v[152:155], v[202:205], v[12:15]
	s_setprio 0
	s_barrier
	s_add_u32 s30, s52, 0x80080
	s_addc_u32 s31, s53, 0
	s_add_i32 s14, s54, s58
	v_lshl_add_u64 v[134:135], s[30:31], 0, v[178:179]
	s_mov_b32 m0, s14
	s_nop 0
	global_load_lds_dwordx4 v[134:135], off
	v_lshl_add_u64 v[134:135], s[30:31], 0, v[128:129]
	s_add_i32 m0, s14, 0x2000
	s_nop 0
	global_load_lds_dwordx4 v[134:135], off
	s_waitcnt vmcnt(6)
	s_barrier
	s_setprio 1
	v_mfma_f32_16x16x32_bf16 v[48:51], v[206:209], v[156:159], v[48:51]
	v_mfma_f32_16x16x32_bf16 v[52:55], v[228:231], v[156:159], v[52:55]
	v_mfma_f32_16x16x32_bf16 v[32:35], v[206:209], v[164:167], v[32:35]
	v_mfma_f32_16x16x32_bf16 v[36:39], v[228:231], v[164:167], v[36:39]
	v_mfma_f32_16x16x32_bf16 v[16:19], v[206:209], v[172:175], v[16:19]
	v_mfma_f32_16x16x32_bf16 v[20:23], v[228:231], v[172:175], v[20:23]
	v_mfma_f32_16x16x32_bf16 v[0:3], v[206:209], v[198:201], v[0:3]
	v_mfma_f32_16x16x32_bf16 v[4:7], v[228:231], v[198:201], v[4:7]
	v_mfma_f32_16x16x32_bf16 v[48:51], v[220:223], v[160:163], v[48:51]
	v_mfma_f32_16x16x32_bf16 v[52:55], v[232:235], v[160:163], v[52:55]
	v_mfma_f32_16x16x32_bf16 v[32:35], v[220:223], v[168:171], v[32:35]
	v_mfma_f32_16x16x32_bf16 v[36:39], v[232:235], v[168:171], v[36:39]
	v_mfma_f32_16x16x32_bf16 v[16:19], v[220:223], v[194:197], v[16:19]
	v_mfma_f32_16x16x32_bf16 v[20:23], v[232:235], v[194:197], v[20:23]
	v_mfma_f32_16x16x32_bf16 v[0:3], v[220:223], v[202:205], v[0:3]
	v_mfma_f32_16x16x32_bf16 v[4:7], v[232:235], v[202:205], v[4:7]
	s_setprio 0
	s_barrier
	s_add_i32 s64, s64, 2
	s_add_u32 s50, s50, 0x100
	s_addc_u32 s51, s51, 0
	s_add_u32 s28, s28, 0x100
	s_addc_u32 s29, s29, 0
	s_cmp_gt_u32 s64, 29
	s_cbranch_scc0 .LBB0_3723
	v_mul_f32_e32 v116, v116, v112
	v_mul_f32_e32 v112, 0xbfb8aa3b, v112
	v_exp_f32_e32 v112, v112
	v_mul_f32_e32 v100, v100, v96
	v_mul_f32_e32 v96, 0xbfb8aa3b, v96
	v_exp_f32_e32 v96, v96
	v_mul_f32_e32 v84, v84, v80
	v_mul_f32_e32 v80, 0xbfb8aa3b, v80
	v_add_f32_e32 v112, 1.0, v112
	v_exp_f32_e32 v80, v80
	v_rcp_f32_e32 v112, v112
	v_mul_f32_e32 v68, v68, v64
	v_mul_f32_e32 v64, 0xbfb8aa3b, v64
	v_add_f32_e32 v96, 1.0, v96
	v_exp_f32_e32 v64, v64
	v_rcp_f32_e32 v96, v96
	v_mul_f32_e32 v52, v52, v48
	v_mul_f32_e32 v48, 0xbfb8aa3b, v48
	v_add_f32_e32 v80, 1.0, v80
	v_exp_f32_e32 v48, v48
	v_mul_f32_e32 v112, v116, v112
	v_mul_f32_e32 v116, v117, v113
	v_mul_f32_e32 v113, 0xbfb8aa3b, v113
	v_rcp_f32_e32 v80, v80
	v_mul_f32_e32 v36, v36, v32
	v_mul_f32_e32 v32, 0xbfb8aa3b, v32
	v_exp_f32_e32 v113, v113
	v_add_f32_e32 v64, 1.0, v64
	v_exp_f32_e32 v32, v32
	v_mul_f32_e32 v96, v100, v96
	v_mul_f32_e32 v100, v101, v97
	v_mul_f32_e32 v97, 0xbfb8aa3b, v97
	v_rcp_f32_e32 v64, v64
	v_mul_f32_e32 v20, v20, v16
	v_mul_f32_e32 v16, 0xbfb8aa3b, v16
	v_exp_f32_e32 v97, v97
	v_add_f32_e32 v48, 1.0, v48
	v_exp_f32_e32 v16, v16
	v_mul_f32_e32 v124, v124, v120
	v_mul_f32_e32 v120, 0xbfb8aa3b, v120
	v_mul_f32_e32 v108, v108, v104
	v_mul_f32_e32 v104, 0xbfb8aa3b, v104
	v_mul_f32_e32 v92, v92, v88
	v_mul_f32_e32 v88, 0xbfb8aa3b, v88
	v_mul_f32_e32 v80, v84, v80
	v_mul_f32_e32 v84, v85, v81
	v_mul_f32_e32 v81, 0xbfb8aa3b, v81
	v_mul_f32_e32 v76, v76, v72
	v_mul_f32_e32 v72, 0xbfb8aa3b, v72
	v_mul_f32_e32 v60, v60, v56
	v_mul_f32_e32 v56, 0xbfb8aa3b, v56
	v_rcp_f32_e32 v48, v48
	v_mul_f32_e32 v44, v44, v40
	v_mul_f32_e32 v40, 0xbfb8aa3b, v40
	v_mul_f32_e32 v28, v28, v24
	v_mul_f32_e32 v24, 0xbfb8aa3b, v24
	v_mul_f32_e32 v12, v12, v8
	v_mul_f32_e32 v8, 0xbfb8aa3b, v8
	v_mul_f32_e32 v4, v4, v0
	v_mul_f32_e32 v0, 0xbfb8aa3b, v0
	v_exp_f32_e32 v120, v120
	v_add_f32_e32 v113, 1.0, v113
	v_exp_f32_e32 v104, v104
	v_exp_f32_e32 v88, v88
	v_exp_f32_e32 v81, v81
	v_exp_f32_e32 v72, v72
	v_exp_f32_e32 v56, v56
	v_exp_f32_e32 v40, v40
	v_add_f32_e32 v32, 1.0, v32
	v_exp_f32_e32 v24, v24
	v_exp_f32_e32 v8, v8
	v_exp_f32_e32 v0, v0
	v_rcp_f32_e32 v113, v113
	v_mul_f32_e32 v64, v68, v64
	v_mul_f32_e32 v68, v69, v65
	v_mul_f32_e32 v65, 0xbfb8aa3b, v65
	v_rcp_f32_e32 v32, v32
	v_add_f32_e32 v97, 1.0, v97
	v_exp_f32_e32 v65, v65
	v_add_f32_e32 v16, 1.0, v16
	v_rcp_f32_e32 v97, v97
	v_mul_f32_e32 v48, v52, v48
	v_mul_f32_e32 v52, v53, v49
	v_mul_f32_e32 v49, 0xbfb8aa3b, v49
	v_rcp_f32_e32 v16, v16
	v_add_f32_e32 v120, 1.0, v120
	v_add_f32_e32 v104, 1.0, v104
	v_add_f32_e32 v88, 1.0, v88
	v_add_f32_e32 v81, 1.0, v81
	v_add_f32_e32 v72, 1.0, v72
	v_add_f32_e32 v56, 1.0, v56
	v_exp_f32_e32 v49, v49
	v_add_f32_e32 v40, 1.0, v40
	v_add_f32_e32 v24, 1.0, v24
	v_add_f32_e32 v8, 1.0, v8
	v_add_f32_e32 v0, 1.0, v0
; __device__ __forceinline__ unsigned cvt_pk_bf16(float lo, float hi) { unsigned r; asm("v_cvt_pk_bf16_f32 %0, %1, %2" : "=v"(r) : "v"(lo), "v"(hi)); return r; }
;     __device__ __forceinline__ void operator()(AccRef acc, const pg8::Unit& u, int wr, int wc, int fr, int fq) const {
;     ...
;             for (int m = 0; m < 4; ++m) { bf16_t* rowp = G + (size_t)(row0 + ai * 128 + m * 16) * FH + col0;
; #pragma unroll
;                 for (int bj = 0; bj < 2; ++bj) { const f32x4 gq = acc[ai][bj][m][0], uq = acc[ai][bj][m][1]; float v[4];
; #pragma unroll
;                     for (int i = 0; i < 4; ++i) v[i] = gq[i] * uq[i] * __builtin_amdgcn_rcpf(1.f + __builtin_amdgcn_exp2f(-gq[i] * LOG2E));
;                     u32x2 w; w.x = cvt_pk_bf16(v[0], v[1]); w.y = cvt_pk_bf16(v[2], v[3]);
	v_rcp_f32_e32 v120, v120
	v_mul_f32_e32 v113, v116, v113
	v_mul_f32_e32 v116, v118, v114
	v_mul_f32_e32 v114, 0xbfb8aa3b, v114
	v_rcp_f32_e32 v104, v104
	v_rcp_f32_e32 v88, v88
	v_rcp_f32_e32 v81, v81
	v_rcp_f32_e32 v72, v72
	v_rcp_f32_e32 v56, v56
	v_rcp_f32_e32 v40, v40
	v_mul_f32_e32 v32, v36, v32
	v_mul_f32_e32 v36, v37, v33
	v_mul_f32_e32 v33, 0xbfb8aa3b, v33
	v_rcp_f32_e32 v24, v24
	v_rcp_f32_e32 v8, v8
	v_rcp_f32_e32 v0, v0
	v_exp_f32_e32 v114, v114
	v_add_f32_e32 v65, 1.0, v65
	v_exp_f32_e32 v33, v33
	v_mul_f32_e32 v97, v100, v97
	v_mul_f32_e32 v100, v102, v98
	v_mul_f32_e32 v98, 0xbfb8aa3b, v98
	v_rcp_f32_e32 v65, v65
	v_mul_f32_e32 v16, v20, v16
	v_mul_f32_e32 v20, v21, v17
	v_mul_f32_e32 v17, 0xbfb8aa3b, v17
	v_exp_f32_e32 v98, v98
	v_add_f32_e32 v49, 1.0, v49
	v_exp_f32_e32 v17, v17
	v_mul_f32_e32 v120, v124, v120
	v_mul_f32_e32 v124, v125, v121
	v_mul_f32_e32 v121, 0xbfb8aa3b, v121
	v_mul_f32_e32 v104, v108, v104
	v_mul_f32_e32 v108, v109, v105
	v_mul_f32_e32 v105, 0xbfb8aa3b, v105
	v_mul_f32_e32 v88, v92, v88
	v_mul_f32_e32 v92, v93, v89
	v_mul_f32_e32 v89, 0xbfb8aa3b, v89
	v_mul_f32_e32 v81, v84, v81
	v_mul_f32_e32 v84, v86, v82
	v_mul_f32_e32 v82, 0xbfb8aa3b, v82
	v_mul_f32_e32 v72, v76, v72
	v_mul_f32_e32 v76, v77, v73
	v_mul_f32_e32 v73, 0xbfb8aa3b, v73
	v_mul_f32_e32 v56, v60, v56
	v_mul_f32_e32 v60, v61, v57
	v_mul_f32_e32 v57, 0xbfb8aa3b, v57
	v_rcp_f32_e32 v49, v49
	v_mul_f32_e32 v40, v44, v40
	v_mul_f32_e32 v44, v45, v41
	v_mul_f32_e32 v41, 0xbfb8aa3b, v41
	v_mul_f32_e32 v24, v28, v24
	v_mul_f32_e32 v28, v29, v25
	v_mul_f32_e32 v25, 0xbfb8aa3b, v25
	v_mul_f32_e32 v8, v12, v8
	v_mul_f32_e32 v12, v13, v9
	v_mul_f32_e32 v9, 0xbfb8aa3b, v9
	v_mul_f32_e32 v0, v4, v0
	v_mul_f32_e32 v4, v5, v1
	v_mul_f32_e32 v1, 0xbfb8aa3b, v1
	v_exp_f32_e32 v121, v121
	v_add_f32_e32 v114, 1.0, v114
	v_exp_f32_e32 v105, v105
	v_exp_f32_e32 v89, v89
	v_exp_f32_e32 v82, v82
	v_exp_f32_e32 v73, v73
	v_exp_f32_e32 v57, v57
	v_exp_f32_e32 v41, v41
	v_add_f32_e32 v33, 1.0, v33
	v_exp_f32_e32 v25, v25
	v_exp_f32_e32 v9, v9
	v_exp_f32_e32 v1, v1
	v_rcp_f32_e32 v114, v114
	v_mul_f32_e32 v65, v68, v65
	v_mul_f32_e32 v68, v70, v66
	v_mul_f32_e32 v66, 0xbfb8aa3b, v66
	v_rcp_f32_e32 v33, v33
	v_add_f32_e32 v98, 1.0, v98
	v_exp_f32_e32 v66, v66
	v_add_f32_e32 v17, 1.0, v17
	v_rcp_f32_e32 v98, v98
	v_mul_f32_e32 v49, v52, v49
	v_mul_f32_e32 v52, v54, v50
	v_mul_f32_e32 v50, 0xbfb8aa3b, v50
	v_rcp_f32_e32 v17, v17
	v_add_f32_e32 v121, 1.0, v121
	v_add_f32_e32 v105, 1.0, v105
	v_add_f32_e32 v89, 1.0, v89
	v_add_f32_e32 v82, 1.0, v82
	v_add_f32_e32 v73, 1.0, v73
	v_add_f32_e32 v57, 1.0, v57
	v_exp_f32_e32 v50, v50
	v_add_f32_e32 v41, 1.0, v41
	v_add_f32_e32 v25, 1.0, v25
	v_add_f32_e32 v9, 1.0, v9
	v_add_f32_e32 v1, 1.0, v1
	v_rcp_f32_e32 v121, v121
	v_mul_f32_e32 v114, v116, v114
	v_mul_f32_e32 v116, v119, v115
	v_mul_f32_e32 v115, 0xbfb8aa3b, v115
	v_rcp_f32_e32 v105, v105
	v_rcp_f32_e32 v89, v89
	v_rcp_f32_e32 v82, v82
	v_rcp_f32_e32 v73, v73
	v_rcp_f32_e32 v57, v57
	v_rcp_f32_e32 v41, v41
	v_mul_f32_e32 v33, v36, v33
	v_mul_f32_e32 v36, v38, v34
	v_mul_f32_e32 v34, 0xbfb8aa3b, v34
	v_rcp_f32_e32 v25, v25
	v_rcp_f32_e32 v9, v9
	v_rcp_f32_e32 v1, v1
	v_exp_f32_e32 v115, v115
	v_add_f32_e32 v66, 1.0, v66
	v_exp_f32_e32 v34, v34
	v_mul_f32_e32 v98, v100, v98
	v_mul_f32_e32 v100, v103, v99
	v_mul_f32_e32 v99, 0xbfb8aa3b, v99
	v_rcp_f32_e32 v66, v66
	v_mul_f32_e32 v17, v20, v17
	v_mul_f32_e32 v20, v22, v18
	v_mul_f32_e32 v18, 0xbfb8aa3b, v18
	v_exp_f32_e32 v99, v99
	v_add_f32_e32 v50, 1.0, v50
	v_exp_f32_e32 v18, v18
	v_mul_f32_e32 v121, v124, v121
	v_mul_f32_e32 v124, v126, v122
	v_mul_f32_e32 v122, 0xbfb8aa3b, v122
	v_mul_f32_e32 v105, v108, v105
	v_mul_f32_e32 v108, v110, v106
	v_mul_f32_e32 v106, 0xbfb8aa3b, v106
	v_mul_f32_e32 v89, v92, v89
	v_mul_f32_e32 v92, v94, v90
	v_mul_f32_e32 v90, 0xbfb8aa3b, v90
	v_mul_f32_e32 v82, v84, v82
	v_mul_f32_e32 v84, v87, v83
	v_mul_f32_e32 v83, 0xbfb8aa3b, v83
	v_mul_f32_e32 v73, v76, v73
	v_mul_f32_e32 v76, v78, v74
	v_mul_f32_e32 v74, 0xbfb8aa3b, v74
	v_mul_f32_e32 v57, v60, v57
	v_mul_f32_e32 v60, v62, v58
	v_mul_f32_e32 v58, 0xbfb8aa3b, v58
	v_rcp_f32_e32 v50, v50
	v_mul_f32_e32 v41, v44, v41
	v_mul_f32_e32 v44, v46, v42
	v_mul_f32_e32 v42, 0xbfb8aa3b, v42
	v_mul_f32_e32 v25, v28, v25
	v_mul_f32_e32 v28, v30, v26
	v_mul_f32_e32 v26, 0xbfb8aa3b, v26
	v_mul_f32_e32 v9, v12, v9
	v_mul_f32_e32 v12, v14, v10
	v_mul_f32_e32 v10, 0xbfb8aa3b, v10
	v_mul_f32_e32 v1, v4, v1
	v_mul_f32_e32 v4, v6, v2
	v_mul_f32_e32 v2, 0xbfb8aa3b, v2
	v_exp_f32_e32 v122, v122
	v_add_f32_e32 v115, 1.0, v115
	v_exp_f32_e32 v106, v106
	v_exp_f32_e32 v90, v90
	v_exp_f32_e32 v83, v83
	v_exp_f32_e32 v74, v74
	v_exp_f32_e32 v58, v58
	v_exp_f32_e32 v42, v42
	v_add_f32_e32 v34, 1.0, v34
	v_exp_f32_e32 v26, v26
	v_exp_f32_e32 v10, v10
	v_exp_f32_e32 v2, v2
	v_lshl_or_b32 v134, s46, 7, v138
	v_rcp_f32_e32 v115, v115
	v_mul_f32_e32 v66, v68, v66
	v_mul_f32_e32 v68, v71, v67
	v_mul_f32_e32 v67, 0xbfb8aa3b, v67
	v_rcp_f32_e32 v34, v34
	v_ashrrev_i32_e32 v135, 31, v134
	v_add_f32_e32 v99, 1.0, v99
	v_exp_f32_e32 v67, v67
	v_add_f32_e32 v18, 1.0, v18
	v_lshl_add_u32 v140, s48, 8, v136
	v_lshl_add_u64 v[134:135], v[134:135], 1, s[74:75]
	v_rcp_f32_e32 v99, v99
	v_mul_f32_e32 v50, v52, v50
	v_mul_f32_e32 v52, v55, v51
	v_mul_f32_e32 v51, 0xbfb8aa3b, v51
	v_rcp_f32_e32 v18, v18
	v_mad_i64_i32 v[142:143], s[26:27], v140, s33, v[134:135]
	v_add_f32_e32 v122, 1.0, v122
	v_cvt_pk_bf16_f32 v112, v112, v113
	v_add_f32_e32 v106, 1.0, v106
	v_add_f32_e32 v90, 1.0, v90
	v_add_f32_e32 v83, 1.0, v83
	v_add_f32_e32 v74, 1.0, v74
	v_add_f32_e32 v58, 1.0, v58
; __device__ __forceinline__ unsigned cvt_pk_bf16(float lo, float hi) { unsigned r; asm("v_cvt_pk_bf16_f32 %0, %1, %2" : "=v"(r) : "v"(lo), "v"(hi)); return r; }
; #define PG8_WAIT_V(n) asm volatile("s_waitcnt vmcnt(" #n ")" ::: "memory")
; #define PG8_BAR __builtin_amdgcn_s_barrier()
; template <class Epi>
; __device__ __forceinline__ void gemm_phase(LAS unsigned char* lds, const Gemm g, const StaticOrder S, const Epi E) {
;     ...
;         E(acc, cur, wr, wc, fr, fq);
;         if (!has_next) break;
; #pragma unroll
;         for (int a = 0; a < 2; ++a)
; #pragma unroll
;             for (int b = 0; b < 2; ++b)
; #pragma unroll
;                 for (int m = 0; m < 4; ++m)
; #pragma unroll
;                     for (int n = 0; n < 2; ++n) acc[a][b][m][n] = (f32x4){0.f, 0.f, 0.f, 0.f};
;         cur = nxt; cA = nA; cB = nB; ++ui;
;     }
;     PG8_WAIT_V(0);
;     if (wr == 0) PG8_BAR;
;     __device__ __forceinline__ void operator()(AccRef acc, const pg8::Unit& u, int wr, int wc, int fr, int fq) const {
;     ...
;             for (int m = 0; m < 4; ++m) { bf16_t* rowp = G + (size_t)(row0 + ai * 128 + m * 16) * FH + col0;
; #pragma unroll
;                 for (int bj = 0; bj < 2; ++bj) { const f32x4 gq = acc[ai][bj][m][0], uq = acc[ai][bj][m][1]; float v[4];
; #pragma unroll
;                     for (int i = 0; i < 4; ++i) v[i] = gq[i] * uq[i] * __builtin_amdgcn_rcpf(1.f + __builtin_amdgcn_exp2f(-gq[i] * LOG2E));
;                     u32x2 w; w.x = cvt_pk_bf16(v[0], v[1]); w.y = cvt_pk_bf16(v[2], v[3]);
;                     *(u32x2*)(rowp + bj * 64) = w; } }
	v_exp_f32_e32 v51, v51
	v_add_f32_e32 v42, 1.0, v42
	v_add_f32_e32 v26, 1.0, v26
	v_add_f32_e32 v10, 1.0, v10
	v_add_f32_e32 v2, 1.0, v2
	v_rcp_f32_e32 v122, v122
	v_mul_f32_e32 v115, v116, v115
	v_cvt_pk_bf16_f32 v113, v114, v115
	global_store_dwordx2 v[142:143], v[112:113], off offset:128
	v_or_b32_e32 v112, 16, v140
	v_rcp_f32_e32 v106, v106
	v_rcp_f32_e32 v90, v90
	v_rcp_f32_e32 v83, v83
	v_rcp_f32_e32 v74, v74
	v_rcp_f32_e32 v58, v58
	v_rcp_f32_e32 v42, v42
	v_mul_f32_e32 v34, v36, v34
	v_mul_f32_e32 v36, v39, v35
	v_mul_f32_e32 v35, 0xbfb8aa3b, v35
	v_rcp_f32_e32 v26, v26
	v_rcp_f32_e32 v10, v10
	v_rcp_f32_e32 v2, v2
	v_mad_i64_i32 v[112:113], s[26:27], v112, s33, v[134:135]
	v_cvt_pk_bf16_f32 v96, v96, v97
	v_add_f32_e32 v67, 1.0, v67
	v_exp_f32_e32 v35, v35
	v_mul_f32_e32 v99, v100, v99
	v_cvt_pk_bf16_f32 v97, v98, v99
	global_store_dwordx2 v[112:113], v[96:97], off offset:128
	v_or_b32_e32 v96, 32, v140
	v_rcp_f32_e32 v67, v67
	v_mul_f32_e32 v18, v20, v18
	v_mul_f32_e32 v20, v23, v19
	v_mul_f32_e32 v19, 0xbfb8aa3b, v19
	v_mad_i64_i32 v[96:97], s[26:27], v96, s33, v[134:135]
	v_cvt_pk_bf16_f32 v80, v80, v81
	v_add_f32_e32 v51, 1.0, v51
	v_exp_f32_e32 v19, v19
	v_mul_f32_e32 v122, v124, v122
	v_mul_f32_e32 v124, v127, v123
	v_mul_f32_e32 v123, 0xbfb8aa3b, v123
	v_mul_f32_e32 v106, v108, v106
	v_mul_f32_e32 v108, v111, v107
	v_mul_f32_e32 v107, 0xbfb8aa3b, v107
	v_mul_f32_e32 v90, v92, v90
	v_mul_f32_e32 v92, v95, v91
	v_mul_f32_e32 v91, 0xbfb8aa3b, v91
	v_mul_f32_e32 v83, v84, v83
	v_cvt_pk_bf16_f32 v81, v82, v83
	global_store_dwordx2 v[96:97], v[80:81], off offset:128
	v_or_b32_e32 v80, 48, v140
	v_mul_f32_e32 v74, v76, v74
	v_mul_f32_e32 v76, v79, v75
	v_mul_f32_e32 v75, 0xbfb8aa3b, v75
	v_mul_f32_e32 v58, v60, v58
	v_mul_f32_e32 v60, v63, v59
	v_mul_f32_e32 v59, 0xbfb8aa3b, v59
	v_rcp_f32_e32 v51, v51
	v_mul_f32_e32 v42, v44, v42
	v_mul_f32_e32 v44, v47, v43
	v_mul_f32_e32 v43, 0xbfb8aa3b, v43
	v_mul_f32_e32 v26, v28, v26
	v_mul_f32_e32 v28, v31, v27
	v_mul_f32_e32 v27, 0xbfb8aa3b, v27
	v_mul_f32_e32 v10, v12, v10
	v_mul_f32_e32 v12, v15, v11
	v_mul_f32_e32 v11, 0xbfb8aa3b, v11
	v_mul_f32_e32 v2, v4, v2
	v_mul_f32_e32 v4, v7, v3
	v_mul_f32_e32 v3, 0xbfb8aa3b, v3
	v_exp_f32_e32 v123, v123
	v_exp_f32_e32 v107, v107
	v_exp_f32_e32 v91, v91
	v_mad_i64_i32 v[80:81], s[26:27], v80, s33, v[134:135]
	v_exp_f32_e32 v75, v75
	v_cvt_pk_bf16_f32 v64, v64, v65
	v_exp_f32_e32 v59, v59
	v_exp_f32_e32 v43, v43
	v_add_f32_e32 v35, 1.0, v35
	v_exp_f32_e32 v27, v27
	v_exp_f32_e32 v11, v11
	v_exp_f32_e32 v3, v3
	v_mul_f32_e32 v67, v68, v67
	v_cvt_pk_bf16_f32 v65, v66, v67
	global_store_dwordx2 v[80:81], v[64:65], off offset:128
	v_add_u32_e32 v64, 0x80, v140
	v_rcp_f32_e32 v35, v35
	v_mad_i64_i32 v[64:65], s[26:27], v64, s33, v[134:135]
	v_cvt_pk_bf16_f32 v48, v48, v49
	v_add_f32_e32 v19, 1.0, v19
	v_mul_f32_e32 v51, v52, v51
	v_cvt_pk_bf16_f32 v49, v50, v51
	global_store_dwordx2 v[64:65], v[48:49], off offset:128
	v_add_u32_e32 v48, 0x90, v140
	v_rcp_f32_e32 v19, v19
	v_add_f32_e32 v123, 1.0, v123
	v_add_f32_e32 v107, 1.0, v107
	v_add_f32_e32 v91, 1.0, v91
	v_add_f32_e32 v75, 1.0, v75
	v_add_f32_e32 v59, 1.0, v59
	v_mad_i64_i32 v[48:49], s[26:27], v48, s33, v[134:135]
	v_add_f32_e32 v43, 1.0, v43
	v_cvt_pk_bf16_f32 v32, v32, v33
	v_add_f32_e32 v27, 1.0, v27
	v_add_f32_e32 v11, 1.0, v11
	v_add_f32_e32 v3, 1.0, v3
	v_rcp_f32_e32 v123, v123
	v_rcp_f32_e32 v107, v107
	v_rcp_f32_e32 v91, v91
	v_rcp_f32_e32 v75, v75
	v_rcp_f32_e32 v59, v59
	v_rcp_f32_e32 v43, v43
	v_mul_f32_e32 v35, v36, v35
	v_cvt_pk_bf16_f32 v33, v34, v35
	global_store_dwordx2 v[48:49], v[32:33], off offset:128
	v_add_u32_e32 v32, 0xa0, v140
	v_rcp_f32_e32 v27, v27
	v_rcp_f32_e32 v11, v11
	v_rcp_f32_e32 v3, v3
	v_mad_i64_i32 v[32:33], s[26:27], v32, s33, v[134:135]
	v_cvt_pk_bf16_f32 v16, v16, v17
	v_mul_f32_e32 v19, v20, v19
	v_cvt_pk_bf16_f32 v17, v18, v19
	global_store_dwordx2 v[32:33], v[16:17], off offset:128
	v_add_u32_e32 v16, 0xb0, v140
	v_mad_i64_i32 v[16:17], s[26:27], v16, s33, v[134:135]
	s_and_b64 vcc, exec, s[38:39]
	s_mov_b32 s46, s0
	s_mov_b32 s48, s2
	s_mov_b64 s[52:53], s[44:45]
	s_mov_b64 s[50:51], s[42:43]
	v_readlane_b32 s64, v255, 53
	v_mul_f32_e32 v123, v124, v123
	v_cvt_pk_bf16_f32 v120, v120, v121
	v_cvt_pk_bf16_f32 v121, v122, v123
	global_store_dwordx2 v[142:143], v[120:121], off
	v_mul_f32_e32 v107, v108, v107
	v_cvt_pk_bf16_f32 v104, v104, v105
	v_cvt_pk_bf16_f32 v105, v106, v107
	global_store_dwordx2 v[112:113], v[104:105], off
	v_mul_f32_e32 v91, v92, v91
	v_cvt_pk_bf16_f32 v88, v88, v89
	v_cvt_pk_bf16_f32 v89, v90, v91
	global_store_dwordx2 v[96:97], v[88:89], off
	v_mul_f32_e32 v75, v76, v75
	v_cvt_pk_bf16_f32 v72, v72, v73
	v_cvt_pk_bf16_f32 v73, v74, v75
	global_store_dwordx2 v[80:81], v[72:73], off
	v_mul_f32_e32 v59, v60, v59
	v_cvt_pk_bf16_f32 v56, v56, v57
	v_cvt_pk_bf16_f32 v57, v58, v59
	global_store_dwordx2 v[64:65], v[56:57], off
	v_mul_f32_e32 v43, v44, v43
	v_cvt_pk_bf16_f32 v40, v40, v41
	v_cvt_pk_bf16_f32 v41, v42, v43
	global_store_dwordx2 v[48:49], v[40:41], off
	v_mul_f32_e32 v27, v28, v27
	v_cvt_pk_bf16_f32 v24, v24, v25
	v_cvt_pk_bf16_f32 v25, v26, v27
	global_store_dwordx2 v[32:33], v[24:25], off
	v_mul_f32_e32 v11, v12, v11
	v_cvt_pk_bf16_f32 v8, v8, v9
	v_cvt_pk_bf16_f32 v9, v10, v11
	global_store_dwordx2 v[16:17], v[8:9], off
	v_mul_f32_e32 v3, v4, v3
	v_cvt_pk_bf16_f32 v0, v0, v1
	v_cvt_pk_bf16_f32 v1, v2, v3
	global_store_dwordx2 v[16:17], v[0:1], off offset:128
	v_readlane_b32 s65, v255, 54
	s_cbranch_vccz .LBB0_3716
	s_waitcnt vmcnt(0)
	s_cmpk_gt_u32 s7, 0xff
	s_cbranch_scc1 .LBB0_3727
	s_barrier

; #define PG8_STAGE(bufoff, gbase, voff) do { _Pragma("unroll") for (int _i = 0; _i < 2; ++_i) \
;         __builtin_amdgcn_global_load_lds((const unsigned*)((const char*)(gbase) + (voff)[_i]), (LAS unsigned*)(lds + (bufoff) + ldsw + _i * 8192), 16, 0, 0); } while (0)
; #define PG8_LDA(dst, b, h) do { _Pragma("unroll") for (int m = 0; m < 4; ++m) _Pragma("unroll") for (int k = 0; k < 2; ++k) dst[m][k] = *(const LAS bf16x8*)(lds + PG8_SA(b, h) + aoff + m * 2048 + k * 1024); } while (0)
; #define PG8_LDB(dst, b, h) do { _Pragma("unroll") for (int n = 0; n < 2; ++n) _Pragma("unroll") for (int k = 0; k < 2; ++k) dst[n][k] = *(const LAS bf16x8*)(lds + PG8_SB(b, h) + boff + n * 2048 + k * 1024); } while (0)
; #define PG8_MMA(ai, bj, At, Bt) do { __builtin_amdgcn_s_setprio(1); _Pragma("unroll") for (int m = 0; m < 4; ++m) _Pragma("unroll") for (int n = 0; n < 2; ++n) _Pragma("unroll") for (int k = 0; k < 2; ++k) \
;         acc[ai][bj][m][n] = __builtin_amdgcn_mfma_f32_16x16x32_bf16(Bt[n][k], At[m][k], acc[ai][bj][m][n], 0, 0, 0); __builtin_amdgcn_s_setprio(0); } while (0)
; #define PG8_WAIT_L(n) asm volatile("s_waitcnt lgkmcnt(" #n ")" ::: "memory")
; #define PG8_BAR __builtin_amdgcn_s_barrier()
; #define PG8_SCHED __builtin_amdgcn_sched_barrier(0)
; template <class Epi>
; __device__ __forceinline__ void gemm_phase(LAS unsigned char* lds, const Gemm g, const StaticOrder S, const Epi E) {
;     ...
;         for (int t = 0; t < nt; t += 2) {
;             const bool last = (t == nt - 2);
;             const char* a1 = cA + (size_t)(t + 1) * kstep;
;             const char* a2 = last ? nA : cA + (size_t)(t + 2) * kstep; const char* b2 = last ? nB : cB + (size_t)(t + 2) * kstep;
;             const char* a3 = a2 + kstep; const char* b3 = b2 + kstep;
;             PG8_LDB(B0, 0, 0); PG8_SCHED; PG8_LDA(At, 0, 0); PG8_STAGE(PG8_SA(1, 1), a1 + hstep, voffA);
;             PG8_WAIT_L(8); PG8_BAR; PG8_WAIT_L(0); PG8_MMA(0, 0, At, B0); PG8_BAR; PG8_SCHED;
;             PG8_LDB(B1, 0, 1); PG8_STAGE(PG8_SB(0, 0), b2, voffA);
;             PG8_BAR; PG8_WAIT_L(0); PG8_MMA(0, 1, At, B1); PG8_BAR;
;             PG8_LDA(At, 0, 1); PG8_STAGE(PG8_SA(0, 0), a2, voffA);
;             PG8_BAR; PG8_WAIT_L(0); PG8_MMA(1, 0, At, B0); PG8_BAR; PG8_SCHED;
.LBB0_3919:
	s_add_i32 vcc_lo, s52, 2
	s_add_u32 s50, s38, 0x100
	s_addc_u32 s51, s39, 0
	s_add_i32 s14, 0, 0x10000
	v_add_u32_e32 v140, s14, v228
	ds_read_b128 v[128:131], v140
	ds_read_b128 v[132:135], v140 offset:1024
	ds_read_b128 v[136:139], v140 offset:2048
	ds_read_b128 v[140:143], v140 offset:3072
	s_cmp_eq_u32 s43, s52
	s_cselect_b32 s52, s48, s68
	s_cselect_b32 s55, s45, s51
	s_cselect_b32 s54, s44, s50
	s_cselect_b32 s53, s49, s69
	v_lshl_add_u64 v[200:201], s[38:39], 0, v[196:197]
	s_add_i32 m0, s25, 0xc000
	ds_read_b128 v[144:147], v230
	ds_read_b128 v[148:151], v230 offset:1024
	ds_read_b128 v[152:155], v230 offset:2048
	ds_read_b128 v[156:159], v230 offset:3072
	ds_read_b128 v[160:163], v230 offset:4096
	ds_read_b128 v[164:167], v230 offset:5120
	ds_read_b128 v[168:171], v230 offset:6144
	ds_read_b128 v[172:175], v230 offset:7168
	global_load_lds_dwordx4 v[200:201], off
	v_lshl_add_u64 v[200:201], s[38:39], 0, v[198:199]
	s_add_i32 m0, s25, 0xe000
	s_nop 0
	global_load_lds_dwordx4 v[200:201], off
	s_waitcnt lgkmcnt(8)
	s_barrier
	s_waitcnt lgkmcnt(0)
	s_setprio 1
	v_mfma_f32_16x16x32_bf16 v[124:127], v[128:131], v[144:147], v[124:127]
	v_mfma_f32_16x16x32_bf16 v[120:123], v[136:139], v[144:147], v[120:123]
	v_mfma_f32_16x16x32_bf16 v[112:115], v[128:131], v[152:155], v[112:115]
	v_mfma_f32_16x16x32_bf16 v[104:107], v[136:139], v[152:155], v[104:107]
	v_mfma_f32_16x16x32_bf16 v[92:95], v[128:131], v[160:163], v[92:95]
	v_mfma_f32_16x16x32_bf16 v[88:91], v[136:139], v[160:163], v[88:91]
	v_mfma_f32_16x16x32_bf16 v[80:83], v[128:131], v[168:171], v[80:83]
	v_mfma_f32_16x16x32_bf16 v[72:75], v[136:139], v[168:171], v[72:75]
	v_mfma_f32_16x16x32_bf16 v[124:127], v[132:135], v[148:151], v[124:127]
	v_mfma_f32_16x16x32_bf16 v[120:123], v[140:143], v[148:151], v[120:123]
	v_mfma_f32_16x16x32_bf16 v[112:115], v[132:135], v[156:159], v[112:115]
	v_mfma_f32_16x16x32_bf16 v[104:107], v[140:143], v[156:159], v[104:107]
	v_mfma_f32_16x16x32_bf16 v[92:95], v[132:135], v[164:167], v[92:95]
	v_mfma_f32_16x16x32_bf16 v[88:91], v[140:143], v[164:167], v[88:91]
	v_mfma_f32_16x16x32_bf16 v[80:83], v[132:135], v[172:175], v[80:83]
	v_mfma_f32_16x16x32_bf16 v[72:75], v[140:143], v[172:175], v[72:75]
	s_setprio 0
	s_barrier
	s_add_i32 s38, 0, 0x14000
	s_add_i32 s14, s14, s24
	v_add_u32_e32 v220, s38, v228
	v_lshl_add_u64 v[232:233], s[52:53], 0, v[178:179]
	s_mov_b32 m0, s14
	ds_read_b128 v[200:203], v220
	ds_read_b128 v[204:207], v220 offset:1024
	ds_read_b128 v[208:211], v220 offset:2048
	ds_read_b128 v[220:223], v220 offset:3072
	global_load_lds_dwordx4 v[232:233], off
	v_lshl_add_u64 v[234:235], s[52:53], 0, v[194:195]
	s_add_i32 m0, s14, 0x2000
	s_nop 0
	global_load_lds_dwordx4 v[234:235], off
	s_barrier
	s_waitcnt lgkmcnt(0)
	s_setprio 1
	v_mfma_f32_16x16x32_bf16 v[116:119], v[200:203], v[144:147], v[116:119]
	v_mfma_f32_16x16x32_bf16 v[108:111], v[208:211], v[144:147], v[108:111]
	v_mfma_f32_16x16x32_bf16 v[100:103], v[200:203], v[152:155], v[100:103]
	v_mfma_f32_16x16x32_bf16 v[96:99], v[208:211], v[152:155], v[96:99]
	v_mfma_f32_16x16x32_bf16 v[84:87], v[200:203], v[160:163], v[84:87]
	v_mfma_f32_16x16x32_bf16 v[76:79], v[208:211], v[160:163], v[76:79]
	v_mfma_f32_16x16x32_bf16 v[68:71], v[200:203], v[168:171], v[68:71]
	v_mfma_f32_16x16x32_bf16 v[64:67], v[208:211], v[168:171], v[64:67]
	v_mfma_f32_16x16x32_bf16 v[116:119], v[204:207], v[148:151], v[116:119]
	v_mfma_f32_16x16x32_bf16 v[108:111], v[220:223], v[148:151], v[108:111]
	v_mfma_f32_16x16x32_bf16 v[100:103], v[204:207], v[156:159], v[100:103]
	v_mfma_f32_16x16x32_bf16 v[96:99], v[220:223], v[156:159], v[96:99]
	v_mfma_f32_16x16x32_bf16 v[84:87], v[204:207], v[164:167], v[84:87]
	v_mfma_f32_16x16x32_bf16 v[76:79], v[220:223], v[164:167], v[76:79]
	v_mfma_f32_16x16x32_bf16 v[68:71], v[204:207], v[172:175], v[68:71]
	v_mfma_f32_16x16x32_bf16 v[64:67], v[220:223], v[172:175], v[64:67]
	s_setprio 0
	s_barrier
	s_mov_b32 m0, s25
	v_lshl_add_u64 v[236:237], s[54:55], 0, v[178:179]
	ds_read_b128 v[144:147], v230 offset:16384
	ds_read_b128 v[148:151], v230 offset:17408
	ds_read_b128 v[152:155], v230 offset:18432
	ds_read_b128 v[156:159], v230 offset:19456
	ds_read_b128 v[160:163], v230 offset:20480
	ds_read_b128 v[164:167], v230 offset:21504
	ds_read_b128 v[168:171], v230 offset:22528
	ds_read_b128 v[172:175], v230 offset:23552
	global_load_lds_dwordx4 v[236:237], off
	v_lshl_add_u64 v[238:239], s[54:55], 0, v[194:195]
	s_mov_b32 m0, s56
	s_nop 0
	global_load_lds_dwordx4 v[238:239], off
	s_barrier
	s_waitcnt lgkmcnt(0)
	s_setprio 1
	v_mfma_f32_16x16x32_bf16 v[60:63], v[128:131], v[144:147], v[60:63]
	v_mfma_f32_16x16x32_bf16 v[56:59], v[136:139], v[144:147], v[56:59]
	v_mfma_f32_16x16x32_bf16 v[48:51], v[128:131], v[152:155], v[48:51]
	v_mfma_f32_16x16x32_bf16 v[40:43], v[136:139], v[152:155], v[40:43]
	v_mfma_f32_16x16x32_bf16 v[28:31], v[128:131], v[160:163], v[28:31]
	v_mfma_f32_16x16x32_bf16 v[24:27], v[136:139], v[160:163], v[24:27]
	v_mfma_f32_16x16x32_bf16 v[16:19], v[128:131], v[168:171], v[16:19]
	v_mfma_f32_16x16x32_bf16 v[8:11], v[136:139], v[168:171], v[8:11]
	v_mfma_f32_16x16x32_bf16 v[60:63], v[132:135], v[148:151], v[60:63]
	v_mfma_f32_16x16x32_bf16 v[56:59], v[140:143], v[148:151], v[56:59]
	v_mfma_f32_16x16x32_bf16 v[48:51], v[132:135], v[156:159], v[48:51]
	v_mfma_f32_16x16x32_bf16 v[40:43], v[140:143], v[156:159], v[40:43]
	v_mfma_f32_16x16x32_bf16 v[28:31], v[132:135], v[164:167], v[28:31]
	v_mfma_f32_16x16x32_bf16 v[24:27], v[140:143], v[164:167], v[24:27]
	v_mfma_f32_16x16x32_bf16 v[16:19], v[132:135], v[172:175], v[16:19]
	v_mfma_f32_16x16x32_bf16 v[8:11], v[140:143], v[172:175], v[8:11]
	s_setprio 0
	s_barrier
; #define PG8_STAGE(bufoff, gbase, voff) do { _Pragma("unroll") for (int _i = 0; _i < 2; ++_i) \
;         __builtin_amdgcn_global_load_lds((const unsigned*)((const char*)(gbase) + (voff)[_i]), (LAS unsigned*)(lds + (bufoff) + ldsw + _i * 8192), 16, 0, 0); } while (0)
; #define PG8_LDA(dst, b, h) do { _Pragma("unroll") for (int m = 0; m < 4; ++m) _Pragma("unroll") for (int k = 0; k < 2; ++k) dst[m][k] = *(const LAS bf16x8*)(lds + PG8_SA(b, h) + aoff + m * 2048 + k * 1024); } while (0)
; #define PG8_LDB(dst, b, h) do { _Pragma("unroll") for (int n = 0; n < 2; ++n) _Pragma("unroll") for (int k = 0; k < 2; ++k) dst[n][k] = *(const LAS bf16x8*)(lds + PG8_SB(b, h) + boff + n * 2048 + k * 1024); } while (0)
; #define PG8_MMA(ai, bj, At, Bt) do { __builtin_amdgcn_s_setprio(1); _Pragma("unroll") for (int m = 0; m < 4; ++m) _Pragma("unroll") for (int n = 0; n < 2; ++n) _Pragma("unroll") for (int k = 0; k < 2; ++k) \
;         acc[ai][bj][m][n] = __builtin_amdgcn_mfma_f32_16x16x32_bf16(Bt[n][k], At[m][k], acc[ai][bj][m][n], 0, 0, 0); __builtin_amdgcn_s_setprio(0); } while (0)
; #define PG8_WAIT_V(n) asm volatile("s_waitcnt vmcnt(" #n ")" ::: "memory")
; #define PG8_WAIT_L(n) asm volatile("s_waitcnt lgkmcnt(" #n ")" ::: "memory")
; #define PG8_BAR __builtin_amdgcn_s_barrier()
; #define PG8_SCHED __builtin_amdgcn_sched_barrier(0)
; template <class Epi>
; __device__ __forceinline__ void gemm_phase(LAS unsigned char* lds, const Gemm g, const StaticOrder S, const Epi E) {
;     ...
;             PG8_STAGE(PG8_SB(0, 1), b2 + hstep, voffA);
;             PG8_WAIT_V(6); PG8_BAR; PG8_MMA(1, 1, At, B1); PG8_BAR;
;             PG8_LDB(B0, 1, 0); PG8_SCHED; PG8_LDA(At, 1, 0); PG8_STAGE(PG8_SA(0, 1), a2 + hstep, voffA);
;             PG8_WAIT_L(8); PG8_BAR; PG8_WAIT_L(0); PG8_MMA(0, 0, At, B0); PG8_BAR; PG8_SCHED;
;             PG8_LDB(B1, 1, 1); PG8_STAGE(PG8_SB(1, 0), b3, voffA);
	s_add_u32 s30, s52, 0x158000
	s_addc_u32 s31, s53, 0
	s_add_i32 s14, s38, s24
	v_lshl_add_u64 v[128:129], s[30:31], 0, v[178:179]
	s_mov_b32 m0, s14
	s_nop 0
	global_load_lds_dwordx4 v[128:129], off
	v_lshl_add_u64 v[128:129], s[30:31], 0, v[194:195]
	s_add_i32 m0, s14, 0x2000
	s_nop 0
	global_load_lds_dwordx4 v[128:129], off
	s_waitcnt vmcnt(6)
	s_barrier
	s_setprio 1
	v_mfma_f32_16x16x32_bf16 v[52:55], v[200:203], v[144:147], v[52:55]
	v_mfma_f32_16x16x32_bf16 v[44:47], v[208:211], v[144:147], v[44:47]
	v_mfma_f32_16x16x32_bf16 v[36:39], v[200:203], v[152:155], v[36:39]
	v_mfma_f32_16x16x32_bf16 v[32:35], v[208:211], v[152:155], v[32:35]
	v_mfma_f32_16x16x32_bf16 v[20:23], v[200:203], v[160:163], v[20:23]
	v_mfma_f32_16x16x32_bf16 v[12:15], v[208:211], v[160:163], v[12:15]
	v_mfma_f32_16x16x32_bf16 v[4:7], v[200:203], v[168:171], v[4:7]
	v_mfma_f32_16x16x32_bf16 v[0:3], v[208:211], v[168:171], v[0:3]
	v_mfma_f32_16x16x32_bf16 v[52:55], v[204:207], v[148:151], v[52:55]
	v_mfma_f32_16x16x32_bf16 v[44:47], v[220:223], v[148:151], v[44:47]
	v_mfma_f32_16x16x32_bf16 v[36:39], v[204:207], v[156:159], v[36:39]
	v_mfma_f32_16x16x32_bf16 v[32:35], v[220:223], v[156:159], v[32:35]
	v_mfma_f32_16x16x32_bf16 v[20:23], v[204:207], v[164:167], v[20:23]
	v_mfma_f32_16x16x32_bf16 v[12:15], v[220:223], v[164:167], v[12:15]
	v_mfma_f32_16x16x32_bf16 v[4:7], v[204:207], v[172:175], v[4:7]
	v_mfma_f32_16x16x32_bf16 v[0:3], v[220:223], v[172:175], v[0:3]
	s_setprio 0
	s_barrier
	s_add_i32 s14, 0, 0x18000
	v_add_u32_e32 v140, s14, v228
	ds_read_b128 v[128:131], v140
	ds_read_b128 v[132:135], v140 offset:1024
	ds_read_b128 v[136:139], v140 offset:2048
	ds_read_b128 v[140:143], v140 offset:3072
	s_add_u32 s30, s54, 0x158000
	s_addc_u32 s31, s55, 0
	s_mov_b32 m0, s57
	v_lshl_add_u64 v[200:201], s[30:31], 0, v[178:179]
	ds_read_b128 v[144:147], v230 offset:32768
	ds_read_b128 v[148:151], v230 offset:33792
	ds_read_b128 v[152:155], v230 offset:34816
	ds_read_b128 v[156:159], v230 offset:35840
	ds_read_b128 v[160:163], v230 offset:36864
	ds_read_b128 v[164:167], v230 offset:37888
	ds_read_b128 v[168:171], v230 offset:38912
	ds_read_b128 v[172:175], v230 offset:39936
	global_load_lds_dwordx4 v[200:201], off
	v_lshl_add_u64 v[200:201], s[30:31], 0, v[194:195]
	s_mov_b32 m0, s58
	s_nop 0
	global_load_lds_dwordx4 v[200:201], off
	s_waitcnt lgkmcnt(8)
	s_barrier
	s_waitcnt lgkmcnt(0)
	s_setprio 1
	v_mfma_f32_16x16x32_bf16 v[124:127], v[128:131], v[144:147], v[124:127]
	v_mfma_f32_16x16x32_bf16 v[120:123], v[136:139], v[144:147], v[120:123]
	v_mfma_f32_16x16x32_bf16 v[112:115], v[128:131], v[152:155], v[112:115]
	v_mfma_f32_16x16x32_bf16 v[104:107], v[136:139], v[152:155], v[104:107]
	v_mfma_f32_16x16x32_bf16 v[92:95], v[128:131], v[160:163], v[92:95]
	v_mfma_f32_16x16x32_bf16 v[88:91], v[136:139], v[160:163], v[88:91]
	v_mfma_f32_16x16x32_bf16 v[80:83], v[128:131], v[168:171], v[80:83]
	v_mfma_f32_16x16x32_bf16 v[72:75], v[136:139], v[168:171], v[72:75]
	v_mfma_f32_16x16x32_bf16 v[124:127], v[132:135], v[148:151], v[124:127]
	v_mfma_f32_16x16x32_bf16 v[120:123], v[140:143], v[148:151], v[120:123]
	v_mfma_f32_16x16x32_bf16 v[112:115], v[132:135], v[156:159], v[112:115]
	v_mfma_f32_16x16x32_bf16 v[104:107], v[140:143], v[156:159], v[104:107]
	v_mfma_f32_16x16x32_bf16 v[92:95], v[132:135], v[164:167], v[92:95]
	v_mfma_f32_16x16x32_bf16 v[88:91], v[140:143], v[164:167], v[88:91]
	v_mfma_f32_16x16x32_bf16 v[80:83], v[132:135], v[172:175], v[80:83]
	v_mfma_f32_16x16x32_bf16 v[72:75], v[140:143], v[172:175], v[72:75]
	s_setprio 0
	s_barrier
	s_add_i32 s38, 0, 0x1c000
	s_add_i32 s14, s14, s24
	v_add_u32_e32 v220, s38, v228
	v_lshl_add_u64 v[232:233], v[232:233], 0, s[34:35]
	s_mov_b32 m0, s14
	ds_read_b128 v[200:203], v220
	ds_read_b128 v[204:207], v220 offset:1024
	ds_read_b128 v[208:211], v220 offset:2048
	ds_read_b128 v[220:223], v220 offset:3072
	global_load_lds_dwordx4 v[232:233], off
	v_lshl_add_u64 v[232:233], v[234:235], 0, s[34:35]
	s_add_i32 m0, s14, 0x2000
	s_nop 0
	global_load_lds_dwordx4 v[232:233], off
	s_barrier
; #define PG8_STAGE(bufoff, gbase, voff) do { _Pragma("unroll") for (int _i = 0; _i < 2; ++_i) \
;         __builtin_amdgcn_global_load_lds((const unsigned*)((const char*)(gbase) + (voff)[_i]), (LAS unsigned*)(lds + (bufoff) + ldsw + _i * 8192), 16, 0, 0); } while (0)
; #define PG8_LDA(dst, b, h) do { _Pragma("unroll") for (int m = 0; m < 4; ++m) _Pragma("unroll") for (int k = 0; k < 2; ++k) dst[m][k] = *(const LAS bf16x8*)(lds + PG8_SA(b, h) + aoff + m * 2048 + k * 1024); } while (0)
; #define PG8_MMA(ai, bj, At, Bt) do { __builtin_amdgcn_s_setprio(1); _Pragma("unroll") for (int m = 0; m < 4; ++m) _Pragma("unroll") for (int n = 0; n < 2; ++n) _Pragma("unroll") for (int k = 0; k < 2; ++k) \
;         acc[ai][bj][m][n] = __builtin_amdgcn_mfma_f32_16x16x32_bf16(Bt[n][k], At[m][k], acc[ai][bj][m][n], 0, 0, 0); __builtin_amdgcn_s_setprio(0); } while (0)
; #define PG8_WAIT_V(n) asm volatile("s_waitcnt vmcnt(" #n ")" ::: "memory")
; #define PG8_WAIT_L(n) asm volatile("s_waitcnt lgkmcnt(" #n ")" ::: "memory")
; #define PG8_BAR __builtin_amdgcn_s_barrier()
; #define PG8_SCHED __builtin_amdgcn_sched_barrier(0)
; template <class Epi>
; __device__ __forceinline__ void gemm_phase(LAS unsigned char* lds, const Gemm g, const StaticOrder S, const Epi E) {
;     ...
;             PG8_BAR; PG8_WAIT_L(0); PG8_MMA(0, 1, At, B1); PG8_BAR;
;             PG8_LDA(At, 1, 1); PG8_STAGE(PG8_SA(1, 0), a3, voffA);
;             PG8_BAR; PG8_WAIT_L(0); PG8_MMA(1, 0, At, B0); PG8_BAR; PG8_SCHED;
;             PG8_STAGE(PG8_SB(1, 1), b3 + hstep, voffA);
;             PG8_WAIT_V(6); PG8_BAR; PG8_MMA(1, 1, At, B1); PG8_BAR;
;         }
;     __device__ __forceinline__ void operator()(AccRef acc, const pg8::Unit& u, int wr, int wc, int fr, int fq) const {
;         const int row0 = u.pm * 256 + wr * 64 + fr, col0 = u.pn * 256 + wc * 32 + 4 * fq;
;         const int v = u.pm < 32 ? (u.pm >> 3) : 4;
;         f32x4 gv[2][2];
; #pragma unroll
;         for (int bj = 0; bj < 2; ++bj)
; #pragma unroll
;             for (int n = 0; n < 2; ++n) gv[bj][n] = *(const f32x4*)(gate + (size_t)v * MODW + col0 + bj * 128 + n * 16) * coef;
	s_waitcnt lgkmcnt(0)
	s_setprio 1
	v_mfma_f32_16x16x32_bf16 v[116:119], v[200:203], v[144:147], v[116:119]
	v_mfma_f32_16x16x32_bf16 v[108:111], v[208:211], v[144:147], v[108:111]
	v_mfma_f32_16x16x32_bf16 v[100:103], v[200:203], v[152:155], v[100:103]
	v_mfma_f32_16x16x32_bf16 v[96:99], v[208:211], v[152:155], v[96:99]
	v_mfma_f32_16x16x32_bf16 v[84:87], v[200:203], v[160:163], v[84:87]
	v_mfma_f32_16x16x32_bf16 v[76:79], v[208:211], v[160:163], v[76:79]
	v_mfma_f32_16x16x32_bf16 v[68:71], v[200:203], v[168:171], v[68:71]
	v_mfma_f32_16x16x32_bf16 v[64:67], v[208:211], v[168:171], v[64:67]
	v_mfma_f32_16x16x32_bf16 v[116:119], v[204:207], v[148:151], v[116:119]
	v_mfma_f32_16x16x32_bf16 v[108:111], v[220:223], v[148:151], v[108:111]
	v_mfma_f32_16x16x32_bf16 v[100:103], v[204:207], v[156:159], v[100:103]
	v_mfma_f32_16x16x32_bf16 v[96:99], v[220:223], v[156:159], v[96:99]
	v_mfma_f32_16x16x32_bf16 v[84:87], v[204:207], v[164:167], v[84:87]
	v_mfma_f32_16x16x32_bf16 v[76:79], v[220:223], v[164:167], v[76:79]
	v_mfma_f32_16x16x32_bf16 v[68:71], v[204:207], v[172:175], v[68:71]
	v_mfma_f32_16x16x32_bf16 v[64:67], v[220:223], v[172:175], v[64:67]
	s_setprio 0
	s_barrier
	s_mov_b32 m0, s61
	v_lshl_add_u64 v[232:233], v[236:237], 0, s[34:35]
	ds_read_b128 v[144:147], v230 offset:49152
	ds_read_b128 v[148:151], v230 offset:50176
	ds_read_b128 v[152:155], v230 offset:51200
	ds_read_b128 v[156:159], v230 offset:52224
	ds_read_b128 v[160:163], v230 offset:53248
	ds_read_b128 v[164:167], v230 offset:54272
	ds_read_b128 v[168:171], v230 offset:55296
	ds_read_b128 v[172:175], v230 offset:56320
	global_load_lds_dwordx4 v[232:233], off
	v_lshl_add_u64 v[232:233], v[238:239], 0, s[34:35]
	s_mov_b32 m0, s62
	s_nop 0
	global_load_lds_dwordx4 v[232:233], off
	s_barrier
	s_waitcnt lgkmcnt(0)
	s_setprio 1
	v_mfma_f32_16x16x32_bf16 v[60:63], v[128:131], v[144:147], v[60:63]
	v_mfma_f32_16x16x32_bf16 v[56:59], v[136:139], v[144:147], v[56:59]
	v_mfma_f32_16x16x32_bf16 v[48:51], v[128:131], v[152:155], v[48:51]
	v_mfma_f32_16x16x32_bf16 v[40:43], v[136:139], v[152:155], v[40:43]
	v_mfma_f32_16x16x32_bf16 v[28:31], v[128:131], v[160:163], v[28:31]
	v_mfma_f32_16x16x32_bf16 v[24:27], v[136:139], v[160:163], v[24:27]
	v_mfma_f32_16x16x32_bf16 v[16:19], v[128:131], v[168:171], v[16:19]
	v_mfma_f32_16x16x32_bf16 v[8:11], v[136:139], v[168:171], v[8:11]
	v_mfma_f32_16x16x32_bf16 v[60:63], v[132:135], v[148:151], v[60:63]
	v_mfma_f32_16x16x32_bf16 v[56:59], v[140:143], v[148:151], v[56:59]
	v_mfma_f32_16x16x32_bf16 v[48:51], v[132:135], v[156:159], v[48:51]
	v_mfma_f32_16x16x32_bf16 v[40:43], v[140:143], v[156:159], v[40:43]
	v_mfma_f32_16x16x32_bf16 v[28:31], v[132:135], v[164:167], v[28:31]
	v_mfma_f32_16x16x32_bf16 v[24:27], v[140:143], v[164:167], v[24:27]
	v_mfma_f32_16x16x32_bf16 v[16:19], v[132:135], v[172:175], v[16:19]
	v_mfma_f32_16x16x32_bf16 v[8:11], v[140:143], v[172:175], v[8:11]
	s_setprio 0
	s_barrier
	s_add_u32 s30, s52, 0x158080
	s_addc_u32 s31, s53, 0
	s_add_i32 s14, s38, s24
	v_lshl_add_u64 v[128:129], s[30:31], 0, v[178:179]
	s_mov_b32 m0, s14
	s_nop 0
	global_load_lds_dwordx4 v[128:129], off
	v_lshl_add_u64 v[128:129], s[30:31], 0, v[194:195]
	s_add_i32 m0, s14, 0x2000
	s_nop 0
	global_load_lds_dwordx4 v[128:129], off
	s_waitcnt vmcnt(6)
	s_barrier
	s_setprio 1
	v_mfma_f32_16x16x32_bf16 v[52:55], v[200:203], v[144:147], v[52:55]
	v_mfma_f32_16x16x32_bf16 v[44:47], v[208:211], v[144:147], v[44:47]
	v_mfma_f32_16x16x32_bf16 v[36:39], v[200:203], v[152:155], v[36:39]
	v_mfma_f32_16x16x32_bf16 v[32:35], v[208:211], v[152:155], v[32:35]
	v_mfma_f32_16x16x32_bf16 v[20:23], v[200:203], v[160:163], v[20:23]
	v_mfma_f32_16x16x32_bf16 v[12:15], v[208:211], v[160:163], v[12:15]
	v_mfma_f32_16x16x32_bf16 v[4:7], v[200:203], v[168:171], v[4:7]
	v_mfma_f32_16x16x32_bf16 v[0:3], v[208:211], v[168:171], v[0:3]
	v_mfma_f32_16x16x32_bf16 v[52:55], v[204:207], v[148:151], v[52:55]
	v_mfma_f32_16x16x32_bf16 v[44:47], v[220:223], v[148:151], v[44:47]
	v_mfma_f32_16x16x32_bf16 v[36:39], v[204:207], v[156:159], v[36:39]
	v_mfma_f32_16x16x32_bf16 v[32:35], v[220:223], v[156:159], v[32:35]
	v_mfma_f32_16x16x32_bf16 v[20:23], v[204:207], v[164:167], v[20:23]
	v_mfma_f32_16x16x32_bf16 v[12:15], v[220:223], v[164:167], v[12:15]
	v_mfma_f32_16x16x32_bf16 v[4:7], v[204:207], v[172:175], v[4:7]
	v_mfma_f32_16x16x32_bf16 v[0:3], v[220:223], v[172:175], v[0:3]
	s_setprio 0
	s_barrier
	s_add_u32 s68, s68, 0x100
	s_addc_u32 s69, s69, 0
	s_cmp_ge_i32 vcc_lo, s67
	s_mov_b64 s[38:39], s[50:51]
	s_mov_b32 s52, vcc_lo
	s_cbranch_scc0 .LBB0_3919
	s_cmp_gt_i32 s28, 31
	s_mov_b64 s[38:39], 0x12000
	s_cbranch_scc1 .LBB0_3922
	s_ashr_i32 s14, s28, 3
	s_mul_hi_i32 s39, s14, 0x4800
	s_mul_i32 s38, s14, 0x4800
